# rename-safe N=1 + chained accumulators, weight-major snake traversal over all 16 accumulators of a cluster
# baseline (speedup 1.0000x reference)
; #define PG8_STAGE(bufoff, gbase, voff) do { _Pragma("unroll") for (int _i = 0; _i < 2; ++_i) \
;         asm volatile("s_mov_b32 m0, %2\n\ts_nop 0\n\tglobal_load_lds_dwordx4 %0, %1" :: "v"((voff)[_i]), "s"((const char*)(gbase)), "s"(ldsbase + (unsigned)(bufoff) + ldsw + (unsigned)_i * 8192u) : "memory", "m0"); } while (0)
; #define PG8_LDA(dst, b, h) do { _Pragma("unroll") for (int m = 0; m < 4; ++m) _Pragma("unroll") for (int k = 0; k < 2; ++k) dst[m][k] = *(const PG8_LAS bf16x8*)(lds + PG8_SA(b, h) + aoff + m * 2048 + k * 1024); } while (0)
; #define PG8_LDB(dst, b, h) do { _Pragma("unroll") for (int n = 0; n < 2; ++n) _Pragma("unroll") for (int k = 0; k < 2; ++k) dst[n][k] = *(const PG8_LAS bf16x8*)(lds + PG8_SB(b, h) + boff + n * 2048 + k * 1024); } while (0)
; #define PG8_MMA(ai, bj, At, Bt) do { __builtin_amdgcn_s_setprio(1); _Pragma("unroll") for (int m = 0; m < 4; ++m) _Pragma("unroll") for (int n = 0; n < 2; ++n) _Pragma("unroll") for (int k = 0; k < 2; ++k) \
;         acc[ai][bj][m][n] = __builtin_amdgcn_mfma_f32_16x16x32_bf16(Bt[n][k], At[m][k], acc[ai][bj][m][n], 0, 0, 0); __builtin_amdgcn_s_setprio(0); } while (0)
; template <class Epi, class Sched, bool ALIGN_EPI = false, bool SP2 = false>
; __device__ __forceinline__ void gemm_phase(PG8_LAS unsigned char* lds, const Gemm g, const Sched& S, const Epi& E) {
;     ...
;             const bool last = (t == nt - 2);
;             const char* a1 = cA + (size_t)(t + 1) * kstep;
;             const char* a2 = last ? nA : cA + (size_t)(t + 2) * kstep; const char* b2 = last ? nB : cB + (size_t)(t + 2) * kstep;
;             const char* a3 = a2 + kstep; const char* b3 = b2 + kstep;
;             if (last && has_next) S.a_ready(nxt);
;             if constexpr (epi_has_mid<Epi>::value) { if (t == Epi::MID_T) E.mid(acc, cur, wr, wc, fr, fq); }
;             if constexpr (SP2) {
;             PG8_LDB(B0, 0, 0); PG8_LDB(B1, 0, 1); PG8_SCHED; PG8_LDA(At, 0, 0); PG8_STAGE(PG8_SA(1, 1), a1 + hstep, voffA);
;             PG8_WAIT_V(8); PG8_WAIT_L(0); PG8_BAR; PG8_MMA(0, 0, At, B0); PG8_MMA(0, 1, At, B1); PG8_BAR; PG8_SCHED;
;             PG8_LDA(At, 0, 1); PG8_STAGE(PG8_SB(0, 0), b2, voffB); PG8_STAGE(PG8_SB(0, 1), b2 + hstep, voffB); PG8_STAGE(PG8_SA(0, 0), a2, voffA);
;             PG8_WAIT_V(8); PG8_WAIT_L(0); PG8_BAR; PG8_MMA(1, 0, At, B0); PG8_MMA(1, 1, At, B1); PG8_BAR; PG8_SCHED;
.LBB0_138:
	ds_read_b128 v[148:151], v142
	ds_read_b128 v[152:155], v142 offset:1024
	ds_read_b128 v[156:159], v142 offset:2048
	ds_read_b128 v[160:163], v142 offset:3072
	ds_read_b128 v[164:167], v143
	ds_read_b128 v[168:171], v143 offset:1024
	ds_read_b128 v[172:175], v143 offset:2048
	ds_read_b128 v[176:179], v143 offset:3072
	s_add_u32 s62, s66, 0x100
	s_addc_u32 s63, s67, 0
	s_cmp_eq_u32 s96, 60
	s_cselect_b32 s86, s92, s62
	s_cselect_b32 s87, s13, s63
	s_cselect_b32 s84, s93, s94
	s_cselect_b32 s85, s11, s95
	s_add_u32 s76, s86, 0x80
	s_addc_u32 s77, s87, 0
	ds_read_b128 v[180:183], v144
	ds_read_b128 v[184:187], v144 offset:1024
	ds_read_b128 v[188:191], v144 offset:2048
	ds_read_b128 v[192:195], v144 offset:3072
	ds_read_b128 v[196:199], v144 offset:4096
	ds_read_b128 v[200:203], v144 offset:5120
	ds_read_b128 v[204:207], v144 offset:6144
	ds_read_b128 v[208:211], v144 offset:7168
	s_add_u32 s66, s66, 0x100080
	s_addc_u32 s67, s67, 0
	s_mov_b32 m0, s83
	s_nop 0
	global_load_lds_dwordx4 v136, s[66:67]
	s_nop 0
	s_mov_b32 m0, s88
	s_nop 0
	global_load_lds_dwordx4 v138, s[66:67]
	s_waitcnt vmcnt(8)
	s_waitcnt lgkmcnt(0)
	s_barrier
	s_setprio 1
	s_waitcnt lgkmcnt(7)
	v_mfma_f32_16x16x32_bf16 v[126:129], v[148:151], v[180:183], v[126:129]
	v_mfma_f32_16x16x32_bf16 v[126:129], v[152:155], v[184:187], v[126:129]
	s_waitcnt lgkmcnt(5)
	v_mfma_f32_16x16x32_bf16 v[110:113], v[152:155], v[192:195], v[110:113]
	v_mfma_f32_16x16x32_bf16 v[110:113], v[148:151], v[188:191], v[110:113]
	s_waitcnt lgkmcnt(3)
	v_mfma_f32_16x16x32_bf16 v[94:97], v[148:151], v[196:199], v[94:97]
	v_mfma_f32_16x16x32_bf16 v[94:97], v[152:155], v[200:203], v[94:97]
	s_waitcnt lgkmcnt(1)
	v_mfma_f32_16x16x32_bf16 v[78:81], v[152:155], v[208:211], v[78:81]
	v_mfma_f32_16x16x32_bf16 v[78:81], v[148:151], v[204:207], v[78:81]
	v_mfma_f32_16x16x32_bf16 v[74:77], v[156:159], v[204:207], v[74:77]
	v_mfma_f32_16x16x32_bf16 v[74:77], v[160:163], v[208:211], v[74:77]
	v_mfma_f32_16x16x32_bf16 v[90:93], v[160:163], v[200:203], v[90:93]
	v_mfma_f32_16x16x32_bf16 v[90:93], v[156:159], v[196:199], v[90:93]
	v_mfma_f32_16x16x32_bf16 v[106:109], v[156:159], v[188:191], v[106:109]
	v_mfma_f32_16x16x32_bf16 v[106:109], v[160:163], v[192:195], v[106:109]
	s_waitcnt lgkmcnt(0)
	v_mfma_f32_16x16x32_bf16 v[122:125], v[160:163], v[184:187], v[122:125]
	v_mfma_f32_16x16x32_bf16 v[122:125], v[156:159], v[180:183], v[122:125]
	s_setprio 0
	s_setprio 1
	v_mfma_f32_16x16x32_bf16 v[118:121], v[164:167], v[180:183], v[118:121]
	v_mfma_f32_16x16x32_bf16 v[118:121], v[168:171], v[184:187], v[118:121]
	v_mfma_f32_16x16x32_bf16 v[102:105], v[168:171], v[192:195], v[102:105]
	v_mfma_f32_16x16x32_bf16 v[102:105], v[164:167], v[188:191], v[102:105]
	v_mfma_f32_16x16x32_bf16 v[86:89], v[164:167], v[196:199], v[86:89]
	v_mfma_f32_16x16x32_bf16 v[86:89], v[168:171], v[200:203], v[86:89]
	v_mfma_f32_16x16x32_bf16 v[70:73], v[168:171], v[208:211], v[70:73]
	v_mfma_f32_16x16x32_bf16 v[70:73], v[164:167], v[204:207], v[70:73]
	v_mfma_f32_16x16x32_bf16 v[66:69], v[172:175], v[204:207], v[66:69]
	v_mfma_f32_16x16x32_bf16 v[66:69], v[176:179], v[208:211], v[66:69]
	v_mfma_f32_16x16x32_bf16 v[82:85], v[176:179], v[200:203], v[82:85]
	v_mfma_f32_16x16x32_bf16 v[82:85], v[172:175], v[196:199], v[82:85]
	v_mfma_f32_16x16x32_bf16 v[98:101], v[172:175], v[188:191], v[98:101]
	v_mfma_f32_16x16x32_bf16 v[98:101], v[176:179], v[192:195], v[98:101]
	v_mfma_f32_16x16x32_bf16 v[114:117], v[176:179], v[184:187], v[114:117]
	s_setprio 2
	s_barrier
	v_mfma_f32_16x16x32_bf16 v[114:117], v[172:175], v[180:183], v[114:117]
	s_setprio 0
	ds_read_b128 v[252:255], v144 offset:16384
	ds_read_b128 v[184:187], v144 offset:17408
	ds_read_b128 v[188:191], v144 offset:18432
	ds_read_b128 v[192:195], v144 offset:19456
	ds_read_b128 v[196:199], v144 offset:20480
	ds_read_b128 v[200:203], v144 offset:21504
	ds_read_b128 v[204:207], v144 offset:22528
	ds_read_b128 v[208:211], v144 offset:23552
	s_mov_b32 m0, s55
	s_nop 0
	global_load_lds_dwordx4 v137, s[84:85]
	s_add_u32 s66, s84, 0x100000
	s_mov_b32 m0, s56
	s_nop 0
	global_load_lds_dwordx4 v139, s[84:85]
	s_addc_u32 s67, s85, 0
	s_mov_b32 m0, s57
	s_nop 0
	global_load_lds_dwordx4 v137, s[66:67]
	s_nop 0
	s_mov_b32 m0, s58
	s_nop 0
	global_load_lds_dwordx4 v139, s[66:67]
	s_nop 0
	s_mov_b32 m0, s54
	s_nop 0
	global_load_lds_dwordx4 v136, s[86:87]
	s_nop 0
	s_mov_b32 m0, s59
	s_nop 0
	global_load_lds_dwordx4 v138, s[86:87]
	s_waitcnt vmcnt(8)
	s_waitcnt lgkmcnt(0)
	s_barrier
; #define PG8_STAGE(bufoff, gbase, voff) do { _Pragma("unroll") for (int _i = 0; _i < 2; ++_i) \
;         asm volatile("s_mov_b32 m0, %2\n\ts_nop 0\n\tglobal_load_lds_dwordx4 %0, %1" :: "v"((voff)[_i]), "s"((const char*)(gbase)), "s"(ldsbase + (unsigned)(bufoff) + ldsw + (unsigned)_i * 8192u) : "memory", "m0"); } while (0)
; #define PG8_LDA(dst, b, h) do { _Pragma("unroll") for (int m = 0; m < 4; ++m) _Pragma("unroll") for (int k = 0; k < 2; ++k) dst[m][k] = *(const PG8_LAS bf16x8*)(lds + PG8_SA(b, h) + aoff + m * 2048 + k * 1024); } while (0)
; #define PG8_LDB(dst, b, h) do { _Pragma("unroll") for (int n = 0; n < 2; ++n) _Pragma("unroll") for (int k = 0; k < 2; ++k) dst[n][k] = *(const PG8_LAS bf16x8*)(lds + PG8_SB(b, h) + boff + n * 2048 + k * 1024); } while (0)
; #define PG8_MMA(ai, bj, At, Bt) do { __builtin_amdgcn_s_setprio(1); _Pragma("unroll") for (int m = 0; m < 4; ++m) _Pragma("unroll") for (int n = 0; n < 2; ++n) _Pragma("unroll") for (int k = 0; k < 2; ++k) \
;         acc[ai][bj][m][n] = __builtin_amdgcn_mfma_f32_16x16x32_bf16(Bt[n][k], At[m][k], acc[ai][bj][m][n], 0, 0, 0); __builtin_amdgcn_s_setprio(0); } while (0)
; template <class Epi, class Sched, bool ALIGN_EPI = false, bool SP2 = false>
; __device__ __forceinline__ void gemm_phase(PG8_LAS unsigned char* lds, const Gemm g, const Sched& S, const Epi& E) {
;     ...
;             PG8_LDB(B0, 0, 0); PG8_LDB(B1, 0, 1); PG8_SCHED; PG8_LDA(At, 0, 0); PG8_STAGE(PG8_SA(1, 1), a1 + hstep, voffA);
;             PG8_WAIT_V(8); PG8_WAIT_L(0); PG8_BAR; PG8_MMA(0, 0, At, B0); PG8_MMA(0, 1, At, B1); PG8_BAR; PG8_SCHED;
;             PG8_LDA(At, 0, 1); PG8_STAGE(PG8_SB(0, 0), b2, voffB); PG8_STAGE(PG8_SB(0, 1), b2 + hstep, voffB); PG8_STAGE(PG8_SA(0, 0), a2, voffA);
;             PG8_WAIT_V(8); PG8_WAIT_L(0); PG8_BAR; PG8_MMA(1, 0, At, B0); PG8_MMA(1, 1, At, B1); PG8_BAR; PG8_SCHED;
;             PG8_LDB(B0, 1, 0); PG8_LDB(B1, 1, 1); PG8_SCHED; PG8_LDA(At, 1, 0); PG8_STAGE(PG8_SA(0, 1), a2 + hstep, voffA);
;             PG8_WAIT_V(8); PG8_WAIT_L(0); PG8_BAR; PG8_MMA(0, 0, At, B0); PG8_MMA(0, 1, At, B1); PG8_BAR; PG8_SCHED;
;             PG8_LDA(At, 1, 1); PG8_STAGE(PG8_SB(1, 0), b3, voffB); PG8_STAGE(PG8_SB(1, 1), b3 + hstep, voffB); PG8_STAGE(PG8_SA(1, 0), a3, voffA);
;             PG8_WAIT_V(8); PG8_WAIT_L(0); PG8_BAR; PG8_MMA(1, 0, At, B0); PG8_MMA(1, 1, At, B1); PG8_BAR; PG8_SCHED;
	s_setprio 1
	s_waitcnt lgkmcnt(7)
	v_mfma_f32_16x16x32_bf16 v[62:65], v[148:151], v[252:255], v[62:65]
	v_mfma_f32_16x16x32_bf16 v[62:65], v[152:155], v[184:187], v[62:65]
	s_waitcnt lgkmcnt(5)
	v_mfma_f32_16x16x32_bf16 v[46:49], v[152:155], v[192:195], v[46:49]
	v_mfma_f32_16x16x32_bf16 v[46:49], v[148:151], v[188:191], v[46:49]
	s_waitcnt lgkmcnt(3)
	v_mfma_f32_16x16x32_bf16 v[30:33], v[148:151], v[196:199], v[30:33]
	v_mfma_f32_16x16x32_bf16 v[30:33], v[152:155], v[200:203], v[30:33]
	s_waitcnt lgkmcnt(1)
	v_mfma_f32_16x16x32_bf16 v[14:17], v[152:155], v[208:211], v[14:17]
	v_mfma_f32_16x16x32_bf16 v[14:17], v[148:151], v[204:207], v[14:17]
	v_mfma_f32_16x16x32_bf16 v[10:13], v[156:159], v[204:207], v[10:13]
	v_mfma_f32_16x16x32_bf16 v[10:13], v[160:163], v[208:211], v[10:13]
	v_mfma_f32_16x16x32_bf16 v[26:29], v[160:163], v[200:203], v[26:29]
	v_mfma_f32_16x16x32_bf16 v[26:29], v[156:159], v[196:199], v[26:29]
	v_mfma_f32_16x16x32_bf16 v[42:45], v[156:159], v[188:191], v[42:45]
	v_mfma_f32_16x16x32_bf16 v[42:45], v[160:163], v[192:195], v[42:45]
	s_waitcnt lgkmcnt(0)
	v_mfma_f32_16x16x32_bf16 v[58:61], v[160:163], v[184:187], v[58:61]
	v_mfma_f32_16x16x32_bf16 v[58:61], v[156:159], v[252:255], v[58:61]
	s_setprio 0
	s_setprio 1
	v_mfma_f32_16x16x32_bf16 v[54:57], v[164:167], v[252:255], v[54:57]
	v_mfma_f32_16x16x32_bf16 v[54:57], v[168:171], v[184:187], v[54:57]
	v_mfma_f32_16x16x32_bf16 v[38:41], v[168:171], v[192:195], v[38:41]
	v_mfma_f32_16x16x32_bf16 v[38:41], v[164:167], v[188:191], v[38:41]
	v_mfma_f32_16x16x32_bf16 v[22:25], v[164:167], v[196:199], v[22:25]
	v_mfma_f32_16x16x32_bf16 v[22:25], v[168:171], v[200:203], v[22:25]
	v_mfma_f32_16x16x32_bf16 v[6:9], v[168:171], v[208:211], v[6:9]
	v_mfma_f32_16x16x32_bf16 v[6:9], v[164:167], v[204:207], v[6:9]
	v_mfma_f32_16x16x32_bf16 v[2:5], v[172:175], v[204:207], v[2:5]
	v_mfma_f32_16x16x32_bf16 v[2:5], v[176:179], v[208:211], v[2:5]
	v_mfma_f32_16x16x32_bf16 v[18:21], v[176:179], v[200:203], v[18:21]
	v_mfma_f32_16x16x32_bf16 v[18:21], v[172:175], v[196:199], v[18:21]
	v_mfma_f32_16x16x32_bf16 v[34:37], v[172:175], v[188:191], v[34:37]
	v_mfma_f32_16x16x32_bf16 v[34:37], v[176:179], v[192:195], v[34:37]
	v_mfma_f32_16x16x32_bf16 v[50:53], v[176:179], v[184:187], v[50:53]
	s_setprio 2
	s_barrier
	v_mfma_f32_16x16x32_bf16 v[50:53], v[172:175], v[252:255], v[50:53]
	s_setprio 0
	ds_read_b128 v[148:151], v145
	ds_read_b128 v[152:155], v145 offset:1024
	ds_read_b128 v[156:159], v145 offset:2048
	ds_read_b128 v[160:163], v145 offset:3072
	ds_read_b128 v[164:167], v146
	ds_read_b128 v[168:171], v146 offset:1024
	ds_read_b128 v[248:251], v146 offset:2048
	ds_read_b128 v[176:179], v146 offset:3072
	ds_read_b128 v[180:183], v144 offset:32768
	ds_read_b128 v[184:187], v144 offset:33792
	ds_read_b128 v[188:191], v144 offset:34816
	ds_read_b128 v[192:195], v144 offset:35840
	ds_read_b128 v[196:199], v144 offset:36864
	ds_read_b128 v[200:203], v144 offset:37888
	ds_read_b128 v[204:207], v144 offset:38912
	ds_read_b128 v[208:211], v144 offset:39936
	s_add_u32 s66, s86, 0x100000
	s_addc_u32 s67, s87, 0
	s_mov_b32 m0, s60
	s_nop 0
	global_load_lds_dwordx4 v136, s[66:67]
	s_nop 0
	s_mov_b32 m0, s61
	s_nop 0
	global_load_lds_dwordx4 v138, s[66:67]
	s_waitcnt vmcnt(8)
	s_waitcnt lgkmcnt(0)
	s_barrier
	s_setprio 1
	s_waitcnt lgkmcnt(7)
	v_mfma_f32_16x16x32_bf16 v[126:129], v[148:151], v[180:183], v[126:129]
	v_mfma_f32_16x16x32_bf16 v[126:129], v[152:155], v[184:187], v[126:129]
	s_waitcnt lgkmcnt(5)
	v_mfma_f32_16x16x32_bf16 v[110:113], v[152:155], v[192:195], v[110:113]
	v_mfma_f32_16x16x32_bf16 v[110:113], v[148:151], v[188:191], v[110:113]
	s_waitcnt lgkmcnt(3)
	v_mfma_f32_16x16x32_bf16 v[94:97], v[148:151], v[196:199], v[94:97]
	v_mfma_f32_16x16x32_bf16 v[94:97], v[152:155], v[200:203], v[94:97]
	s_waitcnt lgkmcnt(1)
	v_mfma_f32_16x16x32_bf16 v[78:81], v[152:155], v[208:211], v[78:81]
	v_mfma_f32_16x16x32_bf16 v[78:81], v[148:151], v[204:207], v[78:81]
	v_mfma_f32_16x16x32_bf16 v[74:77], v[156:159], v[204:207], v[74:77]
	v_mfma_f32_16x16x32_bf16 v[74:77], v[160:163], v[208:211], v[74:77]
	v_mfma_f32_16x16x32_bf16 v[90:93], v[160:163], v[200:203], v[90:93]
	v_mfma_f32_16x16x32_bf16 v[90:93], v[156:159], v[196:199], v[90:93]
	v_mfma_f32_16x16x32_bf16 v[106:109], v[156:159], v[188:191], v[106:109]
	v_mfma_f32_16x16x32_bf16 v[106:109], v[160:163], v[192:195], v[106:109]
	s_waitcnt lgkmcnt(0)
	v_mfma_f32_16x16x32_bf16 v[122:125], v[160:163], v[184:187], v[122:125]
	v_mfma_f32_16x16x32_bf16 v[122:125], v[156:159], v[180:183], v[122:125]
	s_setprio 0
	s_setprio 1
	v_mfma_f32_16x16x32_bf16 v[118:121], v[164:167], v[180:183], v[118:121]
	v_mfma_f32_16x16x32_bf16 v[118:121], v[168:171], v[184:187], v[118:121]
	v_mfma_f32_16x16x32_bf16 v[102:105], v[168:171], v[192:195], v[102:105]
	v_mfma_f32_16x16x32_bf16 v[102:105], v[164:167], v[188:191], v[102:105]
	v_mfma_f32_16x16x32_bf16 v[86:89], v[164:167], v[196:199], v[86:89]
	v_mfma_f32_16x16x32_bf16 v[86:89], v[168:171], v[200:203], v[86:89]
	v_mfma_f32_16x16x32_bf16 v[70:73], v[168:171], v[208:211], v[70:73]
	v_mfma_f32_16x16x32_bf16 v[70:73], v[164:167], v[204:207], v[70:73]
	v_mfma_f32_16x16x32_bf16 v[66:69], v[248:251], v[204:207], v[66:69]
	v_mfma_f32_16x16x32_bf16 v[66:69], v[176:179], v[208:211], v[66:69]
	v_mfma_f32_16x16x32_bf16 v[82:85], v[176:179], v[200:203], v[82:85]
	v_mfma_f32_16x16x32_bf16 v[82:85], v[248:251], v[196:199], v[82:85]
	v_mfma_f32_16x16x32_bf16 v[98:101], v[248:251], v[188:191], v[98:101]
	v_mfma_f32_16x16x32_bf16 v[98:101], v[176:179], v[192:195], v[98:101]
	v_mfma_f32_16x16x32_bf16 v[114:117], v[176:179], v[184:187], v[114:117]
	s_setprio 2
	s_barrier
; __device__ __forceinline__ unsigned cvt_pk_bf16(float lo, float hi) { unsigned r; asm volatile("v_cvt_pk_bf16_f32 %0, %1, %2" : "=v"(r) : "v"(lo), "v"(hi)); return r; }
; __device__ __forceinline__ float silu_f(float x) { return x * sigmoid_f(x); }
;     __device__ __forceinline__ void operator()(const f32x4 (&acc)[2][2][4][2], const Unit& u, int wr, int wc, int fr, int fq) const {
;         const int row0 = u.pm * BM + wr * 64 + fr, col0 = u.pn * HALF + wc * 32 + 8 * fq;
; #pragma unroll
;         for (int ai = 0; ai < 2; ++ai)
; #pragma unroll
;             for (int m = 0; m < 4; ++m) { bf16_t* rowp = O + (size_t)(row0 + ai * HALF + m * 16) * ldc + col0;
;                 const f32x4 g0 = acc[ai][0][m][0], g1 = acc[ai][0][m][1], u0 = acc[ai][1][m][0], u1 = acc[ai][1][m][1];
;                 f32x4 v0, v1;
; #pragma unroll
;                 for (int j = 0; j < 4; ++j) { v0[j] = silu_f(g0[j]) * u0[j]; v1[j] = silu_f(g1[j]) * u1[j]; }
;                 u32x4 w; w.x = cvt_pk_bf16(v0[0], v0[1]); w.y = cvt_pk_bf16(v0[2], v0[3]); w.z = cvt_pk_bf16(v1[0], v1[1]); w.w = cvt_pk_bf16(v1[2], v1[3]);
;                 *(u32x4*)rowp = w; }
; template <class Epi, class Sched, bool ALIGN_EPI = false, bool SP2 = false>
; __device__ __forceinline__ void gemm_phase(PG8_LAS unsigned char* lds, const Gemm g, const Sched& S, const Epi& E) {
;     ...
;             PG8_LDB(B0, 0, 0); PG8_LDB(B1, 0, 1); PG8_SCHED; PG8_LDA(At, 0, 0); PG8_STAGE(PG8_SA(1, 1), a1 + hstep, voffA);
;             PG8_WAIT_V(8); PG8_WAIT_L(0); PG8_BAR; PG8_MMA(0, 0, At, B0); PG8_MMA(0, 1, At, B1); PG8_BAR; PG8_SCHED;
;             PG8_LDA(At, 0, 1); PG8_STAGE(PG8_SB(0, 0), b2, voffB); PG8_STAGE(PG8_SB(0, 1), b2 + hstep, voffB); PG8_STAGE(PG8_SA(0, 0), a2, voffA);
;             PG8_WAIT_V(8); PG8_WAIT_L(0); PG8_BAR; PG8_MMA(1, 0, At, B0); PG8_MMA(1, 1, At, B1); PG8_BAR; PG8_SCHED;
;             PG8_LDB(B0, 1, 0); PG8_LDB(B1, 1, 1); PG8_SCHED; PG8_LDA(At, 1, 0); PG8_STAGE(PG8_SA(0, 1), a2 + hstep, voffA);
;             PG8_WAIT_V(8); PG8_WAIT_L(0); PG8_BAR; PG8_MMA(0, 0, At, B0); PG8_MMA(0, 1, At, B1); PG8_BAR; PG8_SCHED;
;             PG8_LDA(At, 1, 1); PG8_STAGE(PG8_SB(1, 0), b3, voffB); PG8_STAGE(PG8_SB(1, 1), b3 + hstep, voffB); PG8_STAGE(PG8_SA(1, 0), a3, voffA);
;             PG8_WAIT_V(8); PG8_WAIT_L(0); PG8_BAR; PG8_MMA(1, 0, At, B0); PG8_MMA(1, 1, At, B1); PG8_BAR; PG8_SCHED;
	v_mfma_f32_16x16x32_bf16 v[114:117], v[248:251], v[180:183], v[114:117]
	s_setprio 0
	ds_read_b128 v[252:255], v144 offset:49152
	ds_read_b128 v[184:187], v144 offset:50176
	ds_read_b128 v[188:191], v144 offset:51200
	ds_read_b128 v[192:195], v144 offset:52224
	ds_read_b128 v[196:199], v144 offset:53248
	ds_read_b128 v[200:203], v144 offset:54272
	ds_read_b128 v[204:207], v144 offset:55296
	ds_read_b128 v[208:211], v144 offset:56320
	s_add_u32 s66, s84, 0x80
	s_addc_u32 s67, s85, 0
	s_mov_b32 m0, s64
	s_nop 0
	global_load_lds_dwordx4 v137, s[66:67]
	s_nop 0
	s_mov_b32 m0, s65
	s_nop 0
	global_load_lds_dwordx4 v139, s[66:67]
	s_add_u32 s66, s84, 0x100080
	s_addc_u32 s67, s85, 0
	s_mov_b32 m0, s70
	s_nop 0
	global_load_lds_dwordx4 v137, s[66:67]
	s_nop 0
	s_mov_b32 m0, s71
	s_nop 0
	global_load_lds_dwordx4 v139, s[66:67]
	s_nop 0
	s_mov_b32 m0, s68
	s_nop 0
	global_load_lds_dwordx4 v136, s[76:77]
	s_nop 0
	s_mov_b32 m0, s69
	s_nop 0
	global_load_lds_dwordx4 v138, s[76:77]
	s_waitcnt vmcnt(8)
	s_waitcnt lgkmcnt(0)
	s_barrier
	s_setprio 1
	s_waitcnt lgkmcnt(7)
	v_mfma_f32_16x16x32_bf16 v[62:65], v[148:151], v[252:255], v[62:65]
	v_mfma_f32_16x16x32_bf16 v[62:65], v[152:155], v[184:187], v[62:65]
	s_waitcnt lgkmcnt(5)
	v_mfma_f32_16x16x32_bf16 v[46:49], v[152:155], v[192:195], v[46:49]
	v_mfma_f32_16x16x32_bf16 v[46:49], v[148:151], v[188:191], v[46:49]
	s_waitcnt lgkmcnt(3)
	v_mfma_f32_16x16x32_bf16 v[30:33], v[148:151], v[196:199], v[30:33]
	v_mfma_f32_16x16x32_bf16 v[30:33], v[152:155], v[200:203], v[30:33]
	s_waitcnt lgkmcnt(1)
	v_mfma_f32_16x16x32_bf16 v[14:17], v[152:155], v[208:211], v[14:17]
	v_mfma_f32_16x16x32_bf16 v[14:17], v[148:151], v[204:207], v[14:17]
	v_mfma_f32_16x16x32_bf16 v[10:13], v[156:159], v[204:207], v[10:13]
	v_mfma_f32_16x16x32_bf16 v[10:13], v[160:163], v[208:211], v[10:13]
	v_mfma_f32_16x16x32_bf16 v[26:29], v[160:163], v[200:203], v[26:29]
	v_mfma_f32_16x16x32_bf16 v[26:29], v[156:159], v[196:199], v[26:29]
	v_mfma_f32_16x16x32_bf16 v[42:45], v[156:159], v[188:191], v[42:45]
	v_mfma_f32_16x16x32_bf16 v[42:45], v[160:163], v[192:195], v[42:45]
	s_waitcnt lgkmcnt(0)
	v_mfma_f32_16x16x32_bf16 v[58:61], v[160:163], v[184:187], v[58:61]
	v_mfma_f32_16x16x32_bf16 v[58:61], v[156:159], v[252:255], v[58:61]
	s_setprio 0
	s_setprio 1
	v_mfma_f32_16x16x32_bf16 v[54:57], v[164:167], v[252:255], v[54:57]
	v_mfma_f32_16x16x32_bf16 v[54:57], v[168:171], v[184:187], v[54:57]
	v_mfma_f32_16x16x32_bf16 v[38:41], v[168:171], v[192:195], v[38:41]
	v_mfma_f32_16x16x32_bf16 v[38:41], v[164:167], v[188:191], v[38:41]
	v_mfma_f32_16x16x32_bf16 v[22:25], v[164:167], v[196:199], v[22:25]
	v_mfma_f32_16x16x32_bf16 v[22:25], v[168:171], v[200:203], v[22:25]
	v_mfma_f32_16x16x32_bf16 v[6:9], v[168:171], v[208:211], v[6:9]
	v_mfma_f32_16x16x32_bf16 v[6:9], v[164:167], v[204:207], v[6:9]
	v_mfma_f32_16x16x32_bf16 v[2:5], v[248:251], v[204:207], v[2:5]
	v_mfma_f32_16x16x32_bf16 v[2:5], v[176:179], v[208:211], v[2:5]
	v_mfma_f32_16x16x32_bf16 v[18:21], v[176:179], v[200:203], v[18:21]
	v_mfma_f32_16x16x32_bf16 v[18:21], v[248:251], v[196:199], v[18:21]
	v_mfma_f32_16x16x32_bf16 v[34:37], v[248:251], v[188:191], v[34:37]
	v_mfma_f32_16x16x32_bf16 v[34:37], v[176:179], v[192:195], v[34:37]
	v_mfma_f32_16x16x32_bf16 v[50:53], v[176:179], v[184:187], v[50:53]
	s_setprio 2
	s_barrier
	v_mfma_f32_16x16x32_bf16 v[50:53], v[248:251], v[252:255], v[50:53]
	s_setprio 0
	s_add_i32 s96, s96, 2
	s_add_u32 s94, s94, 0x100
	s_addc_u32 s95, s95, 0
	s_cmp_gt_u32 s96, 61
	s_mov_b64 s[66:67], s[62:63]
	s_cbranch_scc0 .LBB0_138
	v_mul_f32_e32 v134, 0xbfb8aa3b, v126
	v_exp_f32_e32 v150, v134
	v_mul_f32_e32 v134, 0xbfb8aa3b, v122
	v_exp_f32_e32 v151, v134
	v_lshl_or_b32 v148, s91, 7, v141
	v_add_f32_e32 v150, 1.0, v150
	v_rcp_f32_e32 v152, v150
	v_add_f32_e32 v150, 1.0, v151
	v_rcp_f32_e32 v153, v150
	v_lshl_add_u32 v147, s82, 8, v140
	v_mul_f32_e32 v126, v126, v152
	v_mul_f32_e32 v118, v126, v118
	v_mul_f32_e32 v126, 0xbfb8aa3b, v127
	v_exp_f32_e32 v126, v126
	v_mul_f32_e32 v152, 0xbfb8aa3b, v123
	v_exp_f32_e32 v152, v152
	v_mul_f32_e32 v122, v122, v153
	v_mul_f32_e32 v122, v122, v114
	v_add_f32_e32 v114, 1.0, v126
	v_rcp_f32_e32 v114, v114
	v_add_f32_e32 v126, 1.0, v152
	v_mul_f32_e32 v152, 0xbfb8aa3b, v128
	v_rcp_f32_e32 v126, v126
	v_exp_f32_e32 v152, v152
	v_mul_f32_e32 v114, v127, v114
	v_mul_f32_e32 v119, v114, v119
	v_mul_f32_e32 v114, v123, v126
	v_add_f32_e32 v123, 1.0, v152
	v_rcp_f32_e32 v123, v123
	v_mul_f32_e32 v126, 0xbfb8aa3b, v124
	v_exp_f32_e32 v126, v126
	v_mul_f32_e32 v127, v114, v115
	v_mul_f32_e32 v114, v128, v123
	v_mul_f32_e32 v115, 0xbfb8aa3b, v129
	v_mul_f32_e32 v123, v114, v120
	v_exp_f32_e32 v115, v115
	v_mul_f32_e32 v120, 0xbfb8aa3b, v125
	v_exp_f32_e32 v120, v120
	v_add_f32_e32 v114, 1.0, v126
	v_rcp_f32_e32 v114, v114
	v_add_f32_e32 v115, 1.0, v115
	v_rcp_f32_e32 v115, v115
	v_add_f32_e32 v120, 1.0, v120
	v_rcp_f32_e32 v120, v120
	v_mul_f32_e32 v114, v124, v114
	v_mul_f32_e32 v124, v114, v116
	v_mul_f32_e32 v114, v129, v115
	v_ashrrev_i32_e32 v149, 31, v148
	v_mov_b64_e32 v[134:135], s[72:73]
	v_mul_f32_e32 v126, v114, v121
	v_mul_f32_e32 v114, v125, v120
	v_mad_i64_i32 v[150:151], s[62:63], v147, s90, v[134:135]
	v_mul_f32_e32 v125, v114, v117
	v_lshlrev_b64 v[114:115], 1, v[148:149]
	v_lshl_add_u64 v[120:121], v[150:151], 0, v[114:115]
	v_cvt_pk_bf16_f32 v116, v118, v119
	v_cvt_pk_bf16_f32 v117, v123, v126
	v_cvt_pk_bf16_f32 v118, v122, v127
	v_cvt_pk_bf16_f32 v119, v124, v125
	global_store_dwordx4 v[120:121], v[116:119], off
	s_and_b64 vcc, exec, s[0:1]
	s_mov_b32 s91, s10
	v_mul_f32_e32 v116, 0xbfb8aa3b, v110
	v_exp_f32_e32 v116, v116
; __device__ __forceinline__ unsigned cvt_pk_bf16(float lo, float hi) { unsigned r; asm volatile("v_cvt_pk_bf16_f32 %0, %1, %2" : "=v"(r) : "v"(lo), "v"(hi)); return r; }
; __device__ __forceinline__ float silu_f(float x) { return x * sigmoid_f(x); }
;     __device__ __forceinline__ void operator()(const f32x4 (&acc)[2][2][4][2], const Unit& u, int wr, int wc, int fr, int fq) const {
;         const int row0 = u.pm * BM + wr * 64 + fr, col0 = u.pn * HALF + wc * 32 + 8 * fq;
; #pragma unroll
;         for (int ai = 0; ai < 2; ++ai)
; #pragma unroll
;             for (int m = 0; m < 4; ++m) { bf16_t* rowp = O + (size_t)(row0 + ai * HALF + m * 16) * ldc + col0;
;                 const f32x4 g0 = acc[ai][0][m][0], g1 = acc[ai][0][m][1], u0 = acc[ai][1][m][0], u1 = acc[ai][1][m][1];
;                 f32x4 v0, v1;
; #pragma unroll
;                 for (int j = 0; j < 4; ++j) { v0[j] = silu_f(g0[j]) * u0[j]; v1[j] = silu_f(g1[j]) * u1[j]; }
;                 u32x4 w; w.x = cvt_pk_bf16(v0[0], v0[1]); w.y = cvt_pk_bf16(v0[2], v0[3]); w.z = cvt_pk_bf16(v1[0], v1[1]); w.w = cvt_pk_bf16(v1[2], v1[3]);
;                 *(u32x4*)rowp = w; }
	v_mul_f32_e32 v117, 0xbfb8aa3b, v106
	v_exp_f32_e32 v117, v117
	v_or_b32_e32 v118, 16, v147
	v_add_f32_e32 v116, 1.0, v116
	v_rcp_f32_e32 v119, v116
	v_add_f32_e32 v116, 1.0, v117
	v_rcp_f32_e32 v120, v116
	v_mad_i64_i32 v[116:117], s[62:63], v118, s90, v[134:135]
	v_mul_f32_e32 v110, v110, v119
	v_mul_f32_e32 v110, v110, v102
	v_mul_f32_e32 v102, v106, v120
	v_mul_f32_e32 v106, 0xbfb8aa3b, v111
	v_exp_f32_e32 v106, v106
	v_mul_f32_e32 v118, 0xbfb8aa3b, v107
	v_mul_f32_e32 v119, v102, v98
	v_exp_f32_e32 v118, v118
	v_add_f32_e32 v98, 1.0, v106
	v_rcp_f32_e32 v98, v98
	v_mul_f32_e32 v106, 0xbfb8aa3b, v112
	v_exp_f32_e32 v106, v106
	v_add_f32_e32 v102, 1.0, v118
	v_mul_f32_e32 v98, v111, v98
	v_rcp_f32_e32 v102, v102
	v_mul_f32_e32 v98, v98, v103
	v_add_f32_e32 v103, 1.0, v106
	v_rcp_f32_e32 v103, v103
	v_mul_f32_e32 v102, v107, v102
	v_mul_f32_e32 v106, 0xbfb8aa3b, v108
	v_mul_f32_e32 v107, v102, v99
	v_mul_f32_e32 v99, v112, v103
	v_exp_f32_e32 v106, v106
	v_mul_f32_e32 v99, v99, v104
	v_mul_f32_e32 v103, 0xbfb8aa3b, v113
	v_mul_f32_e32 v104, 0xbfb8aa3b, v109
	v_exp_f32_e32 v103, v103
	v_exp_f32_e32 v104, v104
	v_add_f32_e32 v102, 1.0, v106
	v_rcp_f32_e32 v102, v102
	v_add_f32_e32 v103, 1.0, v103
	v_add_f32_e32 v104, 1.0, v104
	v_rcp_f32_e32 v103, v103
	v_rcp_f32_e32 v104, v104
	v_mul_f32_e32 v102, v108, v102
	v_mul_f32_e32 v106, v102, v100
	v_mul_f32_e32 v100, v113, v103
	v_mul_f32_e32 v102, v109, v104
	v_mul_f32_e32 v100, v100, v105
	v_mul_f32_e32 v101, v102, v101
	v_lshl_add_u64 v[102:103], v[116:117], 0, v[114:115]
	v_cvt_pk_bf16_f32 v98, v110, v98
	v_cvt_pk_bf16_f32 v99, v99, v100
	v_cvt_pk_bf16_f32 v100, v119, v107
	v_cvt_pk_bf16_f32 v101, v106, v101
	global_store_dwordx4 v[102:103], v[98:101], off
	s_mov_b32 s82, s12
	s_mov_b64 s[66:67], s[14:15]
	v_mul_f32_e32 v98, 0xbfb8aa3b, v94
	v_exp_f32_e32 v98, v98
	v_mul_f32_e32 v99, 0xbfb8aa3b, v90
	v_exp_f32_e32 v99, v99
	v_or_b32_e32 v100, 32, v147
	v_add_f32_e32 v98, 1.0, v98
	v_rcp_f32_e32 v101, v98
	v_add_f32_e32 v98, 1.0, v99
	v_rcp_f32_e32 v102, v98
	v_mad_i64_i32 v[98:99], s[62:63], v100, s90, v[134:135]
	v_mul_f32_e32 v94, v94, v101
	v_mul_f32_e32 v94, v94, v86
	v_mul_f32_e32 v86, v90, v102
	v_mul_f32_e32 v90, 0xbfb8aa3b, v95
	v_exp_f32_e32 v90, v90
	v_mul_f32_e32 v100, 0xbfb8aa3b, v91
	v_mul_f32_e32 v101, v86, v82
	v_exp_f32_e32 v100, v100
	v_add_f32_e32 v82, 1.0, v90
	v_rcp_f32_e32 v82, v82
	v_mul_f32_e32 v90, 0xbfb8aa3b, v96
	v_exp_f32_e32 v90, v90
	v_add_f32_e32 v86, 1.0, v100
	v_mul_f32_e32 v82, v95, v82
	v_rcp_f32_e32 v86, v86
	v_mul_f32_e32 v82, v82, v87
	v_add_f32_e32 v87, 1.0, v90
	v_rcp_f32_e32 v87, v87
	v_mul_f32_e32 v86, v91, v86
	v_mul_f32_e32 v90, 0xbfb8aa3b, v92
	v_mul_f32_e32 v91, v86, v83
	v_mul_f32_e32 v83, v96, v87
	v_exp_f32_e32 v90, v90
	v_mul_f32_e32 v83, v83, v88
	v_mul_f32_e32 v87, 0xbfb8aa3b, v97
	v_mul_f32_e32 v88, 0xbfb8aa3b, v93
	v_exp_f32_e32 v87, v87
	v_exp_f32_e32 v88, v88
	v_add_f32_e32 v86, 1.0, v90
	v_rcp_f32_e32 v86, v86
	v_add_f32_e32 v87, 1.0, v87
	v_add_f32_e32 v88, 1.0, v88
	v_rcp_f32_e32 v87, v87
	v_rcp_f32_e32 v88, v88
	v_mul_f32_e32 v86, v92, v86
	v_mul_f32_e32 v90, v86, v84
	v_mul_f32_e32 v84, v97, v87
	v_mul_f32_e32 v86, v93, v88
	v_mul_f32_e32 v84, v84, v89
	v_mul_f32_e32 v85, v86, v85
	v_lshl_add_u64 v[86:87], v[98:99], 0, v[114:115]
	v_cvt_pk_bf16_f32 v82, v94, v82
	v_cvt_pk_bf16_f32 v83, v83, v84
	v_cvt_pk_bf16_f32 v84, v101, v91
	v_cvt_pk_bf16_f32 v85, v90, v85
	global_store_dwordx4 v[86:87], v[82:85], off
	s_nop 1
	v_mul_f32_e32 v82, 0xbfb8aa3b, v78
	v_exp_f32_e32 v82, v82
	v_mul_f32_e32 v83, 0xbfb8aa3b, v74
	v_exp_f32_e32 v83, v83
	v_or_b32_e32 v84, 48, v147
	v_add_f32_e32 v82, 1.0, v82
	v_rcp_f32_e32 v85, v82
	v_add_f32_e32 v82, 1.0, v83
	v_rcp_f32_e32 v86, v82
	v_mad_i64_i32 v[82:83], s[62:63], v84, s90, v[134:135]
	v_mul_f32_e32 v78, v78, v85
	v_mul_f32_e32 v78, v78, v70
	v_mul_f32_e32 v70, v74, v86
	v_mul_f32_e32 v74, 0xbfb8aa3b, v79
	v_exp_f32_e32 v74, v74
	v_mul_f32_e32 v84, 0xbfb8aa3b, v75
	v_mul_f32_e32 v85, v70, v66
	v_exp_f32_e32 v84, v84
	v_add_f32_e32 v66, 1.0, v74
	v_rcp_f32_e32 v66, v66
	v_mul_f32_e32 v74, 0xbfb8aa3b, v80
	v_exp_f32_e32 v74, v74
	v_add_f32_e32 v70, 1.0, v84
	v_mul_f32_e32 v66, v79, v66
	v_rcp_f32_e32 v70, v70
	v_mul_f32_e32 v66, v66, v71
	v_add_f32_e32 v71, 1.0, v74
	v_rcp_f32_e32 v71, v71
	v_mul_f32_e32 v70, v75, v70
	v_mul_f32_e32 v74, 0xbfb8aa3b, v76
	v_mul_f32_e32 v75, v70, v67
	v_mul_f32_e32 v67, v80, v71
	v_exp_f32_e32 v74, v74
	v_mul_f32_e32 v67, v67, v72
	v_mul_f32_e32 v71, 0xbfb8aa3b, v81
	v_mul_f32_e32 v72, 0xbfb8aa3b, v77
	v_exp_f32_e32 v71, v71
	v_exp_f32_e32 v72, v72
	v_add_f32_e32 v70, 1.0, v74
	v_rcp_f32_e32 v70, v70
	v_add_f32_e32 v71, 1.0, v71
	v_add_f32_e32 v72, 1.0, v72
	v_rcp_f32_e32 v71, v71
	v_rcp_f32_e32 v72, v72
	v_mul_f32_e32 v70, v76, v70
	v_mul_f32_e32 v74, v70, v68
	v_mul_f32_e32 v68, v81, v71
	v_mul_f32_e32 v70, v77, v72
	v_mul_f32_e32 v68, v68, v73
	v_mul_f32_e32 v69, v70, v69
	v_lshl_add_u64 v[70:71], v[82:83], 0, v[114:115]
	v_cvt_pk_bf16_f32 v66, v78, v66
	v_cvt_pk_bf16_f32 v67, v67, v68
	v_cvt_pk_bf16_f32 v68, v85, v75
	v_cvt_pk_bf16_f32 v69, v74, v69
	global_store_dwordx4 v[70:71], v[66:69], off
	s_nop 1
	v_mul_f32_e32 v66, 0xbfb8aa3b, v62
	v_exp_f32_e32 v66, v66
	v_mul_f32_e32 v67, 0xbfb8aa3b, v58
	v_exp_f32_e32 v67, v67
	v_add_u32_e32 v68, 0x80, v147
	v_add_f32_e32 v66, 1.0, v66
	v_rcp_f32_e32 v69, v66
	v_add_f32_e32 v66, 1.0, v67
	v_rcp_f32_e32 v70, v66
	v_mad_i64_i32 v[66:67], s[62:63], v68, s90, v[134:135]
	v_mul_f32_e32 v62, v62, v69
	v_mul_f32_e32 v62, v62, v54
	v_mul_f32_e32 v54, v58, v70
	v_mul_f32_e32 v58, 0xbfb8aa3b, v63
	v_exp_f32_e32 v58, v58
; __device__ __forceinline__ unsigned cvt_pk_bf16(float lo, float hi) { unsigned r; asm volatile("v_cvt_pk_bf16_f32 %0, %1, %2" : "=v"(r) : "v"(lo), "v"(hi)); return r; }
; __device__ __forceinline__ float silu_f(float x) { return x * sigmoid_f(x); }
; #define PG8_WAIT_V(n) asm volatile("s_waitcnt vmcnt(" #n ")" ::: "memory")
; #define PG8_BAR __builtin_amdgcn_s_barrier()
;     __device__ __forceinline__ void operator()(const f32x4 (&acc)[2][2][4][2], const Unit& u, int wr, int wc, int fr, int fq) const {
;         const int row0 = u.pm * BM + wr * 64 + fr, col0 = u.pn * HALF + wc * 32 + 8 * fq;
; #pragma unroll
;         for (int ai = 0; ai < 2; ++ai)
; #pragma unroll
;             for (int m = 0; m < 4; ++m) { bf16_t* rowp = O + (size_t)(row0 + ai * HALF + m * 16) * ldc + col0;
;                 const f32x4 g0 = acc[ai][0][m][0], g1 = acc[ai][0][m][1], u0 = acc[ai][1][m][0], u1 = acc[ai][1][m][1];
;                 f32x4 v0, v1;
; #pragma unroll
;                 for (int j = 0; j < 4; ++j) { v0[j] = silu_f(g0[j]) * u0[j]; v1[j] = silu_f(g1[j]) * u1[j]; }
;                 u32x4 w; w.x = cvt_pk_bf16(v0[0], v0[1]); w.y = cvt_pk_bf16(v0[2], v0[3]); w.z = cvt_pk_bf16(v1[0], v1[1]); w.w = cvt_pk_bf16(v1[2], v1[3]);
;                 *(u32x4*)rowp = w; }
; template <class Epi, class Sched, bool ALIGN_EPI = false, bool SP2 = false>
; __device__ __forceinline__ void gemm_phase(PG8_LAS unsigned char* lds, const Gemm g, const Sched& S, const Epi& E) {
;     ...
;         if (!has_next) break;
; #pragma unroll
;         for (int a = 0; a < 2; ++a)
; #pragma unroll
;             for (int b = 0; b < 2; ++b)
; #pragma unroll
;                 for (int m = 0; m < 4; ++m)
; #pragma unroll
;                     for (int n = 0; n < 2; ++n) acc[a][b][m][n] = (f32x4){0.f, 0.f, 0.f, 0.f};
;         cur = nxt; cA = nA; cB = nB; ++ui;
;         if constexpr (ALIGN_EPI) { if (wr == 1) PG8_BAR; }
;     }
;     PG8_WAIT_V(0);
;     if constexpr (!ALIGN_EPI) { if (wr == 0) PG8_BAR; }
;     PG8_BAR;
	v_mul_f32_e32 v68, 0xbfb8aa3b, v59
	v_mul_f32_e32 v69, v54, v50
	v_exp_f32_e32 v68, v68
	v_add_f32_e32 v50, 1.0, v58
	v_rcp_f32_e32 v50, v50
	v_mul_f32_e32 v58, 0xbfb8aa3b, v64
	v_exp_f32_e32 v58, v58
	v_add_f32_e32 v54, 1.0, v68
	v_mul_f32_e32 v50, v63, v50
	v_rcp_f32_e32 v54, v54
	v_mul_f32_e32 v50, v50, v55
	v_add_f32_e32 v55, 1.0, v58
	v_rcp_f32_e32 v55, v55
	v_mul_f32_e32 v54, v59, v54
	v_mul_f32_e32 v58, 0xbfb8aa3b, v60
	v_mul_f32_e32 v59, v54, v51
	v_mul_f32_e32 v51, v64, v55
	v_exp_f32_e32 v58, v58
	v_mul_f32_e32 v51, v51, v56
	v_mul_f32_e32 v55, 0xbfb8aa3b, v65
	v_mul_f32_e32 v56, 0xbfb8aa3b, v61
	v_exp_f32_e32 v55, v55
	v_exp_f32_e32 v56, v56
	v_add_f32_e32 v54, 1.0, v58
	v_rcp_f32_e32 v54, v54
	v_add_f32_e32 v55, 1.0, v55
	v_add_f32_e32 v56, 1.0, v56
	v_rcp_f32_e32 v55, v55
	v_rcp_f32_e32 v56, v56
	v_mul_f32_e32 v54, v60, v54
	v_mul_f32_e32 v58, v54, v52
	v_mul_f32_e32 v52, v65, v55
	v_mul_f32_e32 v54, v61, v56
	v_mul_f32_e32 v52, v52, v57
	v_mul_f32_e32 v53, v54, v53
	v_lshl_add_u64 v[54:55], v[66:67], 0, v[114:115]
	v_cvt_pk_bf16_f32 v50, v62, v50
	v_cvt_pk_bf16_f32 v51, v51, v52
	v_cvt_pk_bf16_f32 v52, v69, v59
	v_cvt_pk_bf16_f32 v53, v58, v53
	global_store_dwordx4 v[54:55], v[50:53], off
	s_nop 1
	v_mul_f32_e32 v50, 0xbfb8aa3b, v46
	v_exp_f32_e32 v50, v50
	v_mul_f32_e32 v51, 0xbfb8aa3b, v42
	v_exp_f32_e32 v51, v51
	v_add_u32_e32 v52, 0x90, v147
	v_add_f32_e32 v50, 1.0, v50
	v_rcp_f32_e32 v53, v50
	v_add_f32_e32 v50, 1.0, v51
	v_rcp_f32_e32 v54, v50
	v_mad_i64_i32 v[50:51], s[62:63], v52, s90, v[134:135]
	v_mul_f32_e32 v46, v46, v53
	v_mul_f32_e32 v46, v46, v38
	v_mul_f32_e32 v38, v42, v54
	v_mul_f32_e32 v42, 0xbfb8aa3b, v47
	v_exp_f32_e32 v42, v42
	v_mul_f32_e32 v52, 0xbfb8aa3b, v43
	v_mul_f32_e32 v53, v38, v34
	v_exp_f32_e32 v52, v52
	v_add_f32_e32 v34, 1.0, v42
	v_rcp_f32_e32 v34, v34
	v_mul_f32_e32 v42, 0xbfb8aa3b, v48
	v_exp_f32_e32 v42, v42
	v_add_f32_e32 v38, 1.0, v52
	v_mul_f32_e32 v34, v47, v34
	v_rcp_f32_e32 v38, v38
	v_mul_f32_e32 v34, v34, v39
	v_add_f32_e32 v39, 1.0, v42
	v_rcp_f32_e32 v39, v39
	v_mul_f32_e32 v38, v43, v38
	v_mul_f32_e32 v42, 0xbfb8aa3b, v44
	v_mul_f32_e32 v43, v38, v35
	v_mul_f32_e32 v35, v48, v39
	v_exp_f32_e32 v42, v42
	v_mul_f32_e32 v35, v35, v40
	v_mul_f32_e32 v39, 0xbfb8aa3b, v49
	v_mul_f32_e32 v40, 0xbfb8aa3b, v45
	v_exp_f32_e32 v39, v39
	v_exp_f32_e32 v40, v40
	v_add_f32_e32 v38, 1.0, v42
	v_rcp_f32_e32 v38, v38
	v_add_f32_e32 v39, 1.0, v39
	v_add_f32_e32 v40, 1.0, v40
	v_rcp_f32_e32 v39, v39
	v_rcp_f32_e32 v40, v40
	v_mul_f32_e32 v38, v44, v38
	v_mul_f32_e32 v42, v38, v36
	v_mul_f32_e32 v36, v49, v39
	v_mul_f32_e32 v38, v45, v40
	v_mul_f32_e32 v36, v36, v41
	v_mul_f32_e32 v37, v38, v37
	v_lshl_add_u64 v[38:39], v[50:51], 0, v[114:115]
	v_cvt_pk_bf16_f32 v34, v46, v34
	v_cvt_pk_bf16_f32 v35, v35, v36
	v_cvt_pk_bf16_f32 v36, v53, v43
	v_cvt_pk_bf16_f32 v37, v42, v37
	global_store_dwordx4 v[38:39], v[34:37], off
	s_nop 1
	v_mul_f32_e32 v34, 0xbfb8aa3b, v30
	v_exp_f32_e32 v34, v34
	v_mul_f32_e32 v35, 0xbfb8aa3b, v26
	v_exp_f32_e32 v35, v35
	v_add_u32_e32 v36, 0xa0, v147
	v_add_f32_e32 v34, 1.0, v34
	v_rcp_f32_e32 v37, v34
	v_add_f32_e32 v34, 1.0, v35
	v_rcp_f32_e32 v38, v34
	v_mad_i64_i32 v[34:35], s[62:63], v36, s90, v[134:135]
	v_mul_f32_e32 v30, v30, v37
	v_mul_f32_e32 v30, v30, v22
	v_mul_f32_e32 v22, v26, v38
	v_mul_f32_e32 v26, 0xbfb8aa3b, v31
	v_exp_f32_e32 v26, v26
	v_mul_f32_e32 v36, 0xbfb8aa3b, v27
	v_mul_f32_e32 v37, v22, v18
	v_exp_f32_e32 v36, v36
	v_add_f32_e32 v18, 1.0, v26
	v_rcp_f32_e32 v18, v18
	v_mul_f32_e32 v26, 0xbfb8aa3b, v32
	v_exp_f32_e32 v26, v26
	v_add_f32_e32 v22, 1.0, v36
	v_mul_f32_e32 v18, v31, v18
	v_rcp_f32_e32 v22, v22
	v_mul_f32_e32 v18, v18, v23
	v_add_f32_e32 v23, 1.0, v26
	v_rcp_f32_e32 v23, v23
	v_mul_f32_e32 v22, v27, v22
	v_mul_f32_e32 v26, 0xbfb8aa3b, v28
	v_mul_f32_e32 v27, v22, v19
	v_mul_f32_e32 v19, v32, v23
	v_exp_f32_e32 v26, v26
	v_mul_f32_e32 v19, v19, v24
	v_mul_f32_e32 v23, 0xbfb8aa3b, v33
	v_mul_f32_e32 v24, 0xbfb8aa3b, v29
	v_exp_f32_e32 v23, v23
	v_exp_f32_e32 v24, v24
	v_add_f32_e32 v22, 1.0, v26
	v_rcp_f32_e32 v22, v22
	v_add_f32_e32 v23, 1.0, v23
	v_add_f32_e32 v24, 1.0, v24
	v_rcp_f32_e32 v23, v23
	v_rcp_f32_e32 v24, v24
	v_mul_f32_e32 v22, v28, v22
	v_mul_f32_e32 v26, v22, v20
	v_mul_f32_e32 v20, v33, v23
	v_mul_f32_e32 v22, v29, v24
	v_mul_f32_e32 v20, v20, v25
	v_mul_f32_e32 v21, v22, v21
	v_lshl_add_u64 v[22:23], v[34:35], 0, v[114:115]
	v_cvt_pk_bf16_f32 v18, v30, v18
	v_cvt_pk_bf16_f32 v19, v19, v20
	v_cvt_pk_bf16_f32 v20, v37, v27
	v_cvt_pk_bf16_f32 v21, v26, v21
	global_store_dwordx4 v[22:23], v[18:21], off
	s_nop 1
	v_mul_f32_e32 v18, 0xbfb8aa3b, v14
	v_exp_f32_e32 v18, v18
	v_mul_f32_e32 v19, 0xbfb8aa3b, v10
	v_exp_f32_e32 v19, v19
	v_add_u32_e32 v20, 0xb0, v147
	v_add_f32_e32 v18, 1.0, v18
	v_rcp_f32_e32 v21, v18
	v_add_f32_e32 v18, 1.0, v19
	v_rcp_f32_e32 v22, v18
	v_mad_i64_i32 v[18:19], s[62:63], v20, s90, v[134:135]
	v_mul_f32_e32 v14, v14, v21
	v_mul_f32_e32 v14, v14, v6
	v_mul_f32_e32 v6, v10, v22
	v_mul_f32_e32 v10, 0xbfb8aa3b, v15
	v_exp_f32_e32 v10, v10
	v_mul_f32_e32 v20, 0xbfb8aa3b, v11
	v_mul_f32_e32 v21, v6, v2
	v_exp_f32_e32 v20, v20
	v_add_f32_e32 v2, 1.0, v10
	v_rcp_f32_e32 v2, v2
	v_mul_f32_e32 v10, 0xbfb8aa3b, v16
	v_exp_f32_e32 v10, v10
	v_add_f32_e32 v6, 1.0, v20
	v_mul_f32_e32 v2, v15, v2
	v_rcp_f32_e32 v6, v6
	v_mul_f32_e32 v2, v2, v7
	v_add_f32_e32 v7, 1.0, v10
	v_rcp_f32_e32 v7, v7
	v_mul_f32_e32 v6, v11, v6
	v_mul_f32_e32 v10, 0xbfb8aa3b, v12
	v_mul_f32_e32 v11, v6, v3
	v_mul_f32_e32 v3, v16, v7
	v_exp_f32_e32 v10, v10
	v_mul_f32_e32 v3, v3, v8
	v_mul_f32_e32 v7, 0xbfb8aa3b, v17
	v_mul_f32_e32 v8, 0xbfb8aa3b, v13
	v_exp_f32_e32 v7, v7
	v_exp_f32_e32 v8, v8
	v_add_f32_e32 v6, 1.0, v10
	v_rcp_f32_e32 v6, v6
	v_add_f32_e32 v7, 1.0, v7
	v_add_f32_e32 v8, 1.0, v8
	v_rcp_f32_e32 v7, v7
	v_rcp_f32_e32 v8, v8
	v_mul_f32_e32 v6, v12, v6
	v_mul_f32_e32 v10, v6, v4
	v_mul_f32_e32 v4, v17, v7
	v_mul_f32_e32 v6, v13, v8
	v_mul_f32_e32 v4, v4, v9
	v_mul_f32_e32 v5, v6, v5
	v_lshl_add_u64 v[6:7], v[18:19], 0, v[114:115]
	s_mov_b64 s[62:63], s[16:17]
	v_cvt_pk_bf16_f32 v2, v14, v2
	v_cvt_pk_bf16_f32 v3, v3, v4
	v_cvt_pk_bf16_f32 v4, v21, v11
	v_cvt_pk_bf16_f32 v5, v10, v5
	global_store_dwordx4 v[6:7], v[2:5], off
	s_cbranch_vccz .LBB0_135
	s_waitcnt vmcnt(0)
	s_cmpk_gt_u32 s3, 0xff
	s_cbranch_scc1 .LBB0_142
	s_barrier

; #define PG8_STAGE(bufoff, gbase, voff) do { _Pragma("unroll") for (int _i = 0; _i < 2; ++_i) \
;         asm volatile("s_mov_b32 m0, %2\n\ts_nop 0\n\tglobal_load_lds_dwordx4 %0, %1" :: "v"((voff)[_i]), "s"((const char*)(gbase)), "s"(ldsbase + (unsigned)(bufoff) + ldsw + (unsigned)_i * 8192u) : "memory", "m0"); } while (0)
; #define PG8_LDA(dst, b, h) do { _Pragma("unroll") for (int m = 0; m < 4; ++m) _Pragma("unroll") for (int k = 0; k < 2; ++k) dst[m][k] = *(const PG8_LAS bf16x8*)(lds + PG8_SA(b, h) + aoff + m * 2048 + k * 1024); } while (0)
; #define PG8_LDB(dst, b, h) do { _Pragma("unroll") for (int n = 0; n < 2; ++n) _Pragma("unroll") for (int k = 0; k < 2; ++k) dst[n][k] = *(const PG8_LAS bf16x8*)(lds + PG8_SB(b, h) + boff + n * 2048 + k * 1024); } while (0)
; #define PG8_MMA(ai, bj, At, Bt) do { __builtin_amdgcn_s_setprio(1); _Pragma("unroll") for (int m = 0; m < 4; ++m) _Pragma("unroll") for (int n = 0; n < 2; ++n) _Pragma("unroll") for (int k = 0; k < 2; ++k) \
;         acc[ai][bj][m][n] = __builtin_amdgcn_mfma_f32_16x16x32_bf16(Bt[n][k], At[m][k], acc[ai][bj][m][n], 0, 0, 0); __builtin_amdgcn_s_setprio(0); } while (0)
; template <class Epi, class Sched, bool ALIGN_EPI = false, bool SP2 = false>
; __device__ __forceinline__ void gemm_phase(PG8_LAS unsigned char* lds, const Gemm g, const Sched& S, const Epi& E) {
;     ...
;             PG8_LDB(B0, 0, 0); PG8_LDB(B1, 0, 1); PG8_SCHED; PG8_LDA(At, 0, 0); PG8_STAGE(PG8_SA(1, 1), a1 + hstep, voffA);
;             PG8_WAIT_V(8); PG8_WAIT_L(0); PG8_BAR; PG8_MMA(0, 0, At, B0); PG8_MMA(0, 1, At, B1); PG8_BAR; PG8_SCHED;
;             PG8_LDA(At, 0, 1); PG8_STAGE(PG8_SB(0, 0), b2, voffB); PG8_STAGE(PG8_SB(0, 1), b2 + hstep, voffB); PG8_STAGE(PG8_SA(0, 0), a2, voffA);
;             PG8_WAIT_V(8); PG8_WAIT_L(0); PG8_BAR; PG8_MMA(1, 0, At, B0); PG8_MMA(1, 1, At, B1); PG8_BAR; PG8_SCHED;
;             PG8_LDB(B0, 1, 0); PG8_LDB(B1, 1, 1); PG8_SCHED; PG8_LDA(At, 1, 0); PG8_STAGE(PG8_SA(0, 1), a2 + hstep, voffA);
;             PG8_WAIT_V(8); PG8_WAIT_L(0); PG8_BAR; PG8_MMA(0, 0, At, B0); PG8_MMA(0, 1, At, B1); PG8_BAR; PG8_SCHED;
;             PG8_LDA(At, 1, 1); PG8_STAGE(PG8_SB(1, 0), b3, voffB); PG8_STAGE(PG8_SB(1, 1), b3 + hstep, voffB); PG8_STAGE(PG8_SA(1, 0), a3, voffA);
;             PG8_WAIT_V(8); PG8_WAIT_L(0); PG8_BAR; PG8_MMA(1, 0, At, B0); PG8_MMA(1, 1, At, B1); PG8_BAR; PG8_SCHED;
.LBB0_234:
	ds_read_b128 v[134:137], v145
	ds_read_b128 v[152:155], v145 offset:1024
	ds_read_b128 v[156:159], v145 offset:2048
	ds_read_b128 v[160:163], v145 offset:3072
	ds_read_b128 v[164:167], v146
	ds_read_b128 v[168:171], v146 offset:1024
	ds_read_b128 v[172:175], v146 offset:2048
	ds_read_b128 v[176:179], v146 offset:3072
	s_cmpk_eq_i32 s57, 0xa8
	s_cselect_b32 s76, s4, s53
	s_cselect_b32 s77, s5, s54
	s_cselect_b32 s66, s46, s55
	s_cselect_b32 s67, s47, s56
	s_add_u32 s62, s76, 0x80
	s_addc_u32 s63, s77, 0
	ds_read_b128 v[180:183], v147
	ds_read_b128 v[184:187], v147 offset:1024
	ds_read_b128 v[188:191], v147 offset:2048
	ds_read_b128 v[192:195], v147 offset:3072
	ds_read_b128 v[196:199], v147 offset:4096
	ds_read_b128 v[200:203], v147 offset:5120
	ds_read_b128 v[204:207], v147 offset:6144
	ds_read_b128 v[208:211], v147 offset:7168
	s_mov_b32 m0, s94
	s_nop 0
	global_load_lds_dwordx4 v1, s[50:51]
	s_nop 0
	s_mov_b32 m0, s95
	s_nop 0
	global_load_lds_dwordx4 v141, s[50:51]
	s_waitcnt vmcnt(8)
	s_waitcnt lgkmcnt(0)
	s_barrier
	s_setprio 1
	s_waitcnt lgkmcnt(7)
	v_mfma_f32_16x16x32_bf16 v[126:129], v[134:137], v[180:183], v[126:129]
	v_mfma_f32_16x16x32_bf16 v[126:129], v[152:155], v[184:187], v[126:129]
	s_waitcnt lgkmcnt(5)
	v_mfma_f32_16x16x32_bf16 v[110:113], v[152:155], v[192:195], v[110:113]
	v_mfma_f32_16x16x32_bf16 v[110:113], v[134:137], v[188:191], v[110:113]
	s_waitcnt lgkmcnt(3)
	v_mfma_f32_16x16x32_bf16 v[94:97], v[134:137], v[196:199], v[94:97]
	v_mfma_f32_16x16x32_bf16 v[94:97], v[152:155], v[200:203], v[94:97]
	s_waitcnt lgkmcnt(1)
	v_mfma_f32_16x16x32_bf16 v[78:81], v[152:155], v[208:211], v[78:81]
	v_mfma_f32_16x16x32_bf16 v[78:81], v[134:137], v[204:207], v[78:81]
	v_mfma_f32_16x16x32_bf16 v[74:77], v[156:159], v[204:207], v[74:77]
	v_mfma_f32_16x16x32_bf16 v[74:77], v[160:163], v[208:211], v[74:77]
	v_mfma_f32_16x16x32_bf16 v[90:93], v[160:163], v[200:203], v[90:93]
	v_mfma_f32_16x16x32_bf16 v[90:93], v[156:159], v[196:199], v[90:93]
	v_mfma_f32_16x16x32_bf16 v[106:109], v[156:159], v[188:191], v[106:109]
	v_mfma_f32_16x16x32_bf16 v[106:109], v[160:163], v[192:195], v[106:109]
	s_waitcnt lgkmcnt(0)
	v_mfma_f32_16x16x32_bf16 v[122:125], v[160:163], v[184:187], v[122:125]
	v_mfma_f32_16x16x32_bf16 v[122:125], v[156:159], v[180:183], v[122:125]
	s_setprio 0
	s_setprio 1
	v_mfma_f32_16x16x32_bf16 v[118:121], v[164:167], v[180:183], v[118:121]
	v_mfma_f32_16x16x32_bf16 v[118:121], v[168:171], v[184:187], v[118:121]
	v_mfma_f32_16x16x32_bf16 v[102:105], v[168:171], v[192:195], v[102:105]
	v_mfma_f32_16x16x32_bf16 v[102:105], v[164:167], v[188:191], v[102:105]
	v_mfma_f32_16x16x32_bf16 v[86:89], v[164:167], v[196:199], v[86:89]
	v_mfma_f32_16x16x32_bf16 v[86:89], v[168:171], v[200:203], v[86:89]
	v_mfma_f32_16x16x32_bf16 v[70:73], v[168:171], v[208:211], v[70:73]
	v_mfma_f32_16x16x32_bf16 v[70:73], v[164:167], v[204:207], v[70:73]
	v_mfma_f32_16x16x32_bf16 v[66:69], v[172:175], v[204:207], v[66:69]
	v_mfma_f32_16x16x32_bf16 v[66:69], v[176:179], v[208:211], v[66:69]
	v_mfma_f32_16x16x32_bf16 v[82:85], v[176:179], v[200:203], v[82:85]
	v_mfma_f32_16x16x32_bf16 v[82:85], v[172:175], v[196:199], v[82:85]
	v_mfma_f32_16x16x32_bf16 v[98:101], v[172:175], v[188:191], v[98:101]
	v_mfma_f32_16x16x32_bf16 v[98:101], v[176:179], v[192:195], v[98:101]
	v_mfma_f32_16x16x32_bf16 v[114:117], v[176:179], v[184:187], v[114:117]
	s_setprio 2
	s_barrier
	v_mfma_f32_16x16x32_bf16 v[114:117], v[172:175], v[180:183], v[114:117]
	s_setprio 0
	ds_read_b128 v[252:255], v147 offset:16384
	ds_read_b128 v[184:187], v147 offset:17408
	ds_read_b128 v[188:191], v147 offset:18432
	ds_read_b128 v[192:195], v147 offset:19456
	ds_read_b128 v[196:199], v147 offset:20480
	ds_read_b128 v[200:203], v147 offset:21504
	ds_read_b128 v[204:207], v147 offset:22528
	ds_read_b128 v[208:211], v147 offset:23552
	s_mov_b32 m0, s64
	s_nop 0
	global_load_lds_dwordx4 v140, s[66:67]
	s_add_u32 s58, s66, 0x2b0000
	s_mov_b32 m0, s65
	s_nop 0
	global_load_lds_dwordx4 v142, s[66:67]
	s_addc_u32 s59, s67, 0
	s_mov_b32 m0, s82
	s_nop 0
	global_load_lds_dwordx4 v140, s[58:59]
	s_nop 0
	s_mov_b32 m0, s83
	s_nop 0
	global_load_lds_dwordx4 v142, s[58:59]
	s_nop 0
	s_mov_b32 m0, s35
	s_nop 0
	global_load_lds_dwordx4 v1, s[76:77]
	s_nop 0
	s_mov_b32 m0, s84
	s_nop 0
	global_load_lds_dwordx4 v141, s[76:77]
	s_waitcnt vmcnt(8)
	s_waitcnt lgkmcnt(0)
	s_barrier
	s_setprio 1
	s_waitcnt lgkmcnt(7)
	v_mfma_f32_16x16x32_bf16 v[62:65], v[134:137], v[252:255], v[62:65]
	v_mfma_f32_16x16x32_bf16 v[62:65], v[152:155], v[184:187], v[62:65]
	s_waitcnt lgkmcnt(5)
	v_mfma_f32_16x16x32_bf16 v[46:49], v[152:155], v[192:195], v[46:49]
	v_mfma_f32_16x16x32_bf16 v[46:49], v[134:137], v[188:191], v[46:49]
	s_waitcnt lgkmcnt(3)
	v_mfma_f32_16x16x32_bf16 v[30:33], v[134:137], v[196:199], v[30:33]
	v_mfma_f32_16x16x32_bf16 v[30:33], v[152:155], v[200:203], v[30:33]
	s_waitcnt lgkmcnt(1)
	v_mfma_f32_16x16x32_bf16 v[14:17], v[152:155], v[208:211], v[14:17]
	v_mfma_f32_16x16x32_bf16 v[14:17], v[134:137], v[204:207], v[14:17]
	v_mfma_f32_16x16x32_bf16 v[10:13], v[156:159], v[204:207], v[10:13]
	v_mfma_f32_16x16x32_bf16 v[10:13], v[160:163], v[208:211], v[10:13]
	v_mfma_f32_16x16x32_bf16 v[26:29], v[160:163], v[200:203], v[26:29]
	v_mfma_f32_16x16x32_bf16 v[26:29], v[156:159], v[196:199], v[26:29]
	v_mfma_f32_16x16x32_bf16 v[42:45], v[156:159], v[188:191], v[42:45]
	v_mfma_f32_16x16x32_bf16 v[42:45], v[160:163], v[192:195], v[42:45]
	s_waitcnt lgkmcnt(0)
	v_mfma_f32_16x16x32_bf16 v[58:61], v[160:163], v[184:187], v[58:61]
	v_mfma_f32_16x16x32_bf16 v[58:61], v[156:159], v[252:255], v[58:61]
	s_setprio 0
	s_setprio 1
	v_mfma_f32_16x16x32_bf16 v[54:57], v[164:167], v[252:255], v[54:57]
	v_mfma_f32_16x16x32_bf16 v[54:57], v[168:171], v[184:187], v[54:57]
	v_mfma_f32_16x16x32_bf16 v[38:41], v[168:171], v[192:195], v[38:41]
	v_mfma_f32_16x16x32_bf16 v[38:41], v[164:167], v[188:191], v[38:41]
	v_mfma_f32_16x16x32_bf16 v[22:25], v[164:167], v[196:199], v[22:25]
	v_mfma_f32_16x16x32_bf16 v[22:25], v[168:171], v[200:203], v[22:25]
	v_mfma_f32_16x16x32_bf16 v[6:9], v[168:171], v[208:211], v[6:9]
	v_mfma_f32_16x16x32_bf16 v[6:9], v[164:167], v[204:207], v[6:9]
	v_mfma_f32_16x16x32_bf16 v[2:5], v[172:175], v[204:207], v[2:5]
	v_mfma_f32_16x16x32_bf16 v[2:5], v[176:179], v[208:211], v[2:5]
	v_mfma_f32_16x16x32_bf16 v[18:21], v[176:179], v[200:203], v[18:21]
	v_mfma_f32_16x16x32_bf16 v[18:21], v[172:175], v[196:199], v[18:21]
	v_mfma_f32_16x16x32_bf16 v[34:37], v[172:175], v[188:191], v[34:37]
	v_mfma_f32_16x16x32_bf16 v[34:37], v[176:179], v[192:195], v[34:37]
	v_mfma_f32_16x16x32_bf16 v[50:53], v[176:179], v[184:187], v[50:53]
	s_setprio 2
	s_barrier
; #define PG8_STAGE(bufoff, gbase, voff) do { _Pragma("unroll") for (int _i = 0; _i < 2; ++_i) \
;         asm volatile("s_mov_b32 m0, %2\n\ts_nop 0\n\tglobal_load_lds_dwordx4 %0, %1" :: "v"((voff)[_i]), "s"((const char*)(gbase)), "s"(ldsbase + (unsigned)(bufoff) + ldsw + (unsigned)_i * 8192u) : "memory", "m0"); } while (0)
; #define PG8_LDA(dst, b, h) do { _Pragma("unroll") for (int m = 0; m < 4; ++m) _Pragma("unroll") for (int k = 0; k < 2; ++k) dst[m][k] = *(const PG8_LAS bf16x8*)(lds + PG8_SA(b, h) + aoff + m * 2048 + k * 1024); } while (0)
; #define PG8_LDB(dst, b, h) do { _Pragma("unroll") for (int n = 0; n < 2; ++n) _Pragma("unroll") for (int k = 0; k < 2; ++k) dst[n][k] = *(const PG8_LAS bf16x8*)(lds + PG8_SB(b, h) + boff + n * 2048 + k * 1024); } while (0)
; #define PG8_MMA(ai, bj, At, Bt) do { __builtin_amdgcn_s_setprio(1); _Pragma("unroll") for (int m = 0; m < 4; ++m) _Pragma("unroll") for (int n = 0; n < 2; ++n) _Pragma("unroll") for (int k = 0; k < 2; ++k) \
;         acc[ai][bj][m][n] = __builtin_amdgcn_mfma_f32_16x16x32_bf16(Bt[n][k], At[m][k], acc[ai][bj][m][n], 0, 0, 0); __builtin_amdgcn_s_setprio(0); } while (0)
; template <class Epi, class Sched, bool ALIGN_EPI = false, bool SP2 = false>
; __device__ __forceinline__ void gemm_phase(PG8_LAS unsigned char* lds, const Gemm g, const Sched& S, const Epi& E) {
;     ...
;             PG8_LDB(B0, 0, 0); PG8_LDB(B1, 0, 1); PG8_SCHED; PG8_LDA(At, 0, 0); PG8_STAGE(PG8_SA(1, 1), a1 + hstep, voffA);
;             PG8_WAIT_V(8); PG8_WAIT_L(0); PG8_BAR; PG8_MMA(0, 0, At, B0); PG8_MMA(0, 1, At, B1); PG8_BAR; PG8_SCHED;
;             PG8_LDA(At, 0, 1); PG8_STAGE(PG8_SB(0, 0), b2, voffB); PG8_STAGE(PG8_SB(0, 1), b2 + hstep, voffB); PG8_STAGE(PG8_SA(0, 0), a2, voffA);
;             PG8_WAIT_V(8); PG8_WAIT_L(0); PG8_BAR; PG8_MMA(1, 0, At, B0); PG8_MMA(1, 1, At, B1); PG8_BAR; PG8_SCHED;
;             PG8_LDB(B0, 1, 0); PG8_LDB(B1, 1, 1); PG8_SCHED; PG8_LDA(At, 1, 0); PG8_STAGE(PG8_SA(0, 1), a2 + hstep, voffA);
;             PG8_WAIT_V(8); PG8_WAIT_L(0); PG8_BAR; PG8_MMA(0, 0, At, B0); PG8_MMA(0, 1, At, B1); PG8_BAR; PG8_SCHED;
;             PG8_LDA(At, 1, 1); PG8_STAGE(PG8_SB(1, 0), b3, voffB); PG8_STAGE(PG8_SB(1, 1), b3 + hstep, voffB); PG8_STAGE(PG8_SA(1, 0), a3, voffA);
;             PG8_WAIT_V(8); PG8_WAIT_L(0); PG8_BAR; PG8_MMA(1, 0, At, B0); PG8_MMA(1, 1, At, B1); PG8_BAR; PG8_SCHED;
	v_mfma_f32_16x16x32_bf16 v[50:53], v[172:175], v[252:255], v[50:53]
	s_setprio 0
	ds_read_b128 v[134:137], v148
	ds_read_b128 v[152:155], v148 offset:1024
	ds_read_b128 v[156:159], v148 offset:2048
	ds_read_b128 v[160:163], v148 offset:3072
	ds_read_b128 v[164:167], v149
	ds_read_b128 v[168:171], v149 offset:1024
	ds_read_b128 v[248:251], v149 offset:2048
	ds_read_b128 v[176:179], v149 offset:3072
	ds_read_b128 v[180:183], v147 offset:32768
	ds_read_b128 v[184:187], v147 offset:33792
	ds_read_b128 v[188:191], v147 offset:34816
	ds_read_b128 v[192:195], v147 offset:35840
	ds_read_b128 v[196:199], v147 offset:36864
	ds_read_b128 v[200:203], v147 offset:37888
	ds_read_b128 v[204:207], v147 offset:38912
	ds_read_b128 v[208:211], v147 offset:39936
	s_add_u32 s58, s76, 0x2b0000
	s_addc_u32 s59, s77, 0
	s_mov_b32 m0, s85
	s_nop 0
	global_load_lds_dwordx4 v1, s[58:59]
	s_nop 0
	s_mov_b32 m0, s86
	s_nop 0
	global_load_lds_dwordx4 v141, s[58:59]
	s_waitcnt vmcnt(8)
	s_waitcnt lgkmcnt(0)
	s_barrier
	s_setprio 1
	s_waitcnt lgkmcnt(7)
	v_mfma_f32_16x16x32_bf16 v[126:129], v[134:137], v[180:183], v[126:129]
	v_mfma_f32_16x16x32_bf16 v[126:129], v[152:155], v[184:187], v[126:129]
	s_waitcnt lgkmcnt(5)
	v_mfma_f32_16x16x32_bf16 v[110:113], v[152:155], v[192:195], v[110:113]
	v_mfma_f32_16x16x32_bf16 v[110:113], v[134:137], v[188:191], v[110:113]
	s_waitcnt lgkmcnt(3)
	v_mfma_f32_16x16x32_bf16 v[94:97], v[134:137], v[196:199], v[94:97]
	v_mfma_f32_16x16x32_bf16 v[94:97], v[152:155], v[200:203], v[94:97]
	s_waitcnt lgkmcnt(1)
	v_mfma_f32_16x16x32_bf16 v[78:81], v[152:155], v[208:211], v[78:81]
	v_mfma_f32_16x16x32_bf16 v[78:81], v[134:137], v[204:207], v[78:81]
	v_mfma_f32_16x16x32_bf16 v[74:77], v[156:159], v[204:207], v[74:77]
	v_mfma_f32_16x16x32_bf16 v[74:77], v[160:163], v[208:211], v[74:77]
	v_mfma_f32_16x16x32_bf16 v[90:93], v[160:163], v[200:203], v[90:93]
	v_mfma_f32_16x16x32_bf16 v[90:93], v[156:159], v[196:199], v[90:93]
	v_mfma_f32_16x16x32_bf16 v[106:109], v[156:159], v[188:191], v[106:109]
	v_mfma_f32_16x16x32_bf16 v[106:109], v[160:163], v[192:195], v[106:109]
	s_waitcnt lgkmcnt(0)
	v_mfma_f32_16x16x32_bf16 v[122:125], v[160:163], v[184:187], v[122:125]
	v_mfma_f32_16x16x32_bf16 v[122:125], v[156:159], v[180:183], v[122:125]
	s_setprio 0
	s_setprio 1
	v_mfma_f32_16x16x32_bf16 v[118:121], v[164:167], v[180:183], v[118:121]
	v_mfma_f32_16x16x32_bf16 v[118:121], v[168:171], v[184:187], v[118:121]
	v_mfma_f32_16x16x32_bf16 v[102:105], v[168:171], v[192:195], v[102:105]
	v_mfma_f32_16x16x32_bf16 v[102:105], v[164:167], v[188:191], v[102:105]
	v_mfma_f32_16x16x32_bf16 v[86:89], v[164:167], v[196:199], v[86:89]
	v_mfma_f32_16x16x32_bf16 v[86:89], v[168:171], v[200:203], v[86:89]
	v_mfma_f32_16x16x32_bf16 v[70:73], v[168:171], v[208:211], v[70:73]
	v_mfma_f32_16x16x32_bf16 v[70:73], v[164:167], v[204:207], v[70:73]
	v_mfma_f32_16x16x32_bf16 v[66:69], v[248:251], v[204:207], v[66:69]
	v_mfma_f32_16x16x32_bf16 v[66:69], v[176:179], v[208:211], v[66:69]
	v_mfma_f32_16x16x32_bf16 v[82:85], v[176:179], v[200:203], v[82:85]
	v_mfma_f32_16x16x32_bf16 v[82:85], v[248:251], v[196:199], v[82:85]
	v_mfma_f32_16x16x32_bf16 v[98:101], v[248:251], v[188:191], v[98:101]
	v_mfma_f32_16x16x32_bf16 v[98:101], v[176:179], v[192:195], v[98:101]
	v_mfma_f32_16x16x32_bf16 v[114:117], v[176:179], v[184:187], v[114:117]
	s_setprio 2
	s_barrier
; #define PG8_STAGE(bufoff, gbase, voff) do { _Pragma("unroll") for (int _i = 0; _i < 2; ++_i) \
;         asm volatile("s_mov_b32 m0, %2\n\ts_nop 0\n\tglobal_load_lds_dwordx4 %0, %1" :: "v"((voff)[_i]), "s"((const char*)(gbase)), "s"(ldsbase + (unsigned)(bufoff) + ldsw + (unsigned)_i * 8192u) : "memory", "m0"); } while (0)
; #define PG8_LDA(dst, b, h) do { _Pragma("unroll") for (int m = 0; m < 4; ++m) _Pragma("unroll") for (int k = 0; k < 2; ++k) dst[m][k] = *(const PG8_LAS bf16x8*)(lds + PG8_SA(b, h) + aoff + m * 2048 + k * 1024); } while (0)
; #define PG8_LDB(dst, b, h) do { _Pragma("unroll") for (int n = 0; n < 2; ++n) _Pragma("unroll") for (int k = 0; k < 2; ++k) dst[n][k] = *(const PG8_LAS bf16x8*)(lds + PG8_SB(b, h) + boff + n * 2048 + k * 1024); } while (0)
; #define PG8_MMA(ai, bj, At, Bt) do { __builtin_amdgcn_s_setprio(1); _Pragma("unroll") for (int m = 0; m < 4; ++m) _Pragma("unroll") for (int n = 0; n < 2; ++n) _Pragma("unroll") for (int k = 0; k < 2; ++k) \
;         acc[ai][bj][m][n] = __builtin_amdgcn_mfma_f32_16x16x32_bf16(Bt[n][k], At[m][k], acc[ai][bj][m][n], 0, 0, 0); __builtin_amdgcn_s_setprio(0); } while (0)
; template <class Epi, class Sched, bool ALIGN_EPI = false, bool SP2 = false>
; __device__ __forceinline__ void gemm_phase(PG8_LAS unsigned char* lds, const Gemm g, const Sched& S, const Epi& E) {
;     ...
;             PG8_LDB(B0, 0, 0); PG8_LDB(B1, 0, 1); PG8_SCHED; PG8_LDA(At, 0, 0); PG8_STAGE(PG8_SA(1, 1), a1 + hstep, voffA);
;             PG8_WAIT_V(8); PG8_WAIT_L(0); PG8_BAR; PG8_MMA(0, 0, At, B0); PG8_MMA(0, 1, At, B1); PG8_BAR; PG8_SCHED;
;             PG8_LDA(At, 0, 1); PG8_STAGE(PG8_SB(0, 0), b2, voffB); PG8_STAGE(PG8_SB(0, 1), b2 + hstep, voffB); PG8_STAGE(PG8_SA(0, 0), a2, voffA);
;             PG8_WAIT_V(8); PG8_WAIT_L(0); PG8_BAR; PG8_MMA(1, 0, At, B0); PG8_MMA(1, 1, At, B1); PG8_BAR; PG8_SCHED;
;             PG8_LDB(B0, 1, 0); PG8_LDB(B1, 1, 1); PG8_SCHED; PG8_LDA(At, 1, 0); PG8_STAGE(PG8_SA(0, 1), a2 + hstep, voffA);
;             PG8_WAIT_V(8); PG8_WAIT_L(0); PG8_BAR; PG8_MMA(0, 0, At, B0); PG8_MMA(0, 1, At, B1); PG8_BAR; PG8_SCHED;
;             PG8_LDA(At, 1, 1); PG8_STAGE(PG8_SB(1, 0), b3, voffB); PG8_STAGE(PG8_SB(1, 1), b3 + hstep, voffB); PG8_STAGE(PG8_SA(1, 0), a3, voffA);
;             PG8_WAIT_V(8); PG8_WAIT_L(0); PG8_BAR; PG8_MMA(1, 0, At, B0); PG8_MMA(1, 1, At, B1); PG8_BAR; PG8_SCHED;
	v_mfma_f32_16x16x32_bf16 v[114:117], v[248:251], v[180:183], v[114:117]
	s_setprio 0
	ds_read_b128 v[252:255], v147 offset:49152
	ds_read_b128 v[184:187], v147 offset:50176
	ds_read_b128 v[188:191], v147 offset:51200
	ds_read_b128 v[192:195], v147 offset:52224
	ds_read_b128 v[196:199], v147 offset:53248
	ds_read_b128 v[200:203], v147 offset:54272
	ds_read_b128 v[204:207], v147 offset:55296
	ds_read_b128 v[208:211], v147 offset:56320
	s_add_u32 s58, s66, 0x80
	s_addc_u32 s59, s67, 0
	s_mov_b32 m0, s88
	s_nop 0
	global_load_lds_dwordx4 v140, s[58:59]
	s_nop 0
	s_mov_b32 m0, s89
	s_nop 0
	global_load_lds_dwordx4 v142, s[58:59]
	s_add_u32 s58, s66, 0x2b0080
	s_addc_u32 s59, s67, 0
	s_mov_b32 m0, s92
	s_nop 0
	global_load_lds_dwordx4 v140, s[58:59]
	s_nop 0
	s_mov_b32 m0, s93
	s_nop 0
	global_load_lds_dwordx4 v142, s[58:59]
	s_nop 0
	s_mov_b32 m0, s90
	s_nop 0
	global_load_lds_dwordx4 v1, s[62:63]
	s_nop 0
	s_mov_b32 m0, s91
	s_nop 0
	global_load_lds_dwordx4 v141, s[62:63]
	s_waitcnt vmcnt(8)
	s_waitcnt lgkmcnt(0)
	s_barrier
	s_setprio 1
	s_waitcnt lgkmcnt(7)
	v_mfma_f32_16x16x32_bf16 v[62:65], v[134:137], v[252:255], v[62:65]
	v_mfma_f32_16x16x32_bf16 v[62:65], v[152:155], v[184:187], v[62:65]
	s_waitcnt lgkmcnt(5)
	v_mfma_f32_16x16x32_bf16 v[46:49], v[152:155], v[192:195], v[46:49]
	v_mfma_f32_16x16x32_bf16 v[46:49], v[134:137], v[188:191], v[46:49]
	s_waitcnt lgkmcnt(3)
	v_mfma_f32_16x16x32_bf16 v[30:33], v[134:137], v[196:199], v[30:33]
	v_mfma_f32_16x16x32_bf16 v[30:33], v[152:155], v[200:203], v[30:33]
	s_waitcnt lgkmcnt(1)
	v_mfma_f32_16x16x32_bf16 v[14:17], v[152:155], v[208:211], v[14:17]
	v_mfma_f32_16x16x32_bf16 v[14:17], v[134:137], v[204:207], v[14:17]
	v_mfma_f32_16x16x32_bf16 v[10:13], v[156:159], v[204:207], v[10:13]
	v_mfma_f32_16x16x32_bf16 v[10:13], v[160:163], v[208:211], v[10:13]
	v_mfma_f32_16x16x32_bf16 v[26:29], v[160:163], v[200:203], v[26:29]
	v_mfma_f32_16x16x32_bf16 v[26:29], v[156:159], v[196:199], v[26:29]
	v_mfma_f32_16x16x32_bf16 v[42:45], v[156:159], v[188:191], v[42:45]
	v_mfma_f32_16x16x32_bf16 v[42:45], v[160:163], v[192:195], v[42:45]
	s_waitcnt lgkmcnt(0)
	v_mfma_f32_16x16x32_bf16 v[58:61], v[160:163], v[184:187], v[58:61]
	v_mfma_f32_16x16x32_bf16 v[58:61], v[156:159], v[252:255], v[58:61]
	s_setprio 0
	s_setprio 1
	v_mfma_f32_16x16x32_bf16 v[54:57], v[164:167], v[252:255], v[54:57]
	v_mfma_f32_16x16x32_bf16 v[54:57], v[168:171], v[184:187], v[54:57]
	v_mfma_f32_16x16x32_bf16 v[38:41], v[168:171], v[192:195], v[38:41]
	v_mfma_f32_16x16x32_bf16 v[38:41], v[164:167], v[188:191], v[38:41]
	v_mfma_f32_16x16x32_bf16 v[22:25], v[164:167], v[196:199], v[22:25]
	v_mfma_f32_16x16x32_bf16 v[22:25], v[168:171], v[200:203], v[22:25]
	v_mfma_f32_16x16x32_bf16 v[6:9], v[168:171], v[208:211], v[6:9]
	v_mfma_f32_16x16x32_bf16 v[6:9], v[164:167], v[204:207], v[6:9]
	v_mfma_f32_16x16x32_bf16 v[2:5], v[248:251], v[204:207], v[2:5]
	v_mfma_f32_16x16x32_bf16 v[2:5], v[176:179], v[208:211], v[2:5]
	v_mfma_f32_16x16x32_bf16 v[18:21], v[176:179], v[200:203], v[18:21]
	v_mfma_f32_16x16x32_bf16 v[18:21], v[248:251], v[196:199], v[18:21]
	v_mfma_f32_16x16x32_bf16 v[34:37], v[248:251], v[188:191], v[34:37]
	v_mfma_f32_16x16x32_bf16 v[34:37], v[176:179], v[192:195], v[34:37]
	v_mfma_f32_16x16x32_bf16 v[50:53], v[176:179], v[184:187], v[50:53]
	s_setprio 2
	s_barrier
	v_mfma_f32_16x16x32_bf16 v[50:53], v[248:251], v[252:255], v[50:53]
	s_setprio 0
	s_add_i32 s57, s57, 2
	s_add_u32 s53, s53, 0x100
	s_addc_u32 s54, s54, 0
	s_add_u32 s55, s55, 0x100
	s_addc_u32 s56, s56, 0
	s_add_u32 s50, s50, 0x100
	s_addc_u32 s51, s51, 0
	s_cmpk_gt_u32 s57, 0xa9
	s_cbranch_scc0 .LBB0_234
	s_and_b64 vcc, exec, s[16:17]
	s_cbranch_vccz .LBB0_237
	s_barrier

; #define PG8_STAGE(bufoff, gbase, voff) do { _Pragma("unroll") for (int _i = 0; _i < 2; ++_i) \
;         asm volatile("s_mov_b32 m0, %2\n\ts_nop 0\n\tglobal_load_lds_dwordx4 %0, %1" :: "v"((voff)[_i]), "s"((const char*)(gbase)), "s"(ldsbase + (unsigned)(bufoff) + ldsw + (unsigned)_i * 8192u) : "memory", "m0"); } while (0)
; #define PG8_LDA(dst, b, h) do { _Pragma("unroll") for (int m = 0; m < 4; ++m) _Pragma("unroll") for (int k = 0; k < 2; ++k) dst[m][k] = *(const PG8_LAS bf16x8*)(lds + PG8_SA(b, h) + aoff + m * 2048 + k * 1024); } while (0)
; #define PG8_LDB(dst, b, h) do { _Pragma("unroll") for (int n = 0; n < 2; ++n) _Pragma("unroll") for (int k = 0; k < 2; ++k) dst[n][k] = *(const PG8_LAS bf16x8*)(lds + PG8_SB(b, h) + boff + n * 2048 + k * 1024); } while (0)
; #define PG8_WAIT_V(n) asm volatile("s_waitcnt vmcnt(" #n ")" ::: "memory")
; #define PG8_WAIT_L(n) asm volatile("s_waitcnt lgkmcnt(" #n ")" ::: "memory")
; #define PG8_BAR __builtin_amdgcn_s_barrier()
; #define PG8_SCHED __builtin_amdgcn_sched_barrier(0)
; template <class Epi, class Sched, bool ALIGN_EPI = false, bool SP2 = false>
; __device__ __forceinline__ void gemm_phase(PG8_LAS unsigned char* lds, const Gemm g, const Sched& S, const Epi& E) {
;     ...
;             const char* a2 = last ? nA : cA + (size_t)(t + 2) * kstep; const char* b2 = last ? nB : cB + (size_t)(t + 2) * kstep;
;     ...
;             PG8_LDB(B0, 0, 0); PG8_LDB(B1, 0, 1); PG8_SCHED; PG8_LDA(At, 0, 0); PG8_STAGE(PG8_SA(1, 1), a1 + hstep, voffA);
;             PG8_WAIT_V(8); PG8_WAIT_L(0); PG8_BAR; PG8_MMA(0, 0, At, B0); PG8_MMA(0, 1, At, B1); PG8_BAR; PG8_SCHED;
;             PG8_LDA(At, 0, 1); PG8_STAGE(PG8_SB(0, 0), b2, voffB); PG8_STAGE(PG8_SB(0, 1), b2 + hstep, voffB); PG8_STAGE(PG8_SA(0, 0), a2, voffA);
;             PG8_WAIT_V(8); PG8_WAIT_L(0); PG8_BAR; PG8_MMA(1, 0, At, B0); PG8_MMA(1, 1, At, B1); PG8_BAR; PG8_SCHED;
;             PG8_LDB(B0, 1, 0); PG8_LDB(B1, 1, 1); PG8_SCHED; PG8_LDA(At, 1, 0); PG8_STAGE(PG8_SA(0, 1), a2 + hstep, voffA);
;             PG8_WAIT_V(8); PG8_WAIT_L(0); PG8_BAR; PG8_MMA(0, 0, At, B0); PG8_MMA(0, 1, At, B1); PG8_BAR; PG8_SCHED;
;             PG8_LDA(At, 1, 1); PG8_STAGE(PG8_SB(1, 0), b3, voffB); PG8_STAGE(PG8_SB(1, 1), b3 + hstep, voffB); PG8_STAGE(PG8_SA(1, 0), a3, voffA);
;             PG8_WAIT_V(8); PG8_WAIT_L(0); PG8_BAR; PG8_MMA(1, 0, At, B0); PG8_MMA(1, 1, At, B1); PG8_BAR; PG8_SCHED;
.LBB0_325:
	v_add_u32_e32 v138, 0x10000, v151
	ds_read_b128 v[154:157], v138
	ds_read_b128 v[158:161], v138 offset:1024
	ds_read_b128 v[162:165], v138 offset:2048
	ds_read_b128 v[166:169], v138 offset:3072
	v_add_u32_e32 v138, 0x14000, v151
	s_add_u32 s8, s82, 0x100
	ds_read_b128 v[170:173], v138
	ds_read_b128 v[174:177], v138 offset:1024
	ds_read_b128 v[178:181], v138 offset:2048
	ds_read_b128 v[182:185], v138 offset:3072
	s_addc_u32 s9, s83, 0
	s_and_b64 s[60:61], s[62:63], exec
	s_cselect_b32 s84, s54, s8
	s_cselect_b32 s85, s19, s9
	s_cselect_b32 s63, s17, s57
	s_cselect_b32 s62, s55, s56
	s_add_u32 s66, s84, 0x80
	s_addc_u32 s67, s85, 0
	s_add_u32 s76, s62, 0x80
	s_addc_u32 s77, s63, 0
	ds_read_b128 v[186:189], v152
	ds_read_b128 v[190:193], v152 offset:1024
	ds_read_b128 v[194:197], v152 offset:2048
	ds_read_b128 v[198:201], v152 offset:3072
	ds_read_b128 v[202:205], v152 offset:4096
	ds_read_b128 v[206:209], v152 offset:5120
	ds_read_b128 v[210:213], v152 offset:6144
	ds_read_b128 v[214:217], v152 offset:7168
	s_add_u32 s60, s82, 0x100080
	s_addc_u32 s61, s83, 0
	s_mov_b32 m0, s97
	s_nop 0
	global_load_lds_dwordx4 v141, s[60:61]
	s_nop 0
	s_mov_b32 m0, s70
	s_nop 0
	global_load_lds_dwordx4 v143, s[60:61]
	s_waitcnt vmcnt(8)
	s_waitcnt lgkmcnt(0)
	s_barrier
	s_setprio 1
	s_waitcnt lgkmcnt(7)
	v_mfma_f32_16x16x32_bf16 v[126:129], v[154:157], v[186:189], v[126:129]
	v_mfma_f32_16x16x32_bf16 v[126:129], v[158:161], v[190:193], v[126:129]
	s_waitcnt lgkmcnt(5)
	v_mfma_f32_16x16x32_bf16 v[110:113], v[158:161], v[198:201], v[110:113]
	v_mfma_f32_16x16x32_bf16 v[110:113], v[154:157], v[194:197], v[110:113]
	s_waitcnt lgkmcnt(3)
	v_mfma_f32_16x16x32_bf16 v[94:97], v[154:157], v[202:205], v[94:97]
	v_mfma_f32_16x16x32_bf16 v[94:97], v[158:161], v[206:209], v[94:97]
	s_waitcnt lgkmcnt(1)
	v_mfma_f32_16x16x32_bf16 v[78:81], v[158:161], v[214:217], v[78:81]
	v_mfma_f32_16x16x32_bf16 v[78:81], v[154:157], v[210:213], v[78:81]
	v_mfma_f32_16x16x32_bf16 v[74:77], v[162:165], v[210:213], v[74:77]
	v_mfma_f32_16x16x32_bf16 v[74:77], v[166:169], v[214:217], v[74:77]
	v_mfma_f32_16x16x32_bf16 v[90:93], v[166:169], v[206:209], v[90:93]
	v_mfma_f32_16x16x32_bf16 v[90:93], v[162:165], v[202:205], v[90:93]
	v_mfma_f32_16x16x32_bf16 v[106:109], v[162:165], v[194:197], v[106:109]
	v_mfma_f32_16x16x32_bf16 v[106:109], v[166:169], v[198:201], v[106:109]
	s_waitcnt lgkmcnt(0)
	v_mfma_f32_16x16x32_bf16 v[122:125], v[166:169], v[190:193], v[122:125]
	v_mfma_f32_16x16x32_bf16 v[122:125], v[162:165], v[186:189], v[122:125]
	s_setprio 0
	s_setprio 1
	v_mfma_f32_16x16x32_bf16 v[118:121], v[170:173], v[186:189], v[118:121]
	v_mfma_f32_16x16x32_bf16 v[118:121], v[174:177], v[190:193], v[118:121]
	v_mfma_f32_16x16x32_bf16 v[102:105], v[174:177], v[198:201], v[102:105]
	v_mfma_f32_16x16x32_bf16 v[102:105], v[170:173], v[194:197], v[102:105]
	v_mfma_f32_16x16x32_bf16 v[86:89], v[170:173], v[202:205], v[86:89]
	v_mfma_f32_16x16x32_bf16 v[86:89], v[174:177], v[206:209], v[86:89]
	v_mfma_f32_16x16x32_bf16 v[70:73], v[174:177], v[214:217], v[70:73]
	v_mfma_f32_16x16x32_bf16 v[70:73], v[170:173], v[210:213], v[70:73]
	v_mfma_f32_16x16x32_bf16 v[66:69], v[178:181], v[210:213], v[66:69]
	v_mfma_f32_16x16x32_bf16 v[66:69], v[182:185], v[214:217], v[66:69]
	v_mfma_f32_16x16x32_bf16 v[82:85], v[182:185], v[206:209], v[82:85]
	v_mfma_f32_16x16x32_bf16 v[82:85], v[178:181], v[202:205], v[82:85]
	v_mfma_f32_16x16x32_bf16 v[98:101], v[178:181], v[194:197], v[98:101]
	v_mfma_f32_16x16x32_bf16 v[98:101], v[182:185], v[198:201], v[98:101]
	v_mfma_f32_16x16x32_bf16 v[114:117], v[182:185], v[190:193], v[114:117]
	s_setprio 2
	s_barrier
	v_mfma_f32_16x16x32_bf16 v[114:117], v[178:181], v[186:189], v[114:117]
	s_setprio 0
	ds_read_b128 v[252:255], v152 offset:16384
	ds_read_b128 v[190:193], v152 offset:17408
	ds_read_b128 v[194:197], v152 offset:18432
	ds_read_b128 v[198:201], v152 offset:19456
	ds_read_b128 v[202:205], v152 offset:20480
	ds_read_b128 v[206:209], v152 offset:21504
	ds_read_b128 v[210:213], v152 offset:22528
	ds_read_b128 v[214:217], v152 offset:23552
	s_mov_b32 m0, s68
	s_nop 0
	global_load_lds_dwordx4 v142, s[62:63]
	s_add_u32 s60, s62, 0x100000
	s_mov_b32 m0, s69
	s_nop 0
	global_load_lds_dwordx4 v144, s[62:63]
	s_addc_u32 s61, s63, 0
	s_mov_b32 m0, s81
	s_nop 0
	global_load_lds_dwordx4 v142, s[60:61]
	s_nop 0
	s_mov_b32 m0, s86
	s_nop 0
	global_load_lds_dwordx4 v144, s[60:61]
	s_nop 0
	s_mov_b32 m0, s65
	s_nop 0
	global_load_lds_dwordx4 v141, s[84:85]
	s_nop 0
	s_mov_b32 m0, s87
	s_nop 0
	global_load_lds_dwordx4 v143, s[84:85]
	s_waitcnt vmcnt(8)
	s_waitcnt lgkmcnt(0)
	s_barrier
; #define PG8_STAGE(bufoff, gbase, voff) do { _Pragma("unroll") for (int _i = 0; _i < 2; ++_i) \
;         asm volatile("s_mov_b32 m0, %2\n\ts_nop 0\n\tglobal_load_lds_dwordx4 %0, %1" :: "v"((voff)[_i]), "s"((const char*)(gbase)), "s"(ldsbase + (unsigned)(bufoff) + ldsw + (unsigned)_i * 8192u) : "memory", "m0"); } while (0)
; #define PG8_LDA(dst, b, h) do { _Pragma("unroll") for (int m = 0; m < 4; ++m) _Pragma("unroll") for (int k = 0; k < 2; ++k) dst[m][k] = *(const PG8_LAS bf16x8*)(lds + PG8_SA(b, h) + aoff + m * 2048 + k * 1024); } while (0)
; #define PG8_LDB(dst, b, h) do { _Pragma("unroll") for (int n = 0; n < 2; ++n) _Pragma("unroll") for (int k = 0; k < 2; ++k) dst[n][k] = *(const PG8_LAS bf16x8*)(lds + PG8_SB(b, h) + boff + n * 2048 + k * 1024); } while (0)
; #define PG8_MMA(ai, bj, At, Bt) do { __builtin_amdgcn_s_setprio(1); _Pragma("unroll") for (int m = 0; m < 4; ++m) _Pragma("unroll") for (int n = 0; n < 2; ++n) _Pragma("unroll") for (int k = 0; k < 2; ++k) \
;         acc[ai][bj][m][n] = __builtin_amdgcn_mfma_f32_16x16x32_bf16(Bt[n][k], At[m][k], acc[ai][bj][m][n], 0, 0, 0); __builtin_amdgcn_s_setprio(0); } while (0)
; template <class Epi, class Sched, bool ALIGN_EPI = false, bool SP2 = false>
; __device__ __forceinline__ void gemm_phase(PG8_LAS unsigned char* lds, const Gemm g, const Sched& S, const Epi& E) {
;     ...
;             PG8_LDB(B0, 0, 0); PG8_LDB(B1, 0, 1); PG8_SCHED; PG8_LDA(At, 0, 0); PG8_STAGE(PG8_SA(1, 1), a1 + hstep, voffA);
;             PG8_WAIT_V(8); PG8_WAIT_L(0); PG8_BAR; PG8_MMA(0, 0, At, B0); PG8_MMA(0, 1, At, B1); PG8_BAR; PG8_SCHED;
;             PG8_LDA(At, 0, 1); PG8_STAGE(PG8_SB(0, 0), b2, voffB); PG8_STAGE(PG8_SB(0, 1), b2 + hstep, voffB); PG8_STAGE(PG8_SA(0, 0), a2, voffA);
;             PG8_WAIT_V(8); PG8_WAIT_L(0); PG8_BAR; PG8_MMA(1, 0, At, B0); PG8_MMA(1, 1, At, B1); PG8_BAR; PG8_SCHED;
;             PG8_LDB(B0, 1, 0); PG8_LDB(B1, 1, 1); PG8_SCHED; PG8_LDA(At, 1, 0); PG8_STAGE(PG8_SA(0, 1), a2 + hstep, voffA);
;             PG8_WAIT_V(8); PG8_WAIT_L(0); PG8_BAR; PG8_MMA(0, 0, At, B0); PG8_MMA(0, 1, At, B1); PG8_BAR; PG8_SCHED;
;             PG8_LDA(At, 1, 1); PG8_STAGE(PG8_SB(1, 0), b3, voffB); PG8_STAGE(PG8_SB(1, 1), b3 + hstep, voffB); PG8_STAGE(PG8_SA(1, 0), a3, voffA);
;             PG8_WAIT_V(8); PG8_WAIT_L(0); PG8_BAR; PG8_MMA(1, 0, At, B0); PG8_MMA(1, 1, At, B1); PG8_BAR; PG8_SCHED;
	s_setprio 1
	s_waitcnt lgkmcnt(7)
	v_mfma_f32_16x16x32_bf16 v[62:65], v[154:157], v[252:255], v[62:65]
	v_mfma_f32_16x16x32_bf16 v[62:65], v[158:161], v[190:193], v[62:65]
	s_waitcnt lgkmcnt(5)
	v_mfma_f32_16x16x32_bf16 v[46:49], v[158:161], v[198:201], v[46:49]
	v_mfma_f32_16x16x32_bf16 v[46:49], v[154:157], v[194:197], v[46:49]
	s_waitcnt lgkmcnt(3)
	v_mfma_f32_16x16x32_bf16 v[30:33], v[154:157], v[202:205], v[30:33]
	v_mfma_f32_16x16x32_bf16 v[30:33], v[158:161], v[206:209], v[30:33]
	s_waitcnt lgkmcnt(1)
	v_mfma_f32_16x16x32_bf16 v[14:17], v[158:161], v[214:217], v[14:17]
	v_mfma_f32_16x16x32_bf16 v[14:17], v[154:157], v[210:213], v[14:17]
	v_mfma_f32_16x16x32_bf16 v[10:13], v[162:165], v[210:213], v[10:13]
	v_mfma_f32_16x16x32_bf16 v[10:13], v[166:169], v[214:217], v[10:13]
	v_mfma_f32_16x16x32_bf16 v[26:29], v[166:169], v[206:209], v[26:29]
	v_mfma_f32_16x16x32_bf16 v[26:29], v[162:165], v[202:205], v[26:29]
	v_mfma_f32_16x16x32_bf16 v[42:45], v[162:165], v[194:197], v[42:45]
	v_mfma_f32_16x16x32_bf16 v[42:45], v[166:169], v[198:201], v[42:45]
	s_waitcnt lgkmcnt(0)
	v_mfma_f32_16x16x32_bf16 v[58:61], v[166:169], v[190:193], v[58:61]
	v_mfma_f32_16x16x32_bf16 v[58:61], v[162:165], v[252:255], v[58:61]
	s_setprio 0
	s_setprio 1
	v_mfma_f32_16x16x32_bf16 v[54:57], v[170:173], v[252:255], v[54:57]
	v_mfma_f32_16x16x32_bf16 v[54:57], v[174:177], v[190:193], v[54:57]
	v_mfma_f32_16x16x32_bf16 v[38:41], v[174:177], v[198:201], v[38:41]
	v_mfma_f32_16x16x32_bf16 v[38:41], v[170:173], v[194:197], v[38:41]
	v_mfma_f32_16x16x32_bf16 v[22:25], v[170:173], v[202:205], v[22:25]
	v_mfma_f32_16x16x32_bf16 v[22:25], v[174:177], v[206:209], v[22:25]
	v_mfma_f32_16x16x32_bf16 v[6:9], v[174:177], v[214:217], v[6:9]
	v_mfma_f32_16x16x32_bf16 v[6:9], v[170:173], v[210:213], v[6:9]
	v_mfma_f32_16x16x32_bf16 v[2:5], v[178:181], v[210:213], v[2:5]
	v_mfma_f32_16x16x32_bf16 v[2:5], v[182:185], v[214:217], v[2:5]
	v_mfma_f32_16x16x32_bf16 v[18:21], v[182:185], v[206:209], v[18:21]
	v_mfma_f32_16x16x32_bf16 v[18:21], v[178:181], v[202:205], v[18:21]
	v_mfma_f32_16x16x32_bf16 v[34:37], v[178:181], v[194:197], v[34:37]
	v_mfma_f32_16x16x32_bf16 v[34:37], v[182:185], v[198:201], v[34:37]
	v_mfma_f32_16x16x32_bf16 v[50:53], v[182:185], v[190:193], v[50:53]
	s_setprio 2
	s_barrier
	v_mfma_f32_16x16x32_bf16 v[50:53], v[178:181], v[252:255], v[50:53]
	s_setprio 0
	v_add_u32_e32 v138, 0x18000, v151
	ds_read_b128 v[154:157], v138
	ds_read_b128 v[158:161], v138 offset:1024
	ds_read_b128 v[162:165], v138 offset:2048
	ds_read_b128 v[166:169], v138 offset:3072
	v_add_u32_e32 v138, 0x1c000, v151
	ds_read_b128 v[170:173], v138
	ds_read_b128 v[174:177], v138 offset:1024
	ds_read_b128 v[248:251], v138 offset:2048
	ds_read_b128 v[182:185], v138 offset:3072
	ds_read_b128 v[186:189], v152 offset:32768
	ds_read_b128 v[190:193], v152 offset:33792
	ds_read_b128 v[194:197], v152 offset:34816
	ds_read_b128 v[198:201], v152 offset:35840
	ds_read_b128 v[202:205], v152 offset:36864
	ds_read_b128 v[206:209], v152 offset:37888
	ds_read_b128 v[210:213], v152 offset:38912
	ds_read_b128 v[214:217], v152 offset:39936
	s_add_u32 s60, s84, 0x100000
	s_addc_u32 s61, s85, 0
	s_mov_b32 m0, s88
	s_nop 0
	global_load_lds_dwordx4 v141, s[60:61]
	s_nop 0
	s_mov_b32 m0, s89
	s_nop 0
	global_load_lds_dwordx4 v143, s[60:61]
	s_waitcnt vmcnt(8)
	s_waitcnt lgkmcnt(0)
	s_barrier
	s_setprio 1
	s_waitcnt lgkmcnt(7)
	v_mfma_f32_16x16x32_bf16 v[126:129], v[154:157], v[186:189], v[126:129]
	v_mfma_f32_16x16x32_bf16 v[126:129], v[158:161], v[190:193], v[126:129]
	s_waitcnt lgkmcnt(5)
	v_mfma_f32_16x16x32_bf16 v[110:113], v[158:161], v[198:201], v[110:113]
	v_mfma_f32_16x16x32_bf16 v[110:113], v[154:157], v[194:197], v[110:113]
	s_waitcnt lgkmcnt(3)
	v_mfma_f32_16x16x32_bf16 v[94:97], v[154:157], v[202:205], v[94:97]
	v_mfma_f32_16x16x32_bf16 v[94:97], v[158:161], v[206:209], v[94:97]
	s_waitcnt lgkmcnt(1)
	v_mfma_f32_16x16x32_bf16 v[78:81], v[158:161], v[214:217], v[78:81]
	v_mfma_f32_16x16x32_bf16 v[78:81], v[154:157], v[210:213], v[78:81]
	v_mfma_f32_16x16x32_bf16 v[74:77], v[162:165], v[210:213], v[74:77]
	v_mfma_f32_16x16x32_bf16 v[74:77], v[166:169], v[214:217], v[74:77]
	v_mfma_f32_16x16x32_bf16 v[90:93], v[166:169], v[206:209], v[90:93]
	v_mfma_f32_16x16x32_bf16 v[90:93], v[162:165], v[202:205], v[90:93]
	v_mfma_f32_16x16x32_bf16 v[106:109], v[162:165], v[194:197], v[106:109]
	v_mfma_f32_16x16x32_bf16 v[106:109], v[166:169], v[198:201], v[106:109]
	s_waitcnt lgkmcnt(0)
	v_mfma_f32_16x16x32_bf16 v[122:125], v[166:169], v[190:193], v[122:125]
	v_mfma_f32_16x16x32_bf16 v[122:125], v[162:165], v[186:189], v[122:125]
	s_setprio 0
	s_setprio 1
	v_mfma_f32_16x16x32_bf16 v[118:121], v[170:173], v[186:189], v[118:121]
	v_mfma_f32_16x16x32_bf16 v[118:121], v[174:177], v[190:193], v[118:121]
	v_mfma_f32_16x16x32_bf16 v[102:105], v[174:177], v[198:201], v[102:105]
	v_mfma_f32_16x16x32_bf16 v[102:105], v[170:173], v[194:197], v[102:105]
	v_mfma_f32_16x16x32_bf16 v[86:89], v[170:173], v[202:205], v[86:89]
	v_mfma_f32_16x16x32_bf16 v[86:89], v[174:177], v[206:209], v[86:89]
	v_mfma_f32_16x16x32_bf16 v[70:73], v[174:177], v[214:217], v[70:73]
	v_mfma_f32_16x16x32_bf16 v[70:73], v[170:173], v[210:213], v[70:73]
	v_mfma_f32_16x16x32_bf16 v[66:69], v[248:251], v[210:213], v[66:69]
	v_mfma_f32_16x16x32_bf16 v[66:69], v[182:185], v[214:217], v[66:69]
	v_mfma_f32_16x16x32_bf16 v[82:85], v[182:185], v[206:209], v[82:85]
	v_mfma_f32_16x16x32_bf16 v[82:85], v[248:251], v[202:205], v[82:85]
	v_mfma_f32_16x16x32_bf16 v[98:101], v[248:251], v[194:197], v[98:101]
	v_mfma_f32_16x16x32_bf16 v[98:101], v[182:185], v[198:201], v[98:101]
	v_mfma_f32_16x16x32_bf16 v[114:117], v[182:185], v[190:193], v[114:117]
	s_setprio 2
	s_barrier
; #define PG8_STAGE(bufoff, gbase, voff) do { _Pragma("unroll") for (int _i = 0; _i < 2; ++_i) \
;         asm volatile("s_mov_b32 m0, %2\n\ts_nop 0\n\tglobal_load_lds_dwordx4 %0, %1" :: "v"((voff)[_i]), "s"((const char*)(gbase)), "s"(ldsbase + (unsigned)(bufoff) + ldsw + (unsigned)_i * 8192u) : "memory", "m0"); } while (0)
; #define PG8_LDA(dst, b, h) do { _Pragma("unroll") for (int m = 0; m < 4; ++m) _Pragma("unroll") for (int k = 0; k < 2; ++k) dst[m][k] = *(const PG8_LAS bf16x8*)(lds + PG8_SA(b, h) + aoff + m * 2048 + k * 1024); } while (0)
; #define PG8_LDB(dst, b, h) do { _Pragma("unroll") for (int n = 0; n < 2; ++n) _Pragma("unroll") for (int k = 0; k < 2; ++k) dst[n][k] = *(const PG8_LAS bf16x8*)(lds + PG8_SB(b, h) + boff + n * 2048 + k * 1024); } while (0)
; #define PG8_MMA(ai, bj, At, Bt) do { __builtin_amdgcn_s_setprio(1); _Pragma("unroll") for (int m = 0; m < 4; ++m) _Pragma("unroll") for (int n = 0; n < 2; ++n) _Pragma("unroll") for (int k = 0; k < 2; ++k) \
;         acc[ai][bj][m][n] = __builtin_amdgcn_mfma_f32_16x16x32_bf16(Bt[n][k], At[m][k], acc[ai][bj][m][n], 0, 0, 0); __builtin_amdgcn_s_setprio(0); } while (0)
; template <class Epi, class Sched, bool ALIGN_EPI = false, bool SP2 = false>
; __device__ __forceinline__ void gemm_phase(PG8_LAS unsigned char* lds, const Gemm g, const Sched& S, const Epi& E) {
;     ...
;             PG8_LDB(B0, 0, 0); PG8_LDB(B1, 0, 1); PG8_SCHED; PG8_LDA(At, 0, 0); PG8_STAGE(PG8_SA(1, 1), a1 + hstep, voffA);
;             PG8_WAIT_V(8); PG8_WAIT_L(0); PG8_BAR; PG8_MMA(0, 0, At, B0); PG8_MMA(0, 1, At, B1); PG8_BAR; PG8_SCHED;
;             PG8_LDA(At, 0, 1); PG8_STAGE(PG8_SB(0, 0), b2, voffB); PG8_STAGE(PG8_SB(0, 1), b2 + hstep, voffB); PG8_STAGE(PG8_SA(0, 0), a2, voffA);
;             PG8_WAIT_V(8); PG8_WAIT_L(0); PG8_BAR; PG8_MMA(1, 0, At, B0); PG8_MMA(1, 1, At, B1); PG8_BAR; PG8_SCHED;
;             PG8_LDB(B0, 1, 0); PG8_LDB(B1, 1, 1); PG8_SCHED; PG8_LDA(At, 1, 0); PG8_STAGE(PG8_SA(0, 1), a2 + hstep, voffA);
;             PG8_WAIT_V(8); PG8_WAIT_L(0); PG8_BAR; PG8_MMA(0, 0, At, B0); PG8_MMA(0, 1, At, B1); PG8_BAR; PG8_SCHED;
;             PG8_LDA(At, 1, 1); PG8_STAGE(PG8_SB(1, 0), b3, voffB); PG8_STAGE(PG8_SB(1, 1), b3 + hstep, voffB); PG8_STAGE(PG8_SA(1, 0), a3, voffA);
;             PG8_WAIT_V(8); PG8_WAIT_L(0); PG8_BAR; PG8_MMA(1, 0, At, B0); PG8_MMA(1, 1, At, B1); PG8_BAR; PG8_SCHED;
	v_mfma_f32_16x16x32_bf16 v[114:117], v[248:251], v[186:189], v[114:117]
	s_setprio 0
	ds_read_b128 v[252:255], v152 offset:49152
	ds_read_b128 v[190:193], v152 offset:50176
	ds_read_b128 v[194:197], v152 offset:51200
	ds_read_b128 v[198:201], v152 offset:52224
	ds_read_b128 v[202:205], v152 offset:53248
	ds_read_b128 v[206:209], v152 offset:54272
	ds_read_b128 v[210:213], v152 offset:55296
	ds_read_b128 v[214:217], v152 offset:56320
	s_mov_b32 m0, s90
	s_nop 0
	global_load_lds_dwordx4 v142, s[76:77]
	s_add_u32 s60, s62, 0x100080
	s_mov_b32 m0, s91
	s_nop 0
	global_load_lds_dwordx4 v144, s[76:77]
	s_addc_u32 s61, s63, 0
	s_mov_b32 m0, s95
	s_nop 0
	global_load_lds_dwordx4 v142, s[60:61]
	s_nop 0
	s_mov_b32 m0, s96
	s_nop 0
	global_load_lds_dwordx4 v144, s[60:61]
	s_nop 0
	s_mov_b32 m0, s92
	s_nop 0
	global_load_lds_dwordx4 v141, s[66:67]
	s_nop 0
	s_mov_b32 m0, s94
	s_nop 0
	global_load_lds_dwordx4 v143, s[66:67]
	s_waitcnt vmcnt(8)
	s_waitcnt lgkmcnt(0)
	s_barrier
	s_setprio 1
	s_waitcnt lgkmcnt(7)
	v_mfma_f32_16x16x32_bf16 v[62:65], v[154:157], v[252:255], v[62:65]
	v_mfma_f32_16x16x32_bf16 v[62:65], v[158:161], v[190:193], v[62:65]
	s_waitcnt lgkmcnt(5)
	v_mfma_f32_16x16x32_bf16 v[46:49], v[158:161], v[198:201], v[46:49]
	v_mfma_f32_16x16x32_bf16 v[46:49], v[154:157], v[194:197], v[46:49]
	s_waitcnt lgkmcnt(3)
	v_mfma_f32_16x16x32_bf16 v[30:33], v[154:157], v[202:205], v[30:33]
	v_mfma_f32_16x16x32_bf16 v[30:33], v[158:161], v[206:209], v[30:33]
	s_waitcnt lgkmcnt(1)
	v_mfma_f32_16x16x32_bf16 v[14:17], v[158:161], v[214:217], v[14:17]
	v_mfma_f32_16x16x32_bf16 v[14:17], v[154:157], v[210:213], v[14:17]
	v_mfma_f32_16x16x32_bf16 v[10:13], v[162:165], v[210:213], v[10:13]
	v_mfma_f32_16x16x32_bf16 v[10:13], v[166:169], v[214:217], v[10:13]
	v_mfma_f32_16x16x32_bf16 v[26:29], v[166:169], v[206:209], v[26:29]
	v_mfma_f32_16x16x32_bf16 v[26:29], v[162:165], v[202:205], v[26:29]
	v_mfma_f32_16x16x32_bf16 v[42:45], v[162:165], v[194:197], v[42:45]
	v_mfma_f32_16x16x32_bf16 v[42:45], v[166:169], v[198:201], v[42:45]
	s_waitcnt lgkmcnt(0)
	v_mfma_f32_16x16x32_bf16 v[58:61], v[166:169], v[190:193], v[58:61]
	v_mfma_f32_16x16x32_bf16 v[58:61], v[162:165], v[252:255], v[58:61]
	s_setprio 0
	s_setprio 1
	v_mfma_f32_16x16x32_bf16 v[54:57], v[170:173], v[252:255], v[54:57]
	v_mfma_f32_16x16x32_bf16 v[54:57], v[174:177], v[190:193], v[54:57]
	v_mfma_f32_16x16x32_bf16 v[38:41], v[174:177], v[198:201], v[38:41]
	v_mfma_f32_16x16x32_bf16 v[38:41], v[170:173], v[194:197], v[38:41]
	v_mfma_f32_16x16x32_bf16 v[22:25], v[170:173], v[202:205], v[22:25]
	v_mfma_f32_16x16x32_bf16 v[22:25], v[174:177], v[206:209], v[22:25]
	v_mfma_f32_16x16x32_bf16 v[6:9], v[174:177], v[214:217], v[6:9]
	v_mfma_f32_16x16x32_bf16 v[6:9], v[170:173], v[210:213], v[6:9]
	v_mfma_f32_16x16x32_bf16 v[2:5], v[248:251], v[210:213], v[2:5]
	v_mfma_f32_16x16x32_bf16 v[2:5], v[182:185], v[214:217], v[2:5]
	v_mfma_f32_16x16x32_bf16 v[18:21], v[182:185], v[206:209], v[18:21]
	v_mfma_f32_16x16x32_bf16 v[18:21], v[248:251], v[202:205], v[18:21]
	v_mfma_f32_16x16x32_bf16 v[34:37], v[248:251], v[194:197], v[34:37]
	v_mfma_f32_16x16x32_bf16 v[34:37], v[182:185], v[198:201], v[34:37]
	v_mfma_f32_16x16x32_bf16 v[50:53], v[182:185], v[190:193], v[50:53]
	s_setprio 2
	s_barrier
	v_mfma_f32_16x16x32_bf16 v[50:53], v[248:251], v[252:255], v[50:53]
	s_setprio 0
	s_add_i32 s58, s58, 2
	s_add_u32 s56, s56, 0x100
	s_addc_u32 s57, s57, 0
	s_cmp_gt_u32 s58, 61
	s_cbranch_scc1 .LBB0_316
	s_mov_b64 s[82:83], s[8:9]
	s_branch .LBB0_320

; #define PG8_STAGE(bufoff, gbase, voff) do { _Pragma("unroll") for (int _i = 0; _i < 2; ++_i) \
;         asm volatile("s_mov_b32 m0, %2\n\ts_nop 0\n\tglobal_load_lds_dwordx4 %0, %1" :: "v"((voff)[_i]), "s"((const char*)(gbase)), "s"(ldsbase + (unsigned)(bufoff) + ldsw + (unsigned)_i * 8192u) : "memory", "m0"); } while (0)
; #define PG8_LDA(dst, b, h) do { _Pragma("unroll") for (int m = 0; m < 4; ++m) _Pragma("unroll") for (int k = 0; k < 2; ++k) dst[m][k] = *(const PG8_LAS bf16x8*)(lds + PG8_SA(b, h) + aoff + m * 2048 + k * 1024); } while (0)
; #define PG8_LDB(dst, b, h) do { _Pragma("unroll") for (int n = 0; n < 2; ++n) _Pragma("unroll") for (int k = 0; k < 2; ++k) dst[n][k] = *(const PG8_LAS bf16x8*)(lds + PG8_SB(b, h) + boff + n * 2048 + k * 1024); } while (0)
; #define PG8_MMA(ai, bj, At, Bt) do { __builtin_amdgcn_s_setprio(1); _Pragma("unroll") for (int m = 0; m < 4; ++m) _Pragma("unroll") for (int n = 0; n < 2; ++n) _Pragma("unroll") for (int k = 0; k < 2; ++k) \
;         acc[ai][bj][m][n] = __builtin_amdgcn_mfma_f32_16x16x32_bf16(Bt[n][k], At[m][k], acc[ai][bj][m][n], 0, 0, 0); __builtin_amdgcn_s_setprio(0); } while (0)
; template <class Epi, class Sched, bool ALIGN_EPI = false, bool SP2 = false>
; __device__ __forceinline__ void gemm_phase(PG8_LAS unsigned char* lds, const Gemm g, const Sched& S, const Epi& E) {
;     ...
;             PG8_LDB(B0, 0, 0); PG8_LDB(B1, 0, 1); PG8_SCHED; PG8_LDA(At, 0, 0); PG8_STAGE(PG8_SA(1, 1), a1 + hstep, voffA);
;             PG8_WAIT_V(8); PG8_WAIT_L(0); PG8_BAR; PG8_MMA(0, 0, At, B0); PG8_MMA(0, 1, At, B1); PG8_BAR; PG8_SCHED;
;             PG8_LDA(At, 0, 1); PG8_STAGE(PG8_SB(0, 0), b2, voffB); PG8_STAGE(PG8_SB(0, 1), b2 + hstep, voffB); PG8_STAGE(PG8_SA(0, 0), a2, voffA);
;             PG8_WAIT_V(8); PG8_WAIT_L(0); PG8_BAR; PG8_MMA(1, 0, At, B0); PG8_MMA(1, 1, At, B1); PG8_BAR; PG8_SCHED;
;             PG8_LDB(B0, 1, 0); PG8_LDB(B1, 1, 1); PG8_SCHED; PG8_LDA(At, 1, 0); PG8_STAGE(PG8_SA(0, 1), a2 + hstep, voffA);
;             PG8_WAIT_V(8); PG8_WAIT_L(0); PG8_BAR; PG8_MMA(0, 0, At, B0); PG8_MMA(0, 1, At, B1); PG8_BAR; PG8_SCHED;
;             PG8_LDA(At, 1, 1); PG8_STAGE(PG8_SB(1, 0), b3, voffB); PG8_STAGE(PG8_SB(1, 1), b3 + hstep, voffB); PG8_STAGE(PG8_SA(1, 0), a3, voffA);
;             PG8_WAIT_V(8); PG8_WAIT_L(0); PG8_BAR; PG8_MMA(1, 0, At, B0); PG8_MMA(1, 1, At, B1); PG8_BAR; PG8_SCHED;
.LBB0_698:
	ds_read_b128 v[134:137], v145
	ds_read_b128 v[152:155], v145 offset:1024
	ds_read_b128 v[156:159], v145 offset:2048
	ds_read_b128 v[160:163], v145 offset:3072
	ds_read_b128 v[164:167], v146
	ds_read_b128 v[168:171], v146 offset:1024
	ds_read_b128 v[172:175], v146 offset:2048
	ds_read_b128 v[176:179], v146 offset:3072
	s_cmp_eq_u32 s69, 60
	s_cselect_b32 s48, s41, s53
	s_cselect_b32 s49, s19, s58
	s_cselect_b32 s46, s52, s59
	s_cselect_b32 s47, s17, s68
	s_add_u32 s44, s48, 0x80
	s_addc_u32 s45, s49, 0
	ds_read_b128 v[180:183], v147
	ds_read_b128 v[184:187], v147 offset:1024
	ds_read_b128 v[188:191], v147 offset:2048
	ds_read_b128 v[192:195], v147 offset:3072
	ds_read_b128 v[196:199], v147 offset:4096
	ds_read_b128 v[200:203], v147 offset:5120
	ds_read_b128 v[204:207], v147 offset:6144
	ds_read_b128 v[208:211], v147 offset:7168
	s_mov_b32 m0, s67
	s_nop 0
	global_load_lds_dwordx4 v1, s[42:43]
	s_nop 0
	s_mov_b32 m0, s74
	s_nop 0
	global_load_lds_dwordx4 v141, s[42:43]
	s_waitcnt vmcnt(8)
	s_waitcnt lgkmcnt(0)
	s_barrier
	s_setprio 1
	s_waitcnt lgkmcnt(7)
	v_mfma_f32_16x16x32_bf16 v[126:129], v[134:137], v[180:183], v[126:129]
	v_mfma_f32_16x16x32_bf16 v[126:129], v[152:155], v[184:187], v[126:129]
	s_waitcnt lgkmcnt(5)
	v_mfma_f32_16x16x32_bf16 v[110:113], v[152:155], v[192:195], v[110:113]
	v_mfma_f32_16x16x32_bf16 v[110:113], v[134:137], v[188:191], v[110:113]
	s_waitcnt lgkmcnt(3)
	v_mfma_f32_16x16x32_bf16 v[94:97], v[134:137], v[196:199], v[94:97]
	v_mfma_f32_16x16x32_bf16 v[94:97], v[152:155], v[200:203], v[94:97]
	s_waitcnt lgkmcnt(1)
	v_mfma_f32_16x16x32_bf16 v[78:81], v[152:155], v[208:211], v[78:81]
	v_mfma_f32_16x16x32_bf16 v[78:81], v[134:137], v[204:207], v[78:81]
	v_mfma_f32_16x16x32_bf16 v[74:77], v[156:159], v[204:207], v[74:77]
	v_mfma_f32_16x16x32_bf16 v[74:77], v[160:163], v[208:211], v[74:77]
	v_mfma_f32_16x16x32_bf16 v[90:93], v[160:163], v[200:203], v[90:93]
	v_mfma_f32_16x16x32_bf16 v[90:93], v[156:159], v[196:199], v[90:93]
	v_mfma_f32_16x16x32_bf16 v[106:109], v[156:159], v[188:191], v[106:109]
	v_mfma_f32_16x16x32_bf16 v[106:109], v[160:163], v[192:195], v[106:109]
	s_waitcnt lgkmcnt(0)
	v_mfma_f32_16x16x32_bf16 v[122:125], v[160:163], v[184:187], v[122:125]
	v_mfma_f32_16x16x32_bf16 v[122:125], v[156:159], v[180:183], v[122:125]
	s_setprio 0
	s_setprio 1
	v_mfma_f32_16x16x32_bf16 v[118:121], v[164:167], v[180:183], v[118:121]
	v_mfma_f32_16x16x32_bf16 v[118:121], v[168:171], v[184:187], v[118:121]
	v_mfma_f32_16x16x32_bf16 v[102:105], v[168:171], v[192:195], v[102:105]
	v_mfma_f32_16x16x32_bf16 v[102:105], v[164:167], v[188:191], v[102:105]
	v_mfma_f32_16x16x32_bf16 v[86:89], v[164:167], v[196:199], v[86:89]
	v_mfma_f32_16x16x32_bf16 v[86:89], v[168:171], v[200:203], v[86:89]
	v_mfma_f32_16x16x32_bf16 v[70:73], v[168:171], v[208:211], v[70:73]
	v_mfma_f32_16x16x32_bf16 v[70:73], v[164:167], v[204:207], v[70:73]
	v_mfma_f32_16x16x32_bf16 v[66:69], v[172:175], v[204:207], v[66:69]
	v_mfma_f32_16x16x32_bf16 v[66:69], v[176:179], v[208:211], v[66:69]
	v_mfma_f32_16x16x32_bf16 v[82:85], v[176:179], v[200:203], v[82:85]
	v_mfma_f32_16x16x32_bf16 v[82:85], v[172:175], v[196:199], v[82:85]
	v_mfma_f32_16x16x32_bf16 v[98:101], v[172:175], v[188:191], v[98:101]
	v_mfma_f32_16x16x32_bf16 v[98:101], v[176:179], v[192:195], v[98:101]
	v_mfma_f32_16x16x32_bf16 v[114:117], v[176:179], v[184:187], v[114:117]
	s_setprio 2
	s_barrier
	v_mfma_f32_16x16x32_bf16 v[114:117], v[172:175], v[180:183], v[114:117]
	s_setprio 0
	ds_read_b128 v[252:255], v147 offset:16384
	ds_read_b128 v[184:187], v147 offset:17408
	ds_read_b128 v[188:191], v147 offset:18432
	ds_read_b128 v[192:195], v147 offset:19456
	ds_read_b128 v[196:199], v147 offset:20480
	ds_read_b128 v[200:203], v147 offset:21504
	ds_read_b128 v[204:207], v147 offset:22528
	ds_read_b128 v[208:211], v147 offset:23552
	s_mov_b32 m0, s35
	s_nop 0
	global_load_lds_dwordx4 v140, s[46:47]
	s_add_u32 s70, s46, 0x100000
	s_mov_b32 m0, s50
	s_nop 0
	global_load_lds_dwordx4 v142, s[46:47]
	s_addc_u32 s71, s47, 0
	s_mov_b32 m0, s51
	s_nop 0
	global_load_lds_dwordx4 v140, s[70:71]
	s_nop 0
	s_mov_b32 m0, s54
	s_nop 0
	global_load_lds_dwordx4 v142, s[70:71]
	s_nop 0
	s_mov_b32 m0, s3
	s_nop 0
	global_load_lds_dwordx4 v1, s[48:49]
	s_nop 0
	s_mov_b32 m0, s55
	s_nop 0
	global_load_lds_dwordx4 v141, s[48:49]
	s_waitcnt vmcnt(8)
	s_waitcnt lgkmcnt(0)
	s_barrier
	s_setprio 1
	s_waitcnt lgkmcnt(7)
	v_mfma_f32_16x16x32_bf16 v[62:65], v[134:137], v[252:255], v[62:65]
	v_mfma_f32_16x16x32_bf16 v[62:65], v[152:155], v[184:187], v[62:65]
	s_waitcnt lgkmcnt(5)
	v_mfma_f32_16x16x32_bf16 v[46:49], v[152:155], v[192:195], v[46:49]
	v_mfma_f32_16x16x32_bf16 v[46:49], v[134:137], v[188:191], v[46:49]
	s_waitcnt lgkmcnt(3)
	v_mfma_f32_16x16x32_bf16 v[30:33], v[134:137], v[196:199], v[30:33]
	v_mfma_f32_16x16x32_bf16 v[30:33], v[152:155], v[200:203], v[30:33]
	s_waitcnt lgkmcnt(1)
	v_mfma_f32_16x16x32_bf16 v[14:17], v[152:155], v[208:211], v[14:17]
	v_mfma_f32_16x16x32_bf16 v[14:17], v[134:137], v[204:207], v[14:17]
	v_mfma_f32_16x16x32_bf16 v[10:13], v[156:159], v[204:207], v[10:13]
	v_mfma_f32_16x16x32_bf16 v[10:13], v[160:163], v[208:211], v[10:13]
	v_mfma_f32_16x16x32_bf16 v[26:29], v[160:163], v[200:203], v[26:29]
	v_mfma_f32_16x16x32_bf16 v[26:29], v[156:159], v[196:199], v[26:29]
	v_mfma_f32_16x16x32_bf16 v[42:45], v[156:159], v[188:191], v[42:45]
	v_mfma_f32_16x16x32_bf16 v[42:45], v[160:163], v[192:195], v[42:45]
	s_waitcnt lgkmcnt(0)
	v_mfma_f32_16x16x32_bf16 v[58:61], v[160:163], v[184:187], v[58:61]
	v_mfma_f32_16x16x32_bf16 v[58:61], v[156:159], v[252:255], v[58:61]
	s_setprio 0
	s_setprio 1
	v_mfma_f32_16x16x32_bf16 v[54:57], v[164:167], v[252:255], v[54:57]
	v_mfma_f32_16x16x32_bf16 v[54:57], v[168:171], v[184:187], v[54:57]
	v_mfma_f32_16x16x32_bf16 v[38:41], v[168:171], v[192:195], v[38:41]
	v_mfma_f32_16x16x32_bf16 v[38:41], v[164:167], v[188:191], v[38:41]
	v_mfma_f32_16x16x32_bf16 v[22:25], v[164:167], v[196:199], v[22:25]
	v_mfma_f32_16x16x32_bf16 v[22:25], v[168:171], v[200:203], v[22:25]
	v_mfma_f32_16x16x32_bf16 v[6:9], v[168:171], v[208:211], v[6:9]
	v_mfma_f32_16x16x32_bf16 v[6:9], v[164:167], v[204:207], v[6:9]
	v_mfma_f32_16x16x32_bf16 v[2:5], v[172:175], v[204:207], v[2:5]
	v_mfma_f32_16x16x32_bf16 v[2:5], v[176:179], v[208:211], v[2:5]
	v_mfma_f32_16x16x32_bf16 v[18:21], v[176:179], v[200:203], v[18:21]
	v_mfma_f32_16x16x32_bf16 v[18:21], v[172:175], v[196:199], v[18:21]
	v_mfma_f32_16x16x32_bf16 v[34:37], v[172:175], v[188:191], v[34:37]
	v_mfma_f32_16x16x32_bf16 v[34:37], v[176:179], v[192:195], v[34:37]
	v_mfma_f32_16x16x32_bf16 v[50:53], v[176:179], v[184:187], v[50:53]
	s_setprio 2
	s_barrier
; #define PG8_STAGE(bufoff, gbase, voff) do { _Pragma("unroll") for (int _i = 0; _i < 2; ++_i) \
;         asm volatile("s_mov_b32 m0, %2\n\ts_nop 0\n\tglobal_load_lds_dwordx4 %0, %1" :: "v"((voff)[_i]), "s"((const char*)(gbase)), "s"(ldsbase + (unsigned)(bufoff) + ldsw + (unsigned)_i * 8192u) : "memory", "m0"); } while (0)
; #define PG8_LDA(dst, b, h) do { _Pragma("unroll") for (int m = 0; m < 4; ++m) _Pragma("unroll") for (int k = 0; k < 2; ++k) dst[m][k] = *(const PG8_LAS bf16x8*)(lds + PG8_SA(b, h) + aoff + m * 2048 + k * 1024); } while (0)
; #define PG8_LDB(dst, b, h) do { _Pragma("unroll") for (int n = 0; n < 2; ++n) _Pragma("unroll") for (int k = 0; k < 2; ++k) dst[n][k] = *(const PG8_LAS bf16x8*)(lds + PG8_SB(b, h) + boff + n * 2048 + k * 1024); } while (0)
; #define PG8_MMA(ai, bj, At, Bt) do { __builtin_amdgcn_s_setprio(1); _Pragma("unroll") for (int m = 0; m < 4; ++m) _Pragma("unroll") for (int n = 0; n < 2; ++n) _Pragma("unroll") for (int k = 0; k < 2; ++k) \
;         acc[ai][bj][m][n] = __builtin_amdgcn_mfma_f32_16x16x32_bf16(Bt[n][k], At[m][k], acc[ai][bj][m][n], 0, 0, 0); __builtin_amdgcn_s_setprio(0); } while (0)
; template <class Epi, class Sched, bool ALIGN_EPI = false, bool SP2 = false>
; __device__ __forceinline__ void gemm_phase(PG8_LAS unsigned char* lds, const Gemm g, const Sched& S, const Epi& E) {
;     ...
;             PG8_LDB(B0, 0, 0); PG8_LDB(B1, 0, 1); PG8_SCHED; PG8_LDA(At, 0, 0); PG8_STAGE(PG8_SA(1, 1), a1 + hstep, voffA);
;             PG8_WAIT_V(8); PG8_WAIT_L(0); PG8_BAR; PG8_MMA(0, 0, At, B0); PG8_MMA(0, 1, At, B1); PG8_BAR; PG8_SCHED;
;             PG8_LDA(At, 0, 1); PG8_STAGE(PG8_SB(0, 0), b2, voffB); PG8_STAGE(PG8_SB(0, 1), b2 + hstep, voffB); PG8_STAGE(PG8_SA(0, 0), a2, voffA);
;             PG8_WAIT_V(8); PG8_WAIT_L(0); PG8_BAR; PG8_MMA(1, 0, At, B0); PG8_MMA(1, 1, At, B1); PG8_BAR; PG8_SCHED;
;             PG8_LDB(B0, 1, 0); PG8_LDB(B1, 1, 1); PG8_SCHED; PG8_LDA(At, 1, 0); PG8_STAGE(PG8_SA(0, 1), a2 + hstep, voffA);
;             PG8_WAIT_V(8); PG8_WAIT_L(0); PG8_BAR; PG8_MMA(0, 0, At, B0); PG8_MMA(0, 1, At, B1); PG8_BAR; PG8_SCHED;
;             PG8_LDA(At, 1, 1); PG8_STAGE(PG8_SB(1, 0), b3, voffB); PG8_STAGE(PG8_SB(1, 1), b3 + hstep, voffB); PG8_STAGE(PG8_SA(1, 0), a3, voffA);
;             PG8_WAIT_V(8); PG8_WAIT_L(0); PG8_BAR; PG8_MMA(1, 0, At, B0); PG8_MMA(1, 1, At, B1); PG8_BAR; PG8_SCHED;
	v_mfma_f32_16x16x32_bf16 v[50:53], v[172:175], v[252:255], v[50:53]
	s_setprio 0
	ds_read_b128 v[134:137], v148
	ds_read_b128 v[152:155], v148 offset:1024
	ds_read_b128 v[156:159], v148 offset:2048
	ds_read_b128 v[160:163], v148 offset:3072
	ds_read_b128 v[164:167], v149
	ds_read_b128 v[168:171], v149 offset:1024
	ds_read_b128 v[248:251], v149 offset:2048
	ds_read_b128 v[176:179], v149 offset:3072
	ds_read_b128 v[180:183], v147 offset:32768
	ds_read_b128 v[184:187], v147 offset:33792
	ds_read_b128 v[188:191], v147 offset:34816
	ds_read_b128 v[192:195], v147 offset:35840
	ds_read_b128 v[196:199], v147 offset:36864
	ds_read_b128 v[200:203], v147 offset:37888
	ds_read_b128 v[204:207], v147 offset:38912
	ds_read_b128 v[208:211], v147 offset:39936
	s_add_u32 s48, s48, 0x100000
	s_addc_u32 s49, s49, 0
	s_mov_b32 m0, s56
	s_nop 0
	global_load_lds_dwordx4 v1, s[48:49]
	s_nop 0
	s_mov_b32 m0, s57
	s_nop 0
	global_load_lds_dwordx4 v141, s[48:49]
	s_waitcnt vmcnt(8)
	s_waitcnt lgkmcnt(0)
	s_barrier
	s_setprio 1
	s_waitcnt lgkmcnt(7)
	v_mfma_f32_16x16x32_bf16 v[126:129], v[134:137], v[180:183], v[126:129]
	v_mfma_f32_16x16x32_bf16 v[126:129], v[152:155], v[184:187], v[126:129]
	s_waitcnt lgkmcnt(5)
	v_mfma_f32_16x16x32_bf16 v[110:113], v[152:155], v[192:195], v[110:113]
	v_mfma_f32_16x16x32_bf16 v[110:113], v[134:137], v[188:191], v[110:113]
	s_waitcnt lgkmcnt(3)
	v_mfma_f32_16x16x32_bf16 v[94:97], v[134:137], v[196:199], v[94:97]
	v_mfma_f32_16x16x32_bf16 v[94:97], v[152:155], v[200:203], v[94:97]
	s_waitcnt lgkmcnt(1)
	v_mfma_f32_16x16x32_bf16 v[78:81], v[152:155], v[208:211], v[78:81]
	v_mfma_f32_16x16x32_bf16 v[78:81], v[134:137], v[204:207], v[78:81]
	v_mfma_f32_16x16x32_bf16 v[74:77], v[156:159], v[204:207], v[74:77]
	v_mfma_f32_16x16x32_bf16 v[74:77], v[160:163], v[208:211], v[74:77]
	v_mfma_f32_16x16x32_bf16 v[90:93], v[160:163], v[200:203], v[90:93]
	v_mfma_f32_16x16x32_bf16 v[90:93], v[156:159], v[196:199], v[90:93]
	v_mfma_f32_16x16x32_bf16 v[106:109], v[156:159], v[188:191], v[106:109]
	v_mfma_f32_16x16x32_bf16 v[106:109], v[160:163], v[192:195], v[106:109]
	s_waitcnt lgkmcnt(0)
	v_mfma_f32_16x16x32_bf16 v[122:125], v[160:163], v[184:187], v[122:125]
	v_mfma_f32_16x16x32_bf16 v[122:125], v[156:159], v[180:183], v[122:125]
	s_setprio 0
	s_setprio 1
	v_mfma_f32_16x16x32_bf16 v[118:121], v[164:167], v[180:183], v[118:121]
	v_mfma_f32_16x16x32_bf16 v[118:121], v[168:171], v[184:187], v[118:121]
	v_mfma_f32_16x16x32_bf16 v[102:105], v[168:171], v[192:195], v[102:105]
	v_mfma_f32_16x16x32_bf16 v[102:105], v[164:167], v[188:191], v[102:105]
	v_mfma_f32_16x16x32_bf16 v[86:89], v[164:167], v[196:199], v[86:89]
	v_mfma_f32_16x16x32_bf16 v[86:89], v[168:171], v[200:203], v[86:89]
	v_mfma_f32_16x16x32_bf16 v[70:73], v[168:171], v[208:211], v[70:73]
	v_mfma_f32_16x16x32_bf16 v[70:73], v[164:167], v[204:207], v[70:73]
	v_mfma_f32_16x16x32_bf16 v[66:69], v[248:251], v[204:207], v[66:69]
	v_mfma_f32_16x16x32_bf16 v[66:69], v[176:179], v[208:211], v[66:69]
	v_mfma_f32_16x16x32_bf16 v[82:85], v[176:179], v[200:203], v[82:85]
	v_mfma_f32_16x16x32_bf16 v[82:85], v[248:251], v[196:199], v[82:85]
	v_mfma_f32_16x16x32_bf16 v[98:101], v[248:251], v[188:191], v[98:101]
	v_mfma_f32_16x16x32_bf16 v[98:101], v[176:179], v[192:195], v[98:101]
	v_mfma_f32_16x16x32_bf16 v[114:117], v[176:179], v[184:187], v[114:117]
	s_setprio 2
	s_barrier
; #define PG8_STAGE(bufoff, gbase, voff) do { _Pragma("unroll") for (int _i = 0; _i < 2; ++_i) \
;         asm volatile("s_mov_b32 m0, %2\n\ts_nop 0\n\tglobal_load_lds_dwordx4 %0, %1" :: "v"((voff)[_i]), "s"((const char*)(gbase)), "s"(ldsbase + (unsigned)(bufoff) + ldsw + (unsigned)_i * 8192u) : "memory", "m0"); } while (0)
; #define PG8_LDA(dst, b, h) do { _Pragma("unroll") for (int m = 0; m < 4; ++m) _Pragma("unroll") for (int k = 0; k < 2; ++k) dst[m][k] = *(const PG8_LAS bf16x8*)(lds + PG8_SA(b, h) + aoff + m * 2048 + k * 1024); } while (0)
; #define PG8_LDB(dst, b, h) do { _Pragma("unroll") for (int n = 0; n < 2; ++n) _Pragma("unroll") for (int k = 0; k < 2; ++k) dst[n][k] = *(const PG8_LAS bf16x8*)(lds + PG8_SB(b, h) + boff + n * 2048 + k * 1024); } while (0)
; #define PG8_MMA(ai, bj, At, Bt) do { __builtin_amdgcn_s_setprio(1); _Pragma("unroll") for (int m = 0; m < 4; ++m) _Pragma("unroll") for (int n = 0; n < 2; ++n) _Pragma("unroll") for (int k = 0; k < 2; ++k) \
;         acc[ai][bj][m][n] = __builtin_amdgcn_mfma_f32_16x16x32_bf16(Bt[n][k], At[m][k], acc[ai][bj][m][n], 0, 0, 0); __builtin_amdgcn_s_setprio(0); } while (0)
; template <class Epi, class Sched, bool ALIGN_EPI = false, bool SP2 = false>
; __device__ __forceinline__ void gemm_phase(PG8_LAS unsigned char* lds, const Gemm g, const Sched& S, const Epi& E) {
;     ...
;             PG8_LDB(B0, 0, 0); PG8_LDB(B1, 0, 1); PG8_SCHED; PG8_LDA(At, 0, 0); PG8_STAGE(PG8_SA(1, 1), a1 + hstep, voffA);
;             PG8_WAIT_V(8); PG8_WAIT_L(0); PG8_BAR; PG8_MMA(0, 0, At, B0); PG8_MMA(0, 1, At, B1); PG8_BAR; PG8_SCHED;
;             PG8_LDA(At, 0, 1); PG8_STAGE(PG8_SB(0, 0), b2, voffB); PG8_STAGE(PG8_SB(0, 1), b2 + hstep, voffB); PG8_STAGE(PG8_SA(0, 0), a2, voffA);
;             PG8_WAIT_V(8); PG8_WAIT_L(0); PG8_BAR; PG8_MMA(1, 0, At, B0); PG8_MMA(1, 1, At, B1); PG8_BAR; PG8_SCHED;
;             PG8_LDB(B0, 1, 0); PG8_LDB(B1, 1, 1); PG8_SCHED; PG8_LDA(At, 1, 0); PG8_STAGE(PG8_SA(0, 1), a2 + hstep, voffA);
;             PG8_WAIT_V(8); PG8_WAIT_L(0); PG8_BAR; PG8_MMA(0, 0, At, B0); PG8_MMA(0, 1, At, B1); PG8_BAR; PG8_SCHED;
;             PG8_LDA(At, 1, 1); PG8_STAGE(PG8_SB(1, 0), b3, voffB); PG8_STAGE(PG8_SB(1, 1), b3 + hstep, voffB); PG8_STAGE(PG8_SA(1, 0), a3, voffA);
;             PG8_WAIT_V(8); PG8_WAIT_L(0); PG8_BAR; PG8_MMA(1, 0, At, B0); PG8_MMA(1, 1, At, B1); PG8_BAR; PG8_SCHED;
	v_mfma_f32_16x16x32_bf16 v[114:117], v[248:251], v[180:183], v[114:117]
	s_setprio 0
	ds_read_b128 v[252:255], v147 offset:49152
	ds_read_b128 v[184:187], v147 offset:50176
	ds_read_b128 v[188:191], v147 offset:51200
	ds_read_b128 v[192:195], v147 offset:52224
	ds_read_b128 v[196:199], v147 offset:53248
	ds_read_b128 v[200:203], v147 offset:54272
	ds_read_b128 v[204:207], v147 offset:55296
	ds_read_b128 v[208:211], v147 offset:56320
	s_add_u32 s48, s46, 0x80
	s_addc_u32 s49, s47, 0
	s_mov_b32 m0, s61
	s_nop 0
	global_load_lds_dwordx4 v140, s[48:49]
	s_add_u32 s46, s46, 0x100080
	s_mov_b32 m0, s62
	s_nop 0
	global_load_lds_dwordx4 v142, s[48:49]
	s_addc_u32 s47, s47, 0
	s_mov_b32 m0, s65
	s_nop 0
	global_load_lds_dwordx4 v140, s[46:47]
	s_nop 0
	s_mov_b32 m0, s66
	s_nop 0
	global_load_lds_dwordx4 v142, s[46:47]
	s_nop 0
	s_mov_b32 m0, s63
	s_nop 0
	global_load_lds_dwordx4 v1, s[44:45]
	s_nop 0
	s_mov_b32 m0, s64
	s_nop 0
	global_load_lds_dwordx4 v141, s[44:45]
	s_waitcnt vmcnt(8)
	s_waitcnt lgkmcnt(0)
	s_barrier
	s_setprio 1
	s_waitcnt lgkmcnt(7)
	v_mfma_f32_16x16x32_bf16 v[62:65], v[134:137], v[252:255], v[62:65]
	v_mfma_f32_16x16x32_bf16 v[62:65], v[152:155], v[184:187], v[62:65]
	s_waitcnt lgkmcnt(5)
	v_mfma_f32_16x16x32_bf16 v[46:49], v[152:155], v[192:195], v[46:49]
	v_mfma_f32_16x16x32_bf16 v[46:49], v[134:137], v[188:191], v[46:49]
	s_waitcnt lgkmcnt(3)
	v_mfma_f32_16x16x32_bf16 v[30:33], v[134:137], v[196:199], v[30:33]
	v_mfma_f32_16x16x32_bf16 v[30:33], v[152:155], v[200:203], v[30:33]
	s_waitcnt lgkmcnt(1)
	v_mfma_f32_16x16x32_bf16 v[14:17], v[152:155], v[208:211], v[14:17]
	v_mfma_f32_16x16x32_bf16 v[14:17], v[134:137], v[204:207], v[14:17]
	v_mfma_f32_16x16x32_bf16 v[10:13], v[156:159], v[204:207], v[10:13]
	v_mfma_f32_16x16x32_bf16 v[10:13], v[160:163], v[208:211], v[10:13]
	v_mfma_f32_16x16x32_bf16 v[26:29], v[160:163], v[200:203], v[26:29]
	v_mfma_f32_16x16x32_bf16 v[26:29], v[156:159], v[196:199], v[26:29]
	v_mfma_f32_16x16x32_bf16 v[42:45], v[156:159], v[188:191], v[42:45]
	v_mfma_f32_16x16x32_bf16 v[42:45], v[160:163], v[192:195], v[42:45]
	s_waitcnt lgkmcnt(0)
	v_mfma_f32_16x16x32_bf16 v[58:61], v[160:163], v[184:187], v[58:61]
	v_mfma_f32_16x16x32_bf16 v[58:61], v[156:159], v[252:255], v[58:61]
	s_setprio 0
	s_setprio 1
	v_mfma_f32_16x16x32_bf16 v[54:57], v[164:167], v[252:255], v[54:57]
	v_mfma_f32_16x16x32_bf16 v[54:57], v[168:171], v[184:187], v[54:57]
	v_mfma_f32_16x16x32_bf16 v[38:41], v[168:171], v[192:195], v[38:41]
	v_mfma_f32_16x16x32_bf16 v[38:41], v[164:167], v[188:191], v[38:41]
	v_mfma_f32_16x16x32_bf16 v[22:25], v[164:167], v[196:199], v[22:25]
	v_mfma_f32_16x16x32_bf16 v[22:25], v[168:171], v[200:203], v[22:25]
	v_mfma_f32_16x16x32_bf16 v[6:9], v[168:171], v[208:211], v[6:9]
	v_mfma_f32_16x16x32_bf16 v[6:9], v[164:167], v[204:207], v[6:9]
	v_mfma_f32_16x16x32_bf16 v[2:5], v[248:251], v[204:207], v[2:5]
	v_mfma_f32_16x16x32_bf16 v[2:5], v[176:179], v[208:211], v[2:5]
	v_mfma_f32_16x16x32_bf16 v[18:21], v[176:179], v[200:203], v[18:21]
	v_mfma_f32_16x16x32_bf16 v[18:21], v[248:251], v[196:199], v[18:21]
	v_mfma_f32_16x16x32_bf16 v[34:37], v[248:251], v[188:191], v[34:37]
	v_mfma_f32_16x16x32_bf16 v[34:37], v[176:179], v[192:195], v[34:37]
	v_mfma_f32_16x16x32_bf16 v[50:53], v[176:179], v[184:187], v[50:53]
	s_setprio 2
	s_barrier
	v_mfma_f32_16x16x32_bf16 v[50:53], v[248:251], v[252:255], v[50:53]
	s_setprio 0
	s_add_i32 s69, s69, 2
	s_add_u32 s53, s53, 0x100
	s_addc_u32 s58, s58, 0
	s_add_u32 s59, s59, 0x100
	s_addc_u32 s68, s68, 0
	s_add_u32 s42, s42, 0x100
	s_addc_u32 s43, s43, 0
	s_cmp_gt_u32 s69, 61
	s_cbranch_scc0 .LBB0_698
	s_and_b64 vcc, exec, s[14:15]
	s_cbranch_vccz .LBB0_701
	s_barrier

; #define PG8_STAGE(bufoff, gbase, voff) do { _Pragma("unroll") for (int _i = 0; _i < 2; ++_i) \
;         asm volatile("s_mov_b32 m0, %2\n\ts_nop 0\n\tglobal_load_lds_dwordx4 %0, %1" :: "v"((voff)[_i]), "s"((const char*)(gbase)), "s"(ldsbase + (unsigned)(bufoff) + ldsw + (unsigned)_i * 8192u) : "memory", "m0"); } while (0)
; #define PG8_LDA(dst, b, h) do { _Pragma("unroll") for (int m = 0; m < 4; ++m) _Pragma("unroll") for (int k = 0; k < 2; ++k) dst[m][k] = *(const PG8_LAS bf16x8*)(lds + PG8_SA(b, h) + aoff + m * 2048 + k * 1024); } while (0)
; #define PG8_LDB(dst, b, h) do { _Pragma("unroll") for (int n = 0; n < 2; ++n) _Pragma("unroll") for (int k = 0; k < 2; ++k) dst[n][k] = *(const PG8_LAS bf16x8*)(lds + PG8_SB(b, h) + boff + n * 2048 + k * 1024); } while (0)
; #define PG8_WAIT_V(n) asm volatile("s_waitcnt vmcnt(" #n ")" ::: "memory")
; #define PG8_WAIT_L(n) asm volatile("s_waitcnt lgkmcnt(" #n ")" ::: "memory")
; #define PG8_BAR __builtin_amdgcn_s_barrier()
; #define PG8_SCHED __builtin_amdgcn_sched_barrier(0)
; template <class Epi, class Sched, bool ALIGN_EPI = false, bool SP2 = false>
; __device__ __forceinline__ void gemm_phase(PG8_LAS unsigned char* lds, const Gemm g, const Sched& S, const Epi& E) {
;     ...
;             const char* a2 = last ? nA : cA + (size_t)(t + 2) * kstep; const char* b2 = last ? nB : cB + (size_t)(t + 2) * kstep;
;     ...
;             PG8_LDB(B0, 0, 0); PG8_LDB(B1, 0, 1); PG8_SCHED; PG8_LDA(At, 0, 0); PG8_STAGE(PG8_SA(1, 1), a1 + hstep, voffA);
;             PG8_WAIT_V(8); PG8_WAIT_L(0); PG8_BAR; PG8_MMA(0, 0, At, B0); PG8_MMA(0, 1, At, B1); PG8_BAR; PG8_SCHED;
;             PG8_LDA(At, 0, 1); PG8_STAGE(PG8_SB(0, 0), b2, voffB); PG8_STAGE(PG8_SB(0, 1), b2 + hstep, voffB); PG8_STAGE(PG8_SA(0, 0), a2, voffA);
;             PG8_WAIT_V(8); PG8_WAIT_L(0); PG8_BAR; PG8_MMA(1, 0, At, B0); PG8_MMA(1, 1, At, B1); PG8_BAR; PG8_SCHED;
;             PG8_LDB(B0, 1, 0); PG8_LDB(B1, 1, 1); PG8_SCHED; PG8_LDA(At, 1, 0); PG8_STAGE(PG8_SA(0, 1), a2 + hstep, voffA);
;             PG8_WAIT_V(8); PG8_WAIT_L(0); PG8_BAR; PG8_MMA(0, 0, At, B0); PG8_MMA(0, 1, At, B1); PG8_BAR; PG8_SCHED;
;             PG8_LDA(At, 1, 1); PG8_STAGE(PG8_SB(1, 0), b3, voffB); PG8_STAGE(PG8_SB(1, 1), b3 + hstep, voffB); PG8_STAGE(PG8_SA(1, 0), a3, voffA);
;             PG8_WAIT_V(8); PG8_WAIT_L(0); PG8_BAR; PG8_MMA(1, 0, At, B0); PG8_MMA(1, 1, At, B1); PG8_BAR; PG8_SCHED;
.LBB0_789:
	v_add_u32_e32 v164, 0x10000, v149
	v_add_u32_e32 v180, 0x14000, v149
	s_add_u32 s8, s40, 0x100
	s_waitcnt lgkmcnt(0)
	ds_read_b128 v[152:155], v164
	ds_read_b128 v[156:159], v164 offset:1024
	ds_read_b128 v[160:163], v164 offset:2048
	ds_read_b128 v[164:167], v164 offset:3072
	ds_read_b128 v[168:171], v180
	ds_read_b128 v[172:175], v180 offset:1024
	ds_read_b128 v[176:179], v180 offset:2048
	ds_read_b128 v[180:183], v180 offset:3072
	s_addc_u32 s9, s41, 0
	s_and_b64 s[38:39], s[38:39], exec
	s_cselect_b32 s46, s59, s8
	s_cselect_b32 s47, s17, s9
	s_cselect_b32 s39, s15, s75
	s_cselect_b32 s38, s71, s74
	s_add_u32 s42, s46, 0x80
	s_addc_u32 s43, s47, 0
	s_add_u32 s44, s38, 0x80
	s_addc_u32 s45, s39, 0
	ds_read_b128 v[184:187], v150
	ds_read_b128 v[188:191], v150 offset:1024
	ds_read_b128 v[192:195], v150 offset:2048
	ds_read_b128 v[196:199], v150 offset:3072
	ds_read_b128 v[200:203], v150 offset:4096
	ds_read_b128 v[204:207], v150 offset:5120
	ds_read_b128 v[208:211], v150 offset:6144
	ds_read_b128 v[212:215], v150 offset:7168
	s_add_u32 s40, s40, 0x100080
	s_addc_u32 s41, s41, 0
	s_mov_b32 m0, s64
	s_nop 0
	global_load_lds_dwordx4 v139, s[40:41]
	s_nop 0
	s_mov_b32 m0, s65
	s_nop 0
	global_load_lds_dwordx4 v141, s[40:41]
	s_waitcnt vmcnt(8)
	s_waitcnt lgkmcnt(0)
	s_barrier
	s_setprio 1
	s_waitcnt lgkmcnt(7)
	v_mfma_f32_16x16x32_bf16 v[126:129], v[152:155], v[184:187], v[126:129]
	v_mfma_f32_16x16x32_bf16 v[126:129], v[156:159], v[188:191], v[126:129]
	s_waitcnt lgkmcnt(5)
	v_mfma_f32_16x16x32_bf16 v[110:113], v[156:159], v[196:199], v[110:113]
	v_mfma_f32_16x16x32_bf16 v[110:113], v[152:155], v[192:195], v[110:113]
	s_waitcnt lgkmcnt(3)
	v_mfma_f32_16x16x32_bf16 v[94:97], v[152:155], v[200:203], v[94:97]
	v_mfma_f32_16x16x32_bf16 v[94:97], v[156:159], v[204:207], v[94:97]
	s_waitcnt lgkmcnt(1)
	v_mfma_f32_16x16x32_bf16 v[78:81], v[156:159], v[212:215], v[78:81]
	v_mfma_f32_16x16x32_bf16 v[78:81], v[152:155], v[208:211], v[78:81]
	v_mfma_f32_16x16x32_bf16 v[74:77], v[160:163], v[208:211], v[74:77]
	v_mfma_f32_16x16x32_bf16 v[74:77], v[164:167], v[212:215], v[74:77]
	v_mfma_f32_16x16x32_bf16 v[90:93], v[164:167], v[204:207], v[90:93]
	v_mfma_f32_16x16x32_bf16 v[90:93], v[160:163], v[200:203], v[90:93]
	v_mfma_f32_16x16x32_bf16 v[106:109], v[160:163], v[192:195], v[106:109]
	v_mfma_f32_16x16x32_bf16 v[106:109], v[164:167], v[196:199], v[106:109]
	s_waitcnt lgkmcnt(0)
	v_mfma_f32_16x16x32_bf16 v[122:125], v[164:167], v[188:191], v[122:125]
	v_mfma_f32_16x16x32_bf16 v[122:125], v[160:163], v[184:187], v[122:125]
	s_setprio 0
	s_setprio 1
	v_mfma_f32_16x16x32_bf16 v[118:121], v[168:171], v[184:187], v[118:121]
	v_mfma_f32_16x16x32_bf16 v[118:121], v[172:175], v[188:191], v[118:121]
	v_mfma_f32_16x16x32_bf16 v[102:105], v[172:175], v[196:199], v[102:105]
	v_mfma_f32_16x16x32_bf16 v[102:105], v[168:171], v[192:195], v[102:105]
	v_mfma_f32_16x16x32_bf16 v[86:89], v[168:171], v[200:203], v[86:89]
	v_mfma_f32_16x16x32_bf16 v[86:89], v[172:175], v[204:207], v[86:89]
	v_mfma_f32_16x16x32_bf16 v[70:73], v[172:175], v[212:215], v[70:73]
	v_mfma_f32_16x16x32_bf16 v[70:73], v[168:171], v[208:211], v[70:73]
	v_mfma_f32_16x16x32_bf16 v[66:69], v[176:179], v[208:211], v[66:69]
	v_mfma_f32_16x16x32_bf16 v[66:69], v[180:183], v[212:215], v[66:69]
	v_mfma_f32_16x16x32_bf16 v[82:85], v[180:183], v[204:207], v[82:85]
	v_mfma_f32_16x16x32_bf16 v[82:85], v[176:179], v[200:203], v[82:85]
	v_mfma_f32_16x16x32_bf16 v[98:101], v[176:179], v[192:195], v[98:101]
	v_mfma_f32_16x16x32_bf16 v[98:101], v[180:183], v[196:199], v[98:101]
	v_mfma_f32_16x16x32_bf16 v[114:117], v[180:183], v[188:191], v[114:117]
	s_setprio 2
	s_barrier
	v_mfma_f32_16x16x32_bf16 v[114:117], v[176:179], v[184:187], v[114:117]
	s_setprio 0
	ds_read_b128 v[252:255], v150 offset:16384
	ds_read_b128 v[188:191], v150 offset:17408
	ds_read_b128 v[192:195], v150 offset:18432
	ds_read_b128 v[196:199], v150 offset:19456
	ds_read_b128 v[200:203], v150 offset:20480
	ds_read_b128 v[204:207], v150 offset:21504
	ds_read_b128 v[208:211], v150 offset:22528
	ds_read_b128 v[212:215], v150 offset:23552
	s_mov_b32 m0, s49
	s_nop 0
	global_load_lds_dwordx4 v140, s[38:39]
	s_add_u32 s40, s38, 0x100000
	s_mov_b32 m0, s50
	s_nop 0
	global_load_lds_dwordx4 v142, s[38:39]
	s_addc_u32 s41, s39, 0
	s_mov_b32 m0, s51
	s_nop 0
	global_load_lds_dwordx4 v140, s[40:41]
	s_nop 0
	s_mov_b32 m0, s52
	s_nop 0
	global_load_lds_dwordx4 v142, s[40:41]
	s_nop 0
	s_mov_b32 m0, s37
	s_nop 0
	global_load_lds_dwordx4 v139, s[46:47]
	s_nop 0
	s_mov_b32 m0, s53
	s_nop 0
	global_load_lds_dwordx4 v141, s[46:47]
	s_waitcnt vmcnt(8)
	s_waitcnt lgkmcnt(0)
	s_barrier
; #define PG8_STAGE(bufoff, gbase, voff) do { _Pragma("unroll") for (int _i = 0; _i < 2; ++_i) \
;         asm volatile("s_mov_b32 m0, %2\n\ts_nop 0\n\tglobal_load_lds_dwordx4 %0, %1" :: "v"((voff)[_i]), "s"((const char*)(gbase)), "s"(ldsbase + (unsigned)(bufoff) + ldsw + (unsigned)_i * 8192u) : "memory", "m0"); } while (0)
; #define PG8_LDA(dst, b, h) do { _Pragma("unroll") for (int m = 0; m < 4; ++m) _Pragma("unroll") for (int k = 0; k < 2; ++k) dst[m][k] = *(const PG8_LAS bf16x8*)(lds + PG8_SA(b, h) + aoff + m * 2048 + k * 1024); } while (0)
; #define PG8_LDB(dst, b, h) do { _Pragma("unroll") for (int n = 0; n < 2; ++n) _Pragma("unroll") for (int k = 0; k < 2; ++k) dst[n][k] = *(const PG8_LAS bf16x8*)(lds + PG8_SB(b, h) + boff + n * 2048 + k * 1024); } while (0)
; #define PG8_MMA(ai, bj, At, Bt) do { __builtin_amdgcn_s_setprio(1); _Pragma("unroll") for (int m = 0; m < 4; ++m) _Pragma("unroll") for (int n = 0; n < 2; ++n) _Pragma("unroll") for (int k = 0; k < 2; ++k) \
;         acc[ai][bj][m][n] = __builtin_amdgcn_mfma_f32_16x16x32_bf16(Bt[n][k], At[m][k], acc[ai][bj][m][n], 0, 0, 0); __builtin_amdgcn_s_setprio(0); } while (0)
; template <class Epi, class Sched, bool ALIGN_EPI = false, bool SP2 = false>
; __device__ __forceinline__ void gemm_phase(PG8_LAS unsigned char* lds, const Gemm g, const Sched& S, const Epi& E) {
;     ...
;             PG8_LDB(B0, 0, 0); PG8_LDB(B1, 0, 1); PG8_SCHED; PG8_LDA(At, 0, 0); PG8_STAGE(PG8_SA(1, 1), a1 + hstep, voffA);
;             PG8_WAIT_V(8); PG8_WAIT_L(0); PG8_BAR; PG8_MMA(0, 0, At, B0); PG8_MMA(0, 1, At, B1); PG8_BAR; PG8_SCHED;
;             PG8_LDA(At, 0, 1); PG8_STAGE(PG8_SB(0, 0), b2, voffB); PG8_STAGE(PG8_SB(0, 1), b2 + hstep, voffB); PG8_STAGE(PG8_SA(0, 0), a2, voffA);
;             PG8_WAIT_V(8); PG8_WAIT_L(0); PG8_BAR; PG8_MMA(1, 0, At, B0); PG8_MMA(1, 1, At, B1); PG8_BAR; PG8_SCHED;
;             PG8_LDB(B0, 1, 0); PG8_LDB(B1, 1, 1); PG8_SCHED; PG8_LDA(At, 1, 0); PG8_STAGE(PG8_SA(0, 1), a2 + hstep, voffA);
;             PG8_WAIT_V(8); PG8_WAIT_L(0); PG8_BAR; PG8_MMA(0, 0, At, B0); PG8_MMA(0, 1, At, B1); PG8_BAR; PG8_SCHED;
;             PG8_LDA(At, 1, 1); PG8_STAGE(PG8_SB(1, 0), b3, voffB); PG8_STAGE(PG8_SB(1, 1), b3 + hstep, voffB); PG8_STAGE(PG8_SA(1, 0), a3, voffA);
;             PG8_WAIT_V(8); PG8_WAIT_L(0); PG8_BAR; PG8_MMA(1, 0, At, B0); PG8_MMA(1, 1, At, B1); PG8_BAR; PG8_SCHED;
	s_setprio 1
	s_waitcnt lgkmcnt(7)
	v_mfma_f32_16x16x32_bf16 v[62:65], v[152:155], v[252:255], v[62:65]
	v_mfma_f32_16x16x32_bf16 v[62:65], v[156:159], v[188:191], v[62:65]
	s_waitcnt lgkmcnt(5)
	v_mfma_f32_16x16x32_bf16 v[46:49], v[156:159], v[196:199], v[46:49]
	v_mfma_f32_16x16x32_bf16 v[46:49], v[152:155], v[192:195], v[46:49]
	s_waitcnt lgkmcnt(3)
	v_mfma_f32_16x16x32_bf16 v[30:33], v[152:155], v[200:203], v[30:33]
	v_mfma_f32_16x16x32_bf16 v[30:33], v[156:159], v[204:207], v[30:33]
	s_waitcnt lgkmcnt(1)
	v_mfma_f32_16x16x32_bf16 v[14:17], v[156:159], v[212:215], v[14:17]
	v_mfma_f32_16x16x32_bf16 v[14:17], v[152:155], v[208:211], v[14:17]
	v_mfma_f32_16x16x32_bf16 v[10:13], v[160:163], v[208:211], v[10:13]
	v_mfma_f32_16x16x32_bf16 v[10:13], v[164:167], v[212:215], v[10:13]
	v_mfma_f32_16x16x32_bf16 v[26:29], v[164:167], v[204:207], v[26:29]
	v_mfma_f32_16x16x32_bf16 v[26:29], v[160:163], v[200:203], v[26:29]
	v_mfma_f32_16x16x32_bf16 v[42:45], v[160:163], v[192:195], v[42:45]
	v_mfma_f32_16x16x32_bf16 v[42:45], v[164:167], v[196:199], v[42:45]
	s_waitcnt lgkmcnt(0)
	v_mfma_f32_16x16x32_bf16 v[58:61], v[164:167], v[188:191], v[58:61]
	v_mfma_f32_16x16x32_bf16 v[58:61], v[160:163], v[252:255], v[58:61]
	s_setprio 0
	s_setprio 1
	v_mfma_f32_16x16x32_bf16 v[54:57], v[168:171], v[252:255], v[54:57]
	v_mfma_f32_16x16x32_bf16 v[54:57], v[172:175], v[188:191], v[54:57]
	v_mfma_f32_16x16x32_bf16 v[38:41], v[172:175], v[196:199], v[38:41]
	v_mfma_f32_16x16x32_bf16 v[38:41], v[168:171], v[192:195], v[38:41]
	v_mfma_f32_16x16x32_bf16 v[22:25], v[168:171], v[200:203], v[22:25]
	v_mfma_f32_16x16x32_bf16 v[22:25], v[172:175], v[204:207], v[22:25]
	v_mfma_f32_16x16x32_bf16 v[6:9], v[172:175], v[212:215], v[6:9]
	v_mfma_f32_16x16x32_bf16 v[6:9], v[168:171], v[208:211], v[6:9]
	v_mfma_f32_16x16x32_bf16 v[2:5], v[176:179], v[208:211], v[2:5]
	v_mfma_f32_16x16x32_bf16 v[2:5], v[180:183], v[212:215], v[2:5]
	v_mfma_f32_16x16x32_bf16 v[18:21], v[180:183], v[204:207], v[18:21]
	v_mfma_f32_16x16x32_bf16 v[18:21], v[176:179], v[200:203], v[18:21]
	v_mfma_f32_16x16x32_bf16 v[34:37], v[176:179], v[192:195], v[34:37]
	v_mfma_f32_16x16x32_bf16 v[34:37], v[180:183], v[196:199], v[34:37]
	v_mfma_f32_16x16x32_bf16 v[50:53], v[180:183], v[188:191], v[50:53]
	s_setprio 2
	s_barrier
	v_mfma_f32_16x16x32_bf16 v[50:53], v[176:179], v[252:255], v[50:53]
	s_setprio 0
	v_add_u32_e32 v164, 0x18000, v149
	v_add_u32_e32 v180, 0x1c000, v149
	ds_read_b128 v[152:155], v164
	ds_read_b128 v[156:159], v164 offset:1024
	ds_read_b128 v[160:163], v164 offset:2048
	ds_read_b128 v[164:167], v164 offset:3072
	ds_read_b128 v[168:171], v180
	ds_read_b128 v[172:175], v180 offset:1024
	ds_read_b128 v[248:251], v180 offset:2048
	ds_read_b128 v[180:183], v180 offset:3072
	ds_read_b128 v[184:187], v150 offset:32768
	ds_read_b128 v[188:191], v150 offset:33792
	ds_read_b128 v[192:195], v150 offset:34816
	ds_read_b128 v[196:199], v150 offset:35840
	ds_read_b128 v[200:203], v150 offset:36864
	ds_read_b128 v[204:207], v150 offset:37888
	ds_read_b128 v[208:211], v150 offset:38912
	ds_read_b128 v[212:215], v150 offset:39936
	s_add_u32 s40, s46, 0x100000
	s_addc_u32 s41, s47, 0
	s_mov_b32 m0, s54
	s_nop 0
	global_load_lds_dwordx4 v139, s[40:41]
	s_nop 0
	s_mov_b32 m0, s55
	s_nop 0
	global_load_lds_dwordx4 v141, s[40:41]
	s_waitcnt vmcnt(8)
	s_waitcnt lgkmcnt(0)
	s_barrier
	s_setprio 1
	s_waitcnt lgkmcnt(7)
	v_mfma_f32_16x16x32_bf16 v[126:129], v[152:155], v[184:187], v[126:129]
	v_mfma_f32_16x16x32_bf16 v[126:129], v[156:159], v[188:191], v[126:129]
	s_waitcnt lgkmcnt(5)
	v_mfma_f32_16x16x32_bf16 v[110:113], v[156:159], v[196:199], v[110:113]
	v_mfma_f32_16x16x32_bf16 v[110:113], v[152:155], v[192:195], v[110:113]
	s_waitcnt lgkmcnt(3)
	v_mfma_f32_16x16x32_bf16 v[94:97], v[152:155], v[200:203], v[94:97]
	v_mfma_f32_16x16x32_bf16 v[94:97], v[156:159], v[204:207], v[94:97]
	s_waitcnt lgkmcnt(1)
	v_mfma_f32_16x16x32_bf16 v[78:81], v[156:159], v[212:215], v[78:81]
	v_mfma_f32_16x16x32_bf16 v[78:81], v[152:155], v[208:211], v[78:81]
	v_mfma_f32_16x16x32_bf16 v[74:77], v[160:163], v[208:211], v[74:77]
	v_mfma_f32_16x16x32_bf16 v[74:77], v[164:167], v[212:215], v[74:77]
	v_mfma_f32_16x16x32_bf16 v[90:93], v[164:167], v[204:207], v[90:93]
	v_mfma_f32_16x16x32_bf16 v[90:93], v[160:163], v[200:203], v[90:93]
	v_mfma_f32_16x16x32_bf16 v[106:109], v[160:163], v[192:195], v[106:109]
	v_mfma_f32_16x16x32_bf16 v[106:109], v[164:167], v[196:199], v[106:109]
	s_waitcnt lgkmcnt(0)
	v_mfma_f32_16x16x32_bf16 v[122:125], v[164:167], v[188:191], v[122:125]
	v_mfma_f32_16x16x32_bf16 v[122:125], v[160:163], v[184:187], v[122:125]
	s_setprio 0
	s_setprio 1
	v_mfma_f32_16x16x32_bf16 v[118:121], v[168:171], v[184:187], v[118:121]
	v_mfma_f32_16x16x32_bf16 v[118:121], v[172:175], v[188:191], v[118:121]
	v_mfma_f32_16x16x32_bf16 v[102:105], v[172:175], v[196:199], v[102:105]
	v_mfma_f32_16x16x32_bf16 v[102:105], v[168:171], v[192:195], v[102:105]
	v_mfma_f32_16x16x32_bf16 v[86:89], v[168:171], v[200:203], v[86:89]
	v_mfma_f32_16x16x32_bf16 v[86:89], v[172:175], v[204:207], v[86:89]
	v_mfma_f32_16x16x32_bf16 v[70:73], v[172:175], v[212:215], v[70:73]
	v_mfma_f32_16x16x32_bf16 v[70:73], v[168:171], v[208:211], v[70:73]
	v_mfma_f32_16x16x32_bf16 v[66:69], v[248:251], v[208:211], v[66:69]
	v_mfma_f32_16x16x32_bf16 v[66:69], v[180:183], v[212:215], v[66:69]
	v_mfma_f32_16x16x32_bf16 v[82:85], v[180:183], v[204:207], v[82:85]
	v_mfma_f32_16x16x32_bf16 v[82:85], v[248:251], v[200:203], v[82:85]
	v_mfma_f32_16x16x32_bf16 v[98:101], v[248:251], v[192:195], v[98:101]
	v_mfma_f32_16x16x32_bf16 v[98:101], v[180:183], v[196:199], v[98:101]
	v_mfma_f32_16x16x32_bf16 v[114:117], v[180:183], v[188:191], v[114:117]
	s_setprio 2
	s_barrier
; #define PG8_STAGE(bufoff, gbase, voff) do { _Pragma("unroll") for (int _i = 0; _i < 2; ++_i) \
;         asm volatile("s_mov_b32 m0, %2\n\ts_nop 0\n\tglobal_load_lds_dwordx4 %0, %1" :: "v"((voff)[_i]), "s"((const char*)(gbase)), "s"(ldsbase + (unsigned)(bufoff) + ldsw + (unsigned)_i * 8192u) : "memory", "m0"); } while (0)
; #define PG8_LDA(dst, b, h) do { _Pragma("unroll") for (int m = 0; m < 4; ++m) _Pragma("unroll") for (int k = 0; k < 2; ++k) dst[m][k] = *(const PG8_LAS bf16x8*)(lds + PG8_SA(b, h) + aoff + m * 2048 + k * 1024); } while (0)
; #define PG8_LDB(dst, b, h) do { _Pragma("unroll") for (int n = 0; n < 2; ++n) _Pragma("unroll") for (int k = 0; k < 2; ++k) dst[n][k] = *(const PG8_LAS bf16x8*)(lds + PG8_SB(b, h) + boff + n * 2048 + k * 1024); } while (0)
; #define PG8_MMA(ai, bj, At, Bt) do { __builtin_amdgcn_s_setprio(1); _Pragma("unroll") for (int m = 0; m < 4; ++m) _Pragma("unroll") for (int n = 0; n < 2; ++n) _Pragma("unroll") for (int k = 0; k < 2; ++k) \
;         acc[ai][bj][m][n] = __builtin_amdgcn_mfma_f32_16x16x32_bf16(Bt[n][k], At[m][k], acc[ai][bj][m][n], 0, 0, 0); __builtin_amdgcn_s_setprio(0); } while (0)
; template <class Epi, class Sched, bool ALIGN_EPI = false, bool SP2 = false>
; __device__ __forceinline__ void gemm_phase(PG8_LAS unsigned char* lds, const Gemm g, const Sched& S, const Epi& E) {
;     ...
;             PG8_LDB(B0, 0, 0); PG8_LDB(B1, 0, 1); PG8_SCHED; PG8_LDA(At, 0, 0); PG8_STAGE(PG8_SA(1, 1), a1 + hstep, voffA);
;             PG8_WAIT_V(8); PG8_WAIT_L(0); PG8_BAR; PG8_MMA(0, 0, At, B0); PG8_MMA(0, 1, At, B1); PG8_BAR; PG8_SCHED;
;             PG8_LDA(At, 0, 1); PG8_STAGE(PG8_SB(0, 0), b2, voffB); PG8_STAGE(PG8_SB(0, 1), b2 + hstep, voffB); PG8_STAGE(PG8_SA(0, 0), a2, voffA);
;             PG8_WAIT_V(8); PG8_WAIT_L(0); PG8_BAR; PG8_MMA(1, 0, At, B0); PG8_MMA(1, 1, At, B1); PG8_BAR; PG8_SCHED;
;             PG8_LDB(B0, 1, 0); PG8_LDB(B1, 1, 1); PG8_SCHED; PG8_LDA(At, 1, 0); PG8_STAGE(PG8_SA(0, 1), a2 + hstep, voffA);
;             PG8_WAIT_V(8); PG8_WAIT_L(0); PG8_BAR; PG8_MMA(0, 0, At, B0); PG8_MMA(0, 1, At, B1); PG8_BAR; PG8_SCHED;
;             PG8_LDA(At, 1, 1); PG8_STAGE(PG8_SB(1, 0), b3, voffB); PG8_STAGE(PG8_SB(1, 1), b3 + hstep, voffB); PG8_STAGE(PG8_SA(1, 0), a3, voffA);
;             PG8_WAIT_V(8); PG8_WAIT_L(0); PG8_BAR; PG8_MMA(1, 0, At, B0); PG8_MMA(1, 1, At, B1); PG8_BAR; PG8_SCHED;
	v_mfma_f32_16x16x32_bf16 v[114:117], v[248:251], v[184:187], v[114:117]
	s_setprio 0
	ds_read_b128 v[252:255], v150 offset:49152
	ds_read_b128 v[188:191], v150 offset:50176
	ds_read_b128 v[192:195], v150 offset:51200
	ds_read_b128 v[196:199], v150 offset:52224
	ds_read_b128 v[200:203], v150 offset:53248
	ds_read_b128 v[204:207], v150 offset:54272
	ds_read_b128 v[208:211], v150 offset:55296
	ds_read_b128 v[212:215], v150 offset:56320
	s_mov_b32 m0, s56
	s_nop 0
	global_load_lds_dwordx4 v140, s[44:45]
	s_add_u32 s38, s38, 0x100080
	s_mov_b32 m0, s57
	s_nop 0
	global_load_lds_dwordx4 v142, s[44:45]
	s_addc_u32 s39, s39, 0
	s_mov_b32 m0, s62
	s_nop 0
	global_load_lds_dwordx4 v140, s[38:39]
	s_nop 0
	s_mov_b32 m0, s63
	s_nop 0
	global_load_lds_dwordx4 v142, s[38:39]
	s_nop 0
	s_mov_b32 m0, s60
	s_nop 0
	global_load_lds_dwordx4 v139, s[42:43]
	s_nop 0
	s_mov_b32 m0, s61
	s_nop 0
	global_load_lds_dwordx4 v141, s[42:43]
	s_waitcnt vmcnt(8)
	s_waitcnt lgkmcnt(0)
	s_barrier
	s_setprio 1
	s_waitcnt lgkmcnt(7)
	v_mfma_f32_16x16x32_bf16 v[62:65], v[152:155], v[252:255], v[62:65]
	v_mfma_f32_16x16x32_bf16 v[62:65], v[156:159], v[188:191], v[62:65]
	s_waitcnt lgkmcnt(5)
	v_mfma_f32_16x16x32_bf16 v[46:49], v[156:159], v[196:199], v[46:49]
	v_mfma_f32_16x16x32_bf16 v[46:49], v[152:155], v[192:195], v[46:49]
	s_waitcnt lgkmcnt(3)
	v_mfma_f32_16x16x32_bf16 v[30:33], v[152:155], v[200:203], v[30:33]
	v_mfma_f32_16x16x32_bf16 v[30:33], v[156:159], v[204:207], v[30:33]
	s_waitcnt lgkmcnt(1)
	v_mfma_f32_16x16x32_bf16 v[14:17], v[156:159], v[212:215], v[14:17]
	v_mfma_f32_16x16x32_bf16 v[14:17], v[152:155], v[208:211], v[14:17]
	v_mfma_f32_16x16x32_bf16 v[10:13], v[160:163], v[208:211], v[10:13]
	v_mfma_f32_16x16x32_bf16 v[10:13], v[164:167], v[212:215], v[10:13]
	v_mfma_f32_16x16x32_bf16 v[26:29], v[164:167], v[204:207], v[26:29]
	v_mfma_f32_16x16x32_bf16 v[26:29], v[160:163], v[200:203], v[26:29]
	v_mfma_f32_16x16x32_bf16 v[42:45], v[160:163], v[192:195], v[42:45]
	v_mfma_f32_16x16x32_bf16 v[42:45], v[164:167], v[196:199], v[42:45]
	s_waitcnt lgkmcnt(0)
	v_mfma_f32_16x16x32_bf16 v[58:61], v[164:167], v[188:191], v[58:61]
	v_mfma_f32_16x16x32_bf16 v[58:61], v[160:163], v[252:255], v[58:61]
	s_setprio 0
	s_setprio 1
	v_mfma_f32_16x16x32_bf16 v[54:57], v[168:171], v[252:255], v[54:57]
	v_mfma_f32_16x16x32_bf16 v[54:57], v[172:175], v[188:191], v[54:57]
	v_mfma_f32_16x16x32_bf16 v[38:41], v[172:175], v[196:199], v[38:41]
	v_mfma_f32_16x16x32_bf16 v[38:41], v[168:171], v[192:195], v[38:41]
	v_mfma_f32_16x16x32_bf16 v[22:25], v[168:171], v[200:203], v[22:25]
	v_mfma_f32_16x16x32_bf16 v[22:25], v[172:175], v[204:207], v[22:25]
	v_mfma_f32_16x16x32_bf16 v[6:9], v[172:175], v[212:215], v[6:9]
	v_mfma_f32_16x16x32_bf16 v[6:9], v[168:171], v[208:211], v[6:9]
	v_mfma_f32_16x16x32_bf16 v[2:5], v[248:251], v[208:211], v[2:5]
	v_mfma_f32_16x16x32_bf16 v[2:5], v[180:183], v[212:215], v[2:5]
	v_mfma_f32_16x16x32_bf16 v[18:21], v[180:183], v[204:207], v[18:21]
	v_mfma_f32_16x16x32_bf16 v[18:21], v[248:251], v[200:203], v[18:21]
	v_mfma_f32_16x16x32_bf16 v[34:37], v[248:251], v[192:195], v[34:37]
	v_mfma_f32_16x16x32_bf16 v[34:37], v[180:183], v[196:199], v[34:37]
	v_mfma_f32_16x16x32_bf16 v[50:53], v[180:183], v[188:191], v[50:53]
	s_setprio 2
	s_barrier
	v_mfma_f32_16x16x32_bf16 v[50:53], v[248:251], v[252:255], v[50:53]
	s_setprio 0
	s_add_i32 s76, s76, 2
	s_add_u32 s74, s74, 0x100
	s_addc_u32 s75, s75, 0
	s_cmp_gt_u32 s76, 61
	s_cbranch_scc1 .LBB0_780
	s_mov_b64 s[40:41], s[8:9]
	s_branch .LBB0_784

; #define PG8_STAGE(bufoff, gbase, voff) do { _Pragma("unroll") for (int _i = 0; _i < 2; ++_i) \
;         asm volatile("s_mov_b32 m0, %2\n\ts_nop 0\n\tglobal_load_lds_dwordx4 %0, %1" :: "v"((voff)[_i]), "s"((const char*)(gbase)), "s"(ldsbase + (unsigned)(bufoff) + ldsw + (unsigned)_i * 8192u) : "memory", "m0"); } while (0)
; #define PG8_LDA(dst, b, h) do { _Pragma("unroll") for (int m = 0; m < 4; ++m) _Pragma("unroll") for (int k = 0; k < 2; ++k) dst[m][k] = *(const PG8_LAS bf16x8*)(lds + PG8_SA(b, h) + aoff + m * 2048 + k * 1024); } while (0)
; #define PG8_LDB(dst, b, h) do { _Pragma("unroll") for (int n = 0; n < 2; ++n) _Pragma("unroll") for (int k = 0; k < 2; ++k) dst[n][k] = *(const PG8_LAS bf16x8*)(lds + PG8_SB(b, h) + boff + n * 2048 + k * 1024); } while (0)
; #define PG8_MMA(ai, bj, At, Bt) do { __builtin_amdgcn_s_setprio(1); _Pragma("unroll") for (int m = 0; m < 4; ++m) _Pragma("unroll") for (int n = 0; n < 2; ++n) _Pragma("unroll") for (int k = 0; k < 2; ++k) \
;         acc[ai][bj][m][n] = __builtin_amdgcn_mfma_f32_16x16x32_bf16(Bt[n][k], At[m][k], acc[ai][bj][m][n], 0, 0, 0); __builtin_amdgcn_s_setprio(0); } while (0)
; #define PG8_WAIT_V(n) asm volatile("s_waitcnt vmcnt(" #n ")" ::: "memory")
; #define PG8_WAIT_L(n) asm volatile("s_waitcnt lgkmcnt(" #n ")" ::: "memory")
; #define PG8_BAR __builtin_amdgcn_s_barrier()
; #define PG8_SCHED __builtin_amdgcn_sched_barrier(0)
; template <class Epi, class Sched, bool ALIGN_EPI = false, bool SP2 = false>
; __device__ __forceinline__ void gemm_phase(PG8_LAS unsigned char* lds, const Gemm g, const Sched& S, const Epi& E) {
;     ...
;             PG8_LDB(B0, 0, 0); PG8_LDB(B1, 0, 1); PG8_SCHED; PG8_LDA(At, 0, 0); PG8_STAGE(PG8_SA(1, 1), a1 + hstep, voffA);
;             PG8_WAIT_V(8); PG8_WAIT_L(0); PG8_BAR; PG8_MMA(0, 0, At, B0); PG8_MMA(0, 1, At, B1); PG8_BAR; PG8_SCHED;
;             PG8_LDA(At, 0, 1); PG8_STAGE(PG8_SB(0, 0), b2, voffB); PG8_STAGE(PG8_SB(0, 1), b2 + hstep, voffB); PG8_STAGE(PG8_SA(0, 0), a2, voffA);
;             PG8_WAIT_V(8); PG8_WAIT_L(0); PG8_BAR; PG8_MMA(1, 0, At, B0); PG8_MMA(1, 1, At, B1); PG8_BAR; PG8_SCHED;
.LBB0_873:
	ds_read_b128 v[134:137], v145
	ds_read_b128 v[150:153], v145 offset:1024
	ds_read_b128 v[154:157], v145 offset:2048
	ds_read_b128 v[158:161], v145 offset:3072
	ds_read_b128 v[162:165], v146
	ds_read_b128 v[166:169], v146 offset:1024
	ds_read_b128 v[170:173], v146 offset:2048
	ds_read_b128 v[174:177], v146 offset:3072
	s_add_u32 s38, s36, 0x100
	s_addc_u32 s39, s37, 0
	s_cmpk_eq_i32 s69, 0xa8
	s_cselect_b32 s44, s4, s38
	s_cselect_b32 s45, s5, s39
	s_cselect_b32 s42, s22, s67
	s_cselect_b32 s43, s23, s68
	s_add_u32 s40, s44, 0x80
	s_addc_u32 s41, s45, 0
	ds_read_b128 v[178:181], v147
	ds_read_b128 v[182:185], v147 offset:1024
	ds_read_b128 v[186:189], v147 offset:2048
	ds_read_b128 v[190:193], v147 offset:3072
	ds_read_b128 v[194:197], v147 offset:4096
	ds_read_b128 v[198:201], v147 offset:5120
	ds_read_b128 v[202:205], v147 offset:6144
	ds_read_b128 v[206:209], v147 offset:7168
	s_add_u32 s36, s36, 0x2b0080
	s_addc_u32 s37, s37, 0
	s_mov_b32 m0, s60
	s_nop 0
	global_load_lds_dwordx4 v1, s[36:37]
	s_nop 0
	s_mov_b32 m0, s61
	s_nop 0
	global_load_lds_dwordx4 v141, s[36:37]
	s_waitcnt vmcnt(8)
	s_waitcnt lgkmcnt(0)
	s_barrier
	s_setprio 1
	s_waitcnt lgkmcnt(7)
	v_mfma_f32_16x16x32_bf16 v[126:129], v[134:137], v[178:181], v[126:129]
	v_mfma_f32_16x16x32_bf16 v[126:129], v[150:153], v[182:185], v[126:129]
	s_waitcnt lgkmcnt(5)
	v_mfma_f32_16x16x32_bf16 v[110:113], v[150:153], v[190:193], v[110:113]
	v_mfma_f32_16x16x32_bf16 v[110:113], v[134:137], v[186:189], v[110:113]
	s_waitcnt lgkmcnt(3)
	v_mfma_f32_16x16x32_bf16 v[94:97], v[134:137], v[194:197], v[94:97]
	v_mfma_f32_16x16x32_bf16 v[94:97], v[150:153], v[198:201], v[94:97]
	s_waitcnt lgkmcnt(1)
	v_mfma_f32_16x16x32_bf16 v[78:81], v[150:153], v[206:209], v[78:81]
	v_mfma_f32_16x16x32_bf16 v[78:81], v[134:137], v[202:205], v[78:81]
	v_mfma_f32_16x16x32_bf16 v[74:77], v[154:157], v[202:205], v[74:77]
	v_mfma_f32_16x16x32_bf16 v[74:77], v[158:161], v[206:209], v[74:77]
	v_mfma_f32_16x16x32_bf16 v[90:93], v[158:161], v[198:201], v[90:93]
	v_mfma_f32_16x16x32_bf16 v[90:93], v[154:157], v[194:197], v[90:93]
	v_mfma_f32_16x16x32_bf16 v[106:109], v[154:157], v[186:189], v[106:109]
	v_mfma_f32_16x16x32_bf16 v[106:109], v[158:161], v[190:193], v[106:109]
	s_waitcnt lgkmcnt(0)
	v_mfma_f32_16x16x32_bf16 v[122:125], v[158:161], v[182:185], v[122:125]
	v_mfma_f32_16x16x32_bf16 v[122:125], v[154:157], v[178:181], v[122:125]
	s_setprio 0
	s_setprio 1
	v_mfma_f32_16x16x32_bf16 v[118:121], v[162:165], v[178:181], v[118:121]
	v_mfma_f32_16x16x32_bf16 v[118:121], v[166:169], v[182:185], v[118:121]
	v_mfma_f32_16x16x32_bf16 v[102:105], v[166:169], v[190:193], v[102:105]
	v_mfma_f32_16x16x32_bf16 v[102:105], v[162:165], v[186:189], v[102:105]
	v_mfma_f32_16x16x32_bf16 v[86:89], v[162:165], v[194:197], v[86:89]
	v_mfma_f32_16x16x32_bf16 v[86:89], v[166:169], v[198:201], v[86:89]
	v_mfma_f32_16x16x32_bf16 v[70:73], v[166:169], v[206:209], v[70:73]
	v_mfma_f32_16x16x32_bf16 v[70:73], v[162:165], v[202:205], v[70:73]
	v_mfma_f32_16x16x32_bf16 v[66:69], v[170:173], v[202:205], v[66:69]
	v_mfma_f32_16x16x32_bf16 v[66:69], v[174:177], v[206:209], v[66:69]
	v_mfma_f32_16x16x32_bf16 v[82:85], v[174:177], v[198:201], v[82:85]
	v_mfma_f32_16x16x32_bf16 v[82:85], v[170:173], v[194:197], v[82:85]
	v_mfma_f32_16x16x32_bf16 v[98:101], v[170:173], v[186:189], v[98:101]
	v_mfma_f32_16x16x32_bf16 v[98:101], v[174:177], v[190:193], v[98:101]
	v_mfma_f32_16x16x32_bf16 v[114:117], v[174:177], v[182:185], v[114:117]
	s_setprio 2
	s_barrier
	v_mfma_f32_16x16x32_bf16 v[114:117], v[170:173], v[178:181], v[114:117]
	s_setprio 0
	ds_read_b128 v[252:255], v147 offset:16384
	ds_read_b128 v[182:185], v147 offset:17408
	ds_read_b128 v[186:189], v147 offset:18432
	ds_read_b128 v[190:193], v147 offset:19456
	ds_read_b128 v[194:197], v147 offset:20480
	ds_read_b128 v[198:201], v147 offset:21504
	ds_read_b128 v[202:205], v147 offset:22528
	ds_read_b128 v[206:209], v147 offset:23552
	s_mov_b32 m0, s47
	s_nop 0
	global_load_lds_dwordx4 v140, s[42:43]
	s_add_u32 s36, s42, 0x2b0000
	s_mov_b32 m0, s48
	s_nop 0
	global_load_lds_dwordx4 v142, s[42:43]
	s_addc_u32 s37, s43, 0
	s_mov_b32 m0, s49
	s_nop 0
	global_load_lds_dwordx4 v140, s[36:37]
	s_nop 0
	s_mov_b32 m0, s50
	s_nop 0
	global_load_lds_dwordx4 v142, s[36:37]
	s_nop 0
	s_mov_b32 m0, s46
	s_nop 0
	global_load_lds_dwordx4 v1, s[44:45]
	s_nop 0
	s_mov_b32 m0, s51
	s_nop 0
	global_load_lds_dwordx4 v141, s[44:45]
	s_waitcnt vmcnt(8)
	s_waitcnt lgkmcnt(0)
	s_barrier
; #define PG8_STAGE(bufoff, gbase, voff) do { _Pragma("unroll") for (int _i = 0; _i < 2; ++_i) \
;         asm volatile("s_mov_b32 m0, %2\n\ts_nop 0\n\tglobal_load_lds_dwordx4 %0, %1" :: "v"((voff)[_i]), "s"((const char*)(gbase)), "s"(ldsbase + (unsigned)(bufoff) + ldsw + (unsigned)_i * 8192u) : "memory", "m0"); } while (0)
; #define PG8_LDA(dst, b, h) do { _Pragma("unroll") for (int m = 0; m < 4; ++m) _Pragma("unroll") for (int k = 0; k < 2; ++k) dst[m][k] = *(const PG8_LAS bf16x8*)(lds + PG8_SA(b, h) + aoff + m * 2048 + k * 1024); } while (0)
; #define PG8_LDB(dst, b, h) do { _Pragma("unroll") for (int n = 0; n < 2; ++n) _Pragma("unroll") for (int k = 0; k < 2; ++k) dst[n][k] = *(const PG8_LAS bf16x8*)(lds + PG8_SB(b, h) + boff + n * 2048 + k * 1024); } while (0)
; #define PG8_MMA(ai, bj, At, Bt) do { __builtin_amdgcn_s_setprio(1); _Pragma("unroll") for (int m = 0; m < 4; ++m) _Pragma("unroll") for (int n = 0; n < 2; ++n) _Pragma("unroll") for (int k = 0; k < 2; ++k) \
;         acc[ai][bj][m][n] = __builtin_amdgcn_mfma_f32_16x16x32_bf16(Bt[n][k], At[m][k], acc[ai][bj][m][n], 0, 0, 0); __builtin_amdgcn_s_setprio(0); } while (0)
; template <class Epi, class Sched, bool ALIGN_EPI = false, bool SP2 = false>
; __device__ __forceinline__ void gemm_phase(PG8_LAS unsigned char* lds, const Gemm g, const Sched& S, const Epi& E) {
;     ...
;             PG8_LDB(B0, 0, 0); PG8_LDB(B1, 0, 1); PG8_SCHED; PG8_LDA(At, 0, 0); PG8_STAGE(PG8_SA(1, 1), a1 + hstep, voffA);
;             PG8_WAIT_V(8); PG8_WAIT_L(0); PG8_BAR; PG8_MMA(0, 0, At, B0); PG8_MMA(0, 1, At, B1); PG8_BAR; PG8_SCHED;
;             PG8_LDA(At, 0, 1); PG8_STAGE(PG8_SB(0, 0), b2, voffB); PG8_STAGE(PG8_SB(0, 1), b2 + hstep, voffB); PG8_STAGE(PG8_SA(0, 0), a2, voffA);
;             PG8_WAIT_V(8); PG8_WAIT_L(0); PG8_BAR; PG8_MMA(1, 0, At, B0); PG8_MMA(1, 1, At, B1); PG8_BAR; PG8_SCHED;
;             PG8_LDB(B0, 1, 0); PG8_LDB(B1, 1, 1); PG8_SCHED; PG8_LDA(At, 1, 0); PG8_STAGE(PG8_SA(0, 1), a2 + hstep, voffA);
;             PG8_WAIT_V(8); PG8_WAIT_L(0); PG8_BAR; PG8_MMA(0, 0, At, B0); PG8_MMA(0, 1, At, B1); PG8_BAR; PG8_SCHED;
;             PG8_LDA(At, 1, 1); PG8_STAGE(PG8_SB(1, 0), b3, voffB); PG8_STAGE(PG8_SB(1, 1), b3 + hstep, voffB); PG8_STAGE(PG8_SA(1, 0), a3, voffA);
;             PG8_WAIT_V(8); PG8_WAIT_L(0); PG8_BAR; PG8_MMA(1, 0, At, B0); PG8_MMA(1, 1, At, B1); PG8_BAR; PG8_SCHED;
	s_setprio 1
	s_waitcnt lgkmcnt(7)
	v_mfma_f32_16x16x32_bf16 v[62:65], v[134:137], v[252:255], v[62:65]
	v_mfma_f32_16x16x32_bf16 v[62:65], v[150:153], v[182:185], v[62:65]
	s_waitcnt lgkmcnt(5)
	v_mfma_f32_16x16x32_bf16 v[46:49], v[150:153], v[190:193], v[46:49]
	v_mfma_f32_16x16x32_bf16 v[46:49], v[134:137], v[186:189], v[46:49]
	s_waitcnt lgkmcnt(3)
	v_mfma_f32_16x16x32_bf16 v[30:33], v[134:137], v[194:197], v[30:33]
	v_mfma_f32_16x16x32_bf16 v[30:33], v[150:153], v[198:201], v[30:33]
	s_waitcnt lgkmcnt(1)
	v_mfma_f32_16x16x32_bf16 v[14:17], v[150:153], v[206:209], v[14:17]
	v_mfma_f32_16x16x32_bf16 v[14:17], v[134:137], v[202:205], v[14:17]
	v_mfma_f32_16x16x32_bf16 v[10:13], v[154:157], v[202:205], v[10:13]
	v_mfma_f32_16x16x32_bf16 v[10:13], v[158:161], v[206:209], v[10:13]
	v_mfma_f32_16x16x32_bf16 v[26:29], v[158:161], v[198:201], v[26:29]
	v_mfma_f32_16x16x32_bf16 v[26:29], v[154:157], v[194:197], v[26:29]
	v_mfma_f32_16x16x32_bf16 v[42:45], v[154:157], v[186:189], v[42:45]
	v_mfma_f32_16x16x32_bf16 v[42:45], v[158:161], v[190:193], v[42:45]
	s_waitcnt lgkmcnt(0)
	v_mfma_f32_16x16x32_bf16 v[58:61], v[158:161], v[182:185], v[58:61]
	v_mfma_f32_16x16x32_bf16 v[58:61], v[154:157], v[252:255], v[58:61]
	s_setprio 0
	s_setprio 1
	v_mfma_f32_16x16x32_bf16 v[54:57], v[162:165], v[252:255], v[54:57]
	v_mfma_f32_16x16x32_bf16 v[54:57], v[166:169], v[182:185], v[54:57]
	v_mfma_f32_16x16x32_bf16 v[38:41], v[166:169], v[190:193], v[38:41]
	v_mfma_f32_16x16x32_bf16 v[38:41], v[162:165], v[186:189], v[38:41]
	v_mfma_f32_16x16x32_bf16 v[22:25], v[162:165], v[194:197], v[22:25]
	v_mfma_f32_16x16x32_bf16 v[22:25], v[166:169], v[198:201], v[22:25]
	v_mfma_f32_16x16x32_bf16 v[6:9], v[166:169], v[206:209], v[6:9]
	v_mfma_f32_16x16x32_bf16 v[6:9], v[162:165], v[202:205], v[6:9]
	v_mfma_f32_16x16x32_bf16 v[2:5], v[170:173], v[202:205], v[2:5]
	v_mfma_f32_16x16x32_bf16 v[2:5], v[174:177], v[206:209], v[2:5]
	v_mfma_f32_16x16x32_bf16 v[18:21], v[174:177], v[198:201], v[18:21]
	v_mfma_f32_16x16x32_bf16 v[18:21], v[170:173], v[194:197], v[18:21]
	v_mfma_f32_16x16x32_bf16 v[34:37], v[170:173], v[186:189], v[34:37]
	v_mfma_f32_16x16x32_bf16 v[34:37], v[174:177], v[190:193], v[34:37]
	v_mfma_f32_16x16x32_bf16 v[50:53], v[174:177], v[182:185], v[50:53]
	s_setprio 2
	s_barrier
	v_mfma_f32_16x16x32_bf16 v[50:53], v[170:173], v[252:255], v[50:53]
	s_setprio 0
	ds_read_b128 v[134:137], v148
	ds_read_b128 v[150:153], v148 offset:1024
	ds_read_b128 v[154:157], v148 offset:2048
	ds_read_b128 v[158:161], v148 offset:3072
	ds_read_b128 v[162:165], v149
	ds_read_b128 v[166:169], v149 offset:1024
	ds_read_b128 v[248:251], v149 offset:2048
	ds_read_b128 v[174:177], v149 offset:3072
	ds_read_b128 v[178:181], v147 offset:32768
	ds_read_b128 v[182:185], v147 offset:33792
	ds_read_b128 v[186:189], v147 offset:34816
	ds_read_b128 v[190:193], v147 offset:35840
	ds_read_b128 v[194:197], v147 offset:36864
	ds_read_b128 v[198:201], v147 offset:37888
	ds_read_b128 v[202:205], v147 offset:38912
	ds_read_b128 v[206:209], v147 offset:39936
	s_add_u32 s36, s44, 0x2b0000
	s_addc_u32 s37, s45, 0
	s_mov_b32 m0, s52
	s_nop 0
	global_load_lds_dwordx4 v1, s[36:37]
	s_nop 0
	s_mov_b32 m0, s53
	s_nop 0
	global_load_lds_dwordx4 v141, s[36:37]
	s_waitcnt vmcnt(8)
	s_waitcnt lgkmcnt(0)
	s_barrier
	s_setprio 1
	s_waitcnt lgkmcnt(7)
	v_mfma_f32_16x16x32_bf16 v[126:129], v[134:137], v[178:181], v[126:129]
	v_mfma_f32_16x16x32_bf16 v[126:129], v[150:153], v[182:185], v[126:129]
	s_waitcnt lgkmcnt(5)
	v_mfma_f32_16x16x32_bf16 v[110:113], v[150:153], v[190:193], v[110:113]
	v_mfma_f32_16x16x32_bf16 v[110:113], v[134:137], v[186:189], v[110:113]
	s_waitcnt lgkmcnt(3)
	v_mfma_f32_16x16x32_bf16 v[94:97], v[134:137], v[194:197], v[94:97]
	v_mfma_f32_16x16x32_bf16 v[94:97], v[150:153], v[198:201], v[94:97]
	s_waitcnt lgkmcnt(1)
	v_mfma_f32_16x16x32_bf16 v[78:81], v[150:153], v[206:209], v[78:81]
	v_mfma_f32_16x16x32_bf16 v[78:81], v[134:137], v[202:205], v[78:81]
	v_mfma_f32_16x16x32_bf16 v[74:77], v[154:157], v[202:205], v[74:77]
	v_mfma_f32_16x16x32_bf16 v[74:77], v[158:161], v[206:209], v[74:77]
	v_mfma_f32_16x16x32_bf16 v[90:93], v[158:161], v[198:201], v[90:93]
	v_mfma_f32_16x16x32_bf16 v[90:93], v[154:157], v[194:197], v[90:93]
	v_mfma_f32_16x16x32_bf16 v[106:109], v[154:157], v[186:189], v[106:109]
	v_mfma_f32_16x16x32_bf16 v[106:109], v[158:161], v[190:193], v[106:109]
	s_waitcnt lgkmcnt(0)
	v_mfma_f32_16x16x32_bf16 v[122:125], v[158:161], v[182:185], v[122:125]
	v_mfma_f32_16x16x32_bf16 v[122:125], v[154:157], v[178:181], v[122:125]
	s_setprio 0
	s_setprio 1
	v_mfma_f32_16x16x32_bf16 v[118:121], v[162:165], v[178:181], v[118:121]
	v_mfma_f32_16x16x32_bf16 v[118:121], v[166:169], v[182:185], v[118:121]
	v_mfma_f32_16x16x32_bf16 v[102:105], v[166:169], v[190:193], v[102:105]
	v_mfma_f32_16x16x32_bf16 v[102:105], v[162:165], v[186:189], v[102:105]
	v_mfma_f32_16x16x32_bf16 v[86:89], v[162:165], v[194:197], v[86:89]
	v_mfma_f32_16x16x32_bf16 v[86:89], v[166:169], v[198:201], v[86:89]
	v_mfma_f32_16x16x32_bf16 v[70:73], v[166:169], v[206:209], v[70:73]
	v_mfma_f32_16x16x32_bf16 v[70:73], v[162:165], v[202:205], v[70:73]
	v_mfma_f32_16x16x32_bf16 v[66:69], v[248:251], v[202:205], v[66:69]
	v_mfma_f32_16x16x32_bf16 v[66:69], v[174:177], v[206:209], v[66:69]
	v_mfma_f32_16x16x32_bf16 v[82:85], v[174:177], v[198:201], v[82:85]
	v_mfma_f32_16x16x32_bf16 v[82:85], v[248:251], v[194:197], v[82:85]
	v_mfma_f32_16x16x32_bf16 v[98:101], v[248:251], v[186:189], v[98:101]
	v_mfma_f32_16x16x32_bf16 v[98:101], v[174:177], v[190:193], v[98:101]
	v_mfma_f32_16x16x32_bf16 v[114:117], v[174:177], v[182:185], v[114:117]
	s_setprio 2
	s_barrier
; #define PG8_STAGE(bufoff, gbase, voff) do { _Pragma("unroll") for (int _i = 0; _i < 2; ++_i) \
;         asm volatile("s_mov_b32 m0, %2\n\ts_nop 0\n\tglobal_load_lds_dwordx4 %0, %1" :: "v"((voff)[_i]), "s"((const char*)(gbase)), "s"(ldsbase + (unsigned)(bufoff) + ldsw + (unsigned)_i * 8192u) : "memory", "m0"); } while (0)
; #define PG8_LDA(dst, b, h) do { _Pragma("unroll") for (int m = 0; m < 4; ++m) _Pragma("unroll") for (int k = 0; k < 2; ++k) dst[m][k] = *(const PG8_LAS bf16x8*)(lds + PG8_SA(b, h) + aoff + m * 2048 + k * 1024); } while (0)
; #define PG8_LDB(dst, b, h) do { _Pragma("unroll") for (int n = 0; n < 2; ++n) _Pragma("unroll") for (int k = 0; k < 2; ++k) dst[n][k] = *(const PG8_LAS bf16x8*)(lds + PG8_SB(b, h) + boff + n * 2048 + k * 1024); } while (0)
; #define PG8_MMA(ai, bj, At, Bt) do { __builtin_amdgcn_s_setprio(1); _Pragma("unroll") for (int m = 0; m < 4; ++m) _Pragma("unroll") for (int n = 0; n < 2; ++n) _Pragma("unroll") for (int k = 0; k < 2; ++k) \
;         acc[ai][bj][m][n] = __builtin_amdgcn_mfma_f32_16x16x32_bf16(Bt[n][k], At[m][k], acc[ai][bj][m][n], 0, 0, 0); __builtin_amdgcn_s_setprio(0); } while (0)
; #define PG8_WAIT_V(n) asm volatile("s_waitcnt vmcnt(" #n ")" ::: "memory")
; #define PG8_WAIT_L(n) asm volatile("s_waitcnt lgkmcnt(" #n ")" ::: "memory")
; #define PG8_BAR __builtin_amdgcn_s_barrier()
; #define PG8_SCHED __builtin_amdgcn_sched_barrier(0)
; template <class Epi, class Sched, bool ALIGN_EPI = false, bool SP2 = false>
; __device__ __forceinline__ void gemm_phase(PG8_LAS unsigned char* lds, const Gemm g, const Sched& S, const Epi& E) {
;     ...
;         for (int t = 0; t < nt; t += 2) {
;             const bool last = (t == nt - 2);
;     ...
;             PG8_LDB(B0, 1, 0); PG8_LDB(B1, 1, 1); PG8_SCHED; PG8_LDA(At, 1, 0); PG8_STAGE(PG8_SA(0, 1), a2 + hstep, voffA);
;             PG8_WAIT_V(8); PG8_WAIT_L(0); PG8_BAR; PG8_MMA(0, 0, At, B0); PG8_MMA(0, 1, At, B1); PG8_BAR; PG8_SCHED;
;             PG8_LDA(At, 1, 1); PG8_STAGE(PG8_SB(1, 0), b3, voffB); PG8_STAGE(PG8_SB(1, 1), b3 + hstep, voffB); PG8_STAGE(PG8_SA(1, 0), a3, voffA);
;             PG8_WAIT_V(8); PG8_WAIT_L(0); PG8_BAR; PG8_MMA(1, 0, At, B0); PG8_MMA(1, 1, At, B1); PG8_BAR; PG8_SCHED;
	v_mfma_f32_16x16x32_bf16 v[114:117], v[248:251], v[178:181], v[114:117]
	s_setprio 0
	ds_read_b128 v[252:255], v147 offset:49152
	ds_read_b128 v[182:185], v147 offset:50176
	ds_read_b128 v[186:189], v147 offset:51200
	ds_read_b128 v[190:193], v147 offset:52224
	ds_read_b128 v[194:197], v147 offset:53248
	ds_read_b128 v[198:201], v147 offset:54272
	ds_read_b128 v[202:205], v147 offset:55296
	ds_read_b128 v[206:209], v147 offset:56320
	s_add_u32 s36, s42, 0x80
	s_addc_u32 s37, s43, 0
	s_mov_b32 m0, s54
	s_nop 0
	global_load_lds_dwordx4 v140, s[36:37]
	s_nop 0
	s_mov_b32 m0, s55
	s_nop 0
	global_load_lds_dwordx4 v142, s[36:37]
	s_add_u32 s36, s42, 0x2b0080
	s_addc_u32 s37, s43, 0
	s_mov_b32 m0, s58
	s_nop 0
	global_load_lds_dwordx4 v140, s[36:37]
	s_nop 0
	s_mov_b32 m0, s59
	s_nop 0
	global_load_lds_dwordx4 v142, s[36:37]
	s_nop 0
	s_mov_b32 m0, s56
	s_nop 0
	global_load_lds_dwordx4 v1, s[40:41]
	s_nop 0
	s_mov_b32 m0, s57
	s_nop 0
	global_load_lds_dwordx4 v141, s[40:41]
	s_waitcnt vmcnt(8)
	s_waitcnt lgkmcnt(0)
	s_barrier
	s_setprio 1
	s_waitcnt lgkmcnt(7)
	v_mfma_f32_16x16x32_bf16 v[62:65], v[134:137], v[252:255], v[62:65]
	v_mfma_f32_16x16x32_bf16 v[62:65], v[150:153], v[182:185], v[62:65]
	s_waitcnt lgkmcnt(5)
	v_mfma_f32_16x16x32_bf16 v[46:49], v[150:153], v[190:193], v[46:49]
	v_mfma_f32_16x16x32_bf16 v[46:49], v[134:137], v[186:189], v[46:49]
	s_waitcnt lgkmcnt(3)
	v_mfma_f32_16x16x32_bf16 v[30:33], v[134:137], v[194:197], v[30:33]
	v_mfma_f32_16x16x32_bf16 v[30:33], v[150:153], v[198:201], v[30:33]
	s_waitcnt lgkmcnt(1)
	v_mfma_f32_16x16x32_bf16 v[14:17], v[150:153], v[206:209], v[14:17]
	v_mfma_f32_16x16x32_bf16 v[14:17], v[134:137], v[202:205], v[14:17]
	v_mfma_f32_16x16x32_bf16 v[10:13], v[154:157], v[202:205], v[10:13]
	v_mfma_f32_16x16x32_bf16 v[10:13], v[158:161], v[206:209], v[10:13]
	v_mfma_f32_16x16x32_bf16 v[26:29], v[158:161], v[198:201], v[26:29]
	v_mfma_f32_16x16x32_bf16 v[26:29], v[154:157], v[194:197], v[26:29]
	v_mfma_f32_16x16x32_bf16 v[42:45], v[154:157], v[186:189], v[42:45]
	v_mfma_f32_16x16x32_bf16 v[42:45], v[158:161], v[190:193], v[42:45]
	s_waitcnt lgkmcnt(0)
	v_mfma_f32_16x16x32_bf16 v[58:61], v[158:161], v[182:185], v[58:61]
	v_mfma_f32_16x16x32_bf16 v[58:61], v[154:157], v[252:255], v[58:61]
	s_setprio 0
	s_setprio 1
	v_mfma_f32_16x16x32_bf16 v[54:57], v[162:165], v[252:255], v[54:57]
	v_mfma_f32_16x16x32_bf16 v[54:57], v[166:169], v[182:185], v[54:57]
	v_mfma_f32_16x16x32_bf16 v[38:41], v[166:169], v[190:193], v[38:41]
	v_mfma_f32_16x16x32_bf16 v[38:41], v[162:165], v[186:189], v[38:41]
	v_mfma_f32_16x16x32_bf16 v[22:25], v[162:165], v[194:197], v[22:25]
	v_mfma_f32_16x16x32_bf16 v[22:25], v[166:169], v[198:201], v[22:25]
	v_mfma_f32_16x16x32_bf16 v[6:9], v[166:169], v[206:209], v[6:9]
	v_mfma_f32_16x16x32_bf16 v[6:9], v[162:165], v[202:205], v[6:9]
	v_mfma_f32_16x16x32_bf16 v[2:5], v[248:251], v[202:205], v[2:5]
	v_mfma_f32_16x16x32_bf16 v[2:5], v[174:177], v[206:209], v[2:5]
	v_mfma_f32_16x16x32_bf16 v[18:21], v[174:177], v[198:201], v[18:21]
	v_mfma_f32_16x16x32_bf16 v[18:21], v[248:251], v[194:197], v[18:21]
	v_mfma_f32_16x16x32_bf16 v[34:37], v[248:251], v[186:189], v[34:37]
	v_mfma_f32_16x16x32_bf16 v[34:37], v[174:177], v[190:193], v[34:37]
	v_mfma_f32_16x16x32_bf16 v[50:53], v[174:177], v[182:185], v[50:53]
	s_setprio 2
	s_barrier
	v_mfma_f32_16x16x32_bf16 v[50:53], v[248:251], v[252:255], v[50:53]
	s_setprio 0
	s_add_i32 s69, s69, 2
	s_add_u32 s67, s67, 0x100
	s_addc_u32 s68, s68, 0
	s_cmpk_gt_u32 s69, 0xa9
	s_mov_b64 s[36:37], s[38:39]
	s_cbranch_scc0 .LBB0_873
	s_and_b64 vcc, exec, s[10:11]
	s_cbranch_vccz .LBB0_876
	s_barrier
